# first 4 MFMAs of each compute segment hoisted above the leading barrier at low priority (fill the hand-off gap)
# baseline (speedup 1.0000x reference)
; #define PG8_STAGE(bufoff, gbase, voff) do { _Pragma("unroll") for (int _i = 0; _i < 2; ++_i) \
;         __builtin_amdgcn_global_load_lds((const unsigned*)((const char*)(gbase) + (voff)[_i]), (PG8_LAS unsigned*)(lds + (bufoff) + ldsw + _i * 8192), 16, 0, 0); } while (0)
; #define PG8_LDA(dst, b, h) do { _Pragma("unroll") for (int m = 0; m < 4; ++m) _Pragma("unroll") for (int k = 0; k < 2; ++k) dst[m][k] = *(const PG8_LAS bf16x8*)(lds + PG8_SA(b, h) + aoff + m * 2048 + k * 1024); } while (0)
; #define PG8_LDB(dst, b, h) do { _Pragma("unroll") for (int n = 0; n < 2; ++n) _Pragma("unroll") for (int k = 0; k < 2; ++k) dst[n][k] = *(const PG8_LAS bf16x8*)(lds + PG8_SB(b, h) + boff + n * 2048 + k * 1024); } while (0)
; #define PG8_MMA(ai, bj, At, Bt) do { __builtin_amdgcn_s_setprio(3); _Pragma("unroll") for (int m = 0; m < 4; ++m) _Pragma("unroll") for (int n = 0; n < 2; ++n) _Pragma("unroll") for (int k = 0; k < 2; ++k) \
;         acc[ai][bj][m][n] = __builtin_amdgcn_mfma_f32_16x16x32_bf16(Bt[n][k], At[m][k], acc[ai][bj][m][n], 0, 0, 0); __builtin_amdgcn_s_setprio(0); } while (0)
; #define PG8_WAIT_V(n) asm volatile("s_waitcnt vmcnt(" #n ")" ::: "memory")
; #define PG8_WAIT_L(n) asm volatile("s_waitcnt lgkmcnt(" #n ")" ::: "memory")
; #define PG8_BAR __builtin_amdgcn_s_barrier()
; #define PG8_SCHED __builtin_amdgcn_sched_barrier(0)
; template <class Epi, class Sched, bool ALIGN_EPI = false, bool SP2 = false>
; __device__ __forceinline__ void gemm_phase(PG8_LAS unsigned char* lds, const Gemm g, const Sched& S, const Epi& E) {
;     ...
;             PG8_LDB(B0, 0, 0); PG8_LDB(B1, 0, 1); PG8_SCHED; PG8_LDA(At, 0, 0); PG8_STAGE(PG8_SA(1, 1), a1 + hstepA, voffA);
;             PG8_WAIT_V(8); PG8_WAIT_L(0); PG8_BAR; PG8_MMA(0, 0, At, B0); PG8_MMA(0, 1, At, B1); PG8_BAR; PG8_SCHED;
;             PG8_LDA(At, 0, 1); PG8_STAGE(PG8_SB(0, 0), b2, voffB); PG8_STAGE(PG8_SB(0, 1), b2 + hstepB, voffB); PG8_STAGE(PG8_SA(0, 0), a2, voffA);
.Lengw1_e:
	s_waitcnt lgkmcnt(0)
	v_mfma_f32_16x16x32_bf16 v[126:129], v[130:133], v[192:195], v[126:129]
	v_mfma_f32_16x16x32_bf16 v[126:129], v[134:137], v[196:199], v[126:129]
	v_mfma_f32_16x16x32_bf16 v[118:121], v[156:159], v[192:195], v[118:121]
	v_mfma_f32_16x16x32_bf16 v[118:121], v[172:175], v[196:199], v[118:121]
	s_barrier
	s_setprio 3
	v_mfma_f32_16x16x32_bf16 v[102:105], v[156:159], v[200:203], v[102:105]
	v_mfma_f32_16x16x32_bf16 v[102:105], v[172:175], v[204:207], v[102:105]
	v_mfma_f32_16x16x32_bf16 v[110:113], v[130:133], v[200:203], v[110:113]
	v_mfma_f32_16x16x32_bf16 v[110:113], v[134:137], v[204:207], v[110:113]
	v_mfma_f32_16x16x32_bf16 v[94:97], v[130:133], v[208:211], v[94:97]
	v_mfma_f32_16x16x32_bf16 v[94:97], v[134:137], v[212:215], v[94:97]
	v_mfma_f32_16x16x32_bf16 v[86:89], v[156:159], v[208:211], v[86:89]
	v_mfma_f32_16x16x32_bf16 v[86:89], v[172:175], v[212:215], v[86:89]
	v_mfma_f32_16x16x32_bf16 v[70:73], v[156:159], v[216:219], v[70:73]
	v_mfma_f32_16x16x32_bf16 v[70:73], v[172:175], v[220:223], v[70:73]
	v_mfma_f32_16x16x32_bf16 v[78:81], v[130:133], v[216:219], v[78:81]
	v_mfma_f32_16x16x32_bf16 v[78:81], v[134:137], v[220:223], v[78:81]
	v_mfma_f32_16x16x32_bf16 v[122:125], v[176:179], v[192:195], v[122:125]
	v_mfma_f32_16x16x32_bf16 v[122:125], v[180:183], v[196:199], v[122:125]
	v_mfma_f32_16x16x32_bf16 v[114:117], v[184:187], v[192:195], v[114:117]
	v_mfma_f32_16x16x32_bf16 v[114:117], v[188:191], v[196:199], v[114:117]
	v_mfma_f32_16x16x32_bf16 v[98:101], v[184:187], v[200:203], v[98:101]
	v_mfma_f32_16x16x32_bf16 v[98:101], v[188:191], v[204:207], v[98:101]
	v_mfma_f32_16x16x32_bf16 v[106:109], v[176:179], v[200:203], v[106:109]
	v_mfma_f32_16x16x32_bf16 v[106:109], v[180:183], v[204:207], v[106:109]
	v_mfma_f32_16x16x32_bf16 v[90:93], v[176:179], v[208:211], v[90:93]
	v_mfma_f32_16x16x32_bf16 v[90:93], v[180:183], v[212:215], v[90:93]
	v_mfma_f32_16x16x32_bf16 v[82:85], v[184:187], v[208:211], v[82:85]
	v_mfma_f32_16x16x32_bf16 v[82:85], v[188:191], v[212:215], v[82:85]
	v_mfma_f32_16x16x32_bf16 v[66:69], v[184:187], v[216:219], v[66:69]
	v_mfma_f32_16x16x32_bf16 v[66:69], v[188:191], v[220:223], v[66:69]
	v_mfma_f32_16x16x32_bf16 v[74:77], v[176:179], v[216:219], v[74:77]
	v_mfma_f32_16x16x32_bf16 v[74:77], v[180:183], v[220:223], v[74:77]
	s_barrier
	s_setprio 0
	s_add_i32 s56, s83, s66
	v_lshl_add_u64 v[160:161], s[8:9], 0, v[140:141]
	s_mov_b32 m0, s56
	ds_read_b128 v[192:195], v169 offset:16384
	ds_read_b128 v[196:199], v169 offset:17408
	ds_read_b128 v[200:203], v169 offset:18432
	ds_read_b128 v[204:207], v169 offset:19456
	ds_read_b128 v[208:211], v169 offset:20480
	ds_read_b128 v[212:215], v169 offset:21504
	ds_read_b128 v[216:219], v169 offset:22528
	ds_read_b128 v[220:223], v169 offset:23552
	global_load_lds_dwordx4 v[160:161], off
	s_add_i32 m0, s56, 0x2000
	s_add_u32 s56, s8, 0x100000
	v_lshl_add_u64 v[224:225], s[8:9], 0, v[144:145]
	s_addc_u32 s57, s9, 0
	s_add_i32 s58, s89, s66
	global_load_lds_dwordx4 v[224:225], off
	v_lshl_add_u64 v[226:227], s[56:57], 0, v[140:141]
	s_mov_b32 m0, s58
	v_lshl_add_u64 v[228:229], s[36:37], 0, v[142:143]
	global_load_lds_dwordx4 v[226:227], off
	v_lshl_add_u64 v[226:227], s[56:57], 0, v[144:145]
	s_add_i32 m0, s58, 0x2000
	s_nop 0
	global_load_lds_dwordx4 v[226:227], off
	v_lshl_add_u64 v[226:227], s[36:37], 0, v[138:139]
	s_mov_b32 m0, s55
	s_nop 0
	global_load_lds_dwordx4 v[226:227], off
	s_mov_b32 m0, s67
	s_nop 0
	global_load_lds_dwordx4 v[228:229], off
	s_cmp_eq_u32 s97, 0
	s_cbranch_scc1 .Lengw2_a
	s_cmp_eq_u32 s97, 2
	s_cbranch_scc1 .Lengw2_b
	s_cmp_eq_u32 s97, 4
	s_cbranch_scc1 .Lengw2_c
	s_waitcnt vmcnt(16)
	s_branch .Lengw2_e

; #define PG8_STAGE(bufoff, gbase, voff) do { _Pragma("unroll") for (int _i = 0; _i < 2; ++_i) \
;         __builtin_amdgcn_global_load_lds((const unsigned*)((const char*)(gbase) + (voff)[_i]), (PG8_LAS unsigned*)(lds + (bufoff) + ldsw + _i * 8192), 16, 0, 0); } while (0)
; #define PG8_LDA(dst, b, h) do { _Pragma("unroll") for (int m = 0; m < 4; ++m) _Pragma("unroll") for (int k = 0; k < 2; ++k) dst[m][k] = *(const PG8_LAS bf16x8*)(lds + PG8_SA(b, h) + aoff + m * 2048 + k * 1024); } while (0)
; #define PG8_LDB(dst, b, h) do { _Pragma("unroll") for (int n = 0; n < 2; ++n) _Pragma("unroll") for (int k = 0; k < 2; ++k) dst[n][k] = *(const PG8_LAS bf16x8*)(lds + PG8_SB(b, h) + boff + n * 2048 + k * 1024); } while (0)
; #define PG8_MMA(ai, bj, At, Bt) do { __builtin_amdgcn_s_setprio(3); _Pragma("unroll") for (int m = 0; m < 4; ++m) _Pragma("unroll") for (int n = 0; n < 2; ++n) _Pragma("unroll") for (int k = 0; k < 2; ++k) \
;         acc[ai][bj][m][n] = __builtin_amdgcn_mfma_f32_16x16x32_bf16(Bt[n][k], At[m][k], acc[ai][bj][m][n], 0, 0, 0); __builtin_amdgcn_s_setprio(0); } while (0)
; #define PG8_WAIT_V(n) asm volatile("s_waitcnt vmcnt(" #n ")" ::: "memory")
; #define PG8_WAIT_L(n) asm volatile("s_waitcnt lgkmcnt(" #n ")" ::: "memory")
; #define PG8_BAR __builtin_amdgcn_s_barrier()
; #define PG8_SCHED __builtin_amdgcn_sched_barrier(0)
; template <class Epi, class Sched, bool ALIGN_EPI = false, bool SP2 = false>
; __device__ __forceinline__ void gemm_phase(PG8_LAS unsigned char* lds, const Gemm g, const Sched& S, const Epi& E) {
;     ...
;             PG8_WAIT_V(8); PG8_WAIT_L(0); PG8_BAR; PG8_MMA(1, 0, At, B0); PG8_MMA(1, 1, At, B1); PG8_BAR; PG8_SCHED;
;             PG8_LDB(B0, 1, 0); PG8_LDB(B1, 1, 1); PG8_SCHED; PG8_LDA(At, 1, 0); PG8_STAGE(PG8_SA(0, 1), a2 + hstepA, voffA);
.Lengw2_e:
	s_waitcnt lgkmcnt(0)
	v_mfma_f32_16x16x32_bf16 v[62:65], v[130:133], v[192:195], v[62:65]
	v_mfma_f32_16x16x32_bf16 v[62:65], v[134:137], v[196:199], v[62:65]
	v_mfma_f32_16x16x32_bf16 v[54:57], v[156:159], v[192:195], v[54:57]
	v_mfma_f32_16x16x32_bf16 v[54:57], v[172:175], v[196:199], v[54:57]
	s_barrier
	s_setprio 3
	v_mfma_f32_16x16x32_bf16 v[38:41], v[156:159], v[200:203], v[38:41]
	v_mfma_f32_16x16x32_bf16 v[38:41], v[172:175], v[204:207], v[38:41]
	v_mfma_f32_16x16x32_bf16 v[46:49], v[130:133], v[200:203], v[46:49]
	v_mfma_f32_16x16x32_bf16 v[46:49], v[134:137], v[204:207], v[46:49]
	v_mfma_f32_16x16x32_bf16 v[30:33], v[130:133], v[208:211], v[30:33]
	v_mfma_f32_16x16x32_bf16 v[30:33], v[134:137], v[212:215], v[30:33]
	v_mfma_f32_16x16x32_bf16 v[22:25], v[156:159], v[208:211], v[22:25]
	v_mfma_f32_16x16x32_bf16 v[22:25], v[172:175], v[212:215], v[22:25]
	v_mfma_f32_16x16x32_bf16 v[6:9], v[156:159], v[216:219], v[6:9]
	v_mfma_f32_16x16x32_bf16 v[6:9], v[172:175], v[220:223], v[6:9]
	v_mfma_f32_16x16x32_bf16 v[14:17], v[130:133], v[216:219], v[14:17]
	v_mfma_f32_16x16x32_bf16 v[14:17], v[134:137], v[220:223], v[14:17]
	v_mfma_f32_16x16x32_bf16 v[58:61], v[176:179], v[192:195], v[58:61]
	v_mfma_f32_16x16x32_bf16 v[58:61], v[180:183], v[196:199], v[58:61]
	v_mfma_f32_16x16x32_bf16 v[50:53], v[184:187], v[192:195], v[50:53]
	v_mfma_f32_16x16x32_bf16 v[50:53], v[188:191], v[196:199], v[50:53]
	v_mfma_f32_16x16x32_bf16 v[34:37], v[184:187], v[200:203], v[34:37]
	v_mfma_f32_16x16x32_bf16 v[34:37], v[188:191], v[204:207], v[34:37]
	v_mfma_f32_16x16x32_bf16 v[42:45], v[176:179], v[200:203], v[42:45]
	v_mfma_f32_16x16x32_bf16 v[42:45], v[180:183], v[204:207], v[42:45]
	v_mfma_f32_16x16x32_bf16 v[26:29], v[176:179], v[208:211], v[26:29]
	v_mfma_f32_16x16x32_bf16 v[26:29], v[180:183], v[212:215], v[26:29]
	v_mfma_f32_16x16x32_bf16 v[18:21], v[184:187], v[208:211], v[18:21]
	v_mfma_f32_16x16x32_bf16 v[18:21], v[188:191], v[212:215], v[18:21]
	v_mfma_f32_16x16x32_bf16 v[2:5], v[184:187], v[216:219], v[2:5]
	v_mfma_f32_16x16x32_bf16 v[2:5], v[188:191], v[220:223], v[2:5]
	v_mfma_f32_16x16x32_bf16 v[10:13], v[176:179], v[216:219], v[10:13]
	v_mfma_f32_16x16x32_bf16 v[10:13], v[180:183], v[220:223], v[10:13]
	s_barrier
	s_setprio 0
	s_add_i32 s56, 0, 0x18000
	v_add_u32_e32 v146, s56, v164
	s_add_i32 s57, 0, 0x1c000
	ds_read_b128 v[130:133], v146
	ds_read_b128 v[134:137], v146 offset:1024
	ds_read_b128 v[156:159], v146 offset:2048
	ds_read_b128 v[172:175], v146 offset:3072
	v_add_u32_e32 v146, s57, v164
	ds_read_b128 v[176:179], v146
	ds_read_b128 v[180:183], v146 offset:1024
	ds_read_b128 v[184:187], v146 offset:2048
	ds_read_b128 v[188:191], v146 offset:3072
	s_add_u32 s36, s36, 0x100000
	s_addc_u32 s37, s37, 0
	s_mov_b32 m0, s72
	v_lshl_add_u64 v[230:231], s[36:37], 0, v[138:139]
	ds_read_b128 v[192:195], v169 offset:32768
	ds_read_b128 v[196:199], v169 offset:33792
	ds_read_b128 v[200:203], v169 offset:34816
	ds_read_b128 v[204:207], v169 offset:35840
	ds_read_b128 v[208:211], v169 offset:36864
	ds_read_b128 v[212:215], v169 offset:37888
	ds_read_b128 v[216:219], v169 offset:38912
	ds_read_b128 v[220:223], v169 offset:39936
	global_load_lds_dwordx4 v[230:231], off
	v_lshl_add_u64 v[230:231], s[36:37], 0, v[142:143]
	s_mov_b32 m0, s73
	s_nop 0
	global_load_lds_dwordx4 v[230:231], off
	s_cmp_eq_u32 s97, 4
	s_cbranch_scc1 .Lengw3_c
	s_cmp_eq_u32 s97, 8
	s_cbranch_scc1 .Lengw3_d
	s_waitcnt vmcnt(8)
	s_branch .Lengw3_e

; #define PG8_STAGE(bufoff, gbase, voff) do { _Pragma("unroll") for (int _i = 0; _i < 2; ++_i) \
;         __builtin_amdgcn_global_load_lds((const unsigned*)((const char*)(gbase) + (voff)[_i]), (PG8_LAS unsigned*)(lds + (bufoff) + ldsw + _i * 8192), 16, 0, 0); } while (0)
; #define PG8_LDA(dst, b, h) do { _Pragma("unroll") for (int m = 0; m < 4; ++m) _Pragma("unroll") for (int k = 0; k < 2; ++k) dst[m][k] = *(const PG8_LAS bf16x8*)(lds + PG8_SA(b, h) + aoff + m * 2048 + k * 1024); } while (0)
; #define PG8_MMA(ai, bj, At, Bt) do { __builtin_amdgcn_s_setprio(3); _Pragma("unroll") for (int m = 0; m < 4; ++m) _Pragma("unroll") for (int n = 0; n < 2; ++n) _Pragma("unroll") for (int k = 0; k < 2; ++k) \
;         acc[ai][bj][m][n] = __builtin_amdgcn_mfma_f32_16x16x32_bf16(Bt[n][k], At[m][k], acc[ai][bj][m][n], 0, 0, 0); __builtin_amdgcn_s_setprio(0); } while (0)
; #define PG8_WAIT_V(n) asm volatile("s_waitcnt vmcnt(" #n ")" ::: "memory")
; #define PG8_WAIT_L(n) asm volatile("s_waitcnt lgkmcnt(" #n ")" ::: "memory")
; #define PG8_BAR __builtin_amdgcn_s_barrier()
; #define PG8_SCHED __builtin_amdgcn_sched_barrier(0)
; template <class Epi, class Sched, bool ALIGN_EPI = false, bool SP2 = false>
; __device__ __forceinline__ void gemm_phase(PG8_LAS unsigned char* lds, const Gemm g, const Sched& S, const Epi& E) {
;     ...
;             PG8_WAIT_V(8); PG8_WAIT_L(0); PG8_BAR; PG8_MMA(0, 0, At, B0); PG8_MMA(0, 1, At, B1); PG8_BAR; PG8_SCHED;
;             PG8_LDA(At, 1, 1); PG8_STAGE(PG8_SB(1, 0), b3, voffB); PG8_STAGE(PG8_SB(1, 1), b3 + hstepB, voffB); PG8_STAGE(PG8_SA(1, 0), a3, voffA);
;             PG8_WAIT_V(8); PG8_WAIT_L(0); PG8_BAR; PG8_MMA(1, 0, At, B0); PG8_MMA(1, 1, At, B1); PG8_BAR; PG8_SCHED;
.Lengw3_e:
	s_waitcnt lgkmcnt(0)
	v_mfma_f32_16x16x32_bf16 v[126:129], v[130:133], v[192:195], v[126:129]
	v_mfma_f32_16x16x32_bf16 v[126:129], v[134:137], v[196:199], v[126:129]
	v_mfma_f32_16x16x32_bf16 v[118:121], v[156:159], v[192:195], v[118:121]
	v_mfma_f32_16x16x32_bf16 v[118:121], v[172:175], v[196:199], v[118:121]
	s_barrier
	s_setprio 3
	v_mfma_f32_16x16x32_bf16 v[102:105], v[156:159], v[200:203], v[102:105]
	v_mfma_f32_16x16x32_bf16 v[102:105], v[172:175], v[204:207], v[102:105]
	v_mfma_f32_16x16x32_bf16 v[110:113], v[130:133], v[200:203], v[110:113]
	v_mfma_f32_16x16x32_bf16 v[110:113], v[134:137], v[204:207], v[110:113]
	v_mfma_f32_16x16x32_bf16 v[94:97], v[130:133], v[208:211], v[94:97]
	v_mfma_f32_16x16x32_bf16 v[94:97], v[134:137], v[212:215], v[94:97]
	v_mfma_f32_16x16x32_bf16 v[86:89], v[156:159], v[208:211], v[86:89]
	v_mfma_f32_16x16x32_bf16 v[86:89], v[172:175], v[212:215], v[86:89]
	v_mfma_f32_16x16x32_bf16 v[70:73], v[156:159], v[216:219], v[70:73]
	v_mfma_f32_16x16x32_bf16 v[70:73], v[172:175], v[220:223], v[70:73]
	v_mfma_f32_16x16x32_bf16 v[78:81], v[130:133], v[216:219], v[78:81]
	v_mfma_f32_16x16x32_bf16 v[78:81], v[134:137], v[220:223], v[78:81]
	v_mfma_f32_16x16x32_bf16 v[122:125], v[176:179], v[192:195], v[122:125]
	v_mfma_f32_16x16x32_bf16 v[122:125], v[180:183], v[196:199], v[122:125]
	v_mfma_f32_16x16x32_bf16 v[114:117], v[184:187], v[192:195], v[114:117]
	v_mfma_f32_16x16x32_bf16 v[114:117], v[188:191], v[196:199], v[114:117]
	v_mfma_f32_16x16x32_bf16 v[98:101], v[184:187], v[200:203], v[98:101]
	v_mfma_f32_16x16x32_bf16 v[98:101], v[188:191], v[204:207], v[98:101]
	v_mfma_f32_16x16x32_bf16 v[106:109], v[176:179], v[200:203], v[106:109]
	v_mfma_f32_16x16x32_bf16 v[106:109], v[180:183], v[204:207], v[106:109]
	v_mfma_f32_16x16x32_bf16 v[90:93], v[176:179], v[208:211], v[90:93]
	v_mfma_f32_16x16x32_bf16 v[90:93], v[180:183], v[212:215], v[90:93]
	v_mfma_f32_16x16x32_bf16 v[82:85], v[184:187], v[208:211], v[82:85]
	v_mfma_f32_16x16x32_bf16 v[82:85], v[188:191], v[212:215], v[82:85]
	v_mfma_f32_16x16x32_bf16 v[66:69], v[184:187], v[216:219], v[66:69]
	v_mfma_f32_16x16x32_bf16 v[66:69], v[188:191], v[220:223], v[66:69]
	v_mfma_f32_16x16x32_bf16 v[74:77], v[176:179], v[216:219], v[74:77]
	v_mfma_f32_16x16x32_bf16 v[74:77], v[180:183], v[220:223], v[74:77]
	s_barrier
	s_setprio 0
	s_add_i32 s36, s56, s66
	v_lshl_add_u64 v[160:161], v[160:161], 0, s[18:19]
	s_mov_b32 m0, s36
	ds_read_b128 v[192:195], v169 offset:49152
	ds_read_b128 v[196:199], v169 offset:50176
	ds_read_b128 v[200:203], v169 offset:51200
	ds_read_b128 v[204:207], v169 offset:52224
	ds_read_b128 v[208:211], v169 offset:53248
	ds_read_b128 v[212:215], v169 offset:54272
	ds_read_b128 v[216:219], v169 offset:55296
	ds_read_b128 v[220:223], v169 offset:56320
	global_load_lds_dwordx4 v[160:161], off
	s_add_i32 m0, s36, 0x2000
	s_add_u32 s8, s8, 0x100080
	v_lshl_add_u64 v[160:161], v[224:225], 0, s[18:19]
	s_addc_u32 s9, s9, 0
	s_add_i32 s36, s57, s66
	global_load_lds_dwordx4 v[160:161], off
	v_lshl_add_u64 v[160:161], s[8:9], 0, v[140:141]
	s_mov_b32 m0, s36
	s_nop 0
	global_load_lds_dwordx4 v[160:161], off
	v_lshl_add_u64 v[160:161], s[8:9], 0, v[144:145]
	s_add_i32 m0, s36, 0x2000
	s_nop 0
	global_load_lds_dwordx4 v[160:161], off
	v_lshl_add_u64 v[160:161], v[226:227], 0, s[18:19]
	s_mov_b32 m0, s75
	s_nop 0
	global_load_lds_dwordx4 v[160:161], off
	v_lshl_add_u64 v[160:161], v[228:229], 0, s[18:19]
	s_mov_b32 m0, s76
	s_nop 0
	global_load_lds_dwordx4 v[160:161], off
	s_waitcnt vmcnt(8)
	s_waitcnt lgkmcnt(0)
	v_mfma_f32_16x16x32_bf16 v[62:65], v[130:133], v[192:195], v[62:65]
	v_mfma_f32_16x16x32_bf16 v[62:65], v[134:137], v[196:199], v[62:65]
	v_mfma_f32_16x16x32_bf16 v[54:57], v[156:159], v[192:195], v[54:57]
	v_mfma_f32_16x16x32_bf16 v[54:57], v[172:175], v[196:199], v[54:57]
	s_barrier
	s_setprio 3
	v_mfma_f32_16x16x32_bf16 v[38:41], v[156:159], v[200:203], v[38:41]
	v_mfma_f32_16x16x32_bf16 v[38:41], v[172:175], v[204:207], v[38:41]
	v_mfma_f32_16x16x32_bf16 v[46:49], v[130:133], v[200:203], v[46:49]
	v_mfma_f32_16x16x32_bf16 v[46:49], v[134:137], v[204:207], v[46:49]
	v_mfma_f32_16x16x32_bf16 v[30:33], v[130:133], v[208:211], v[30:33]
	v_mfma_f32_16x16x32_bf16 v[30:33], v[134:137], v[212:215], v[30:33]
	v_mfma_f32_16x16x32_bf16 v[22:25], v[156:159], v[208:211], v[22:25]
	v_mfma_f32_16x16x32_bf16 v[22:25], v[172:175], v[212:215], v[22:25]
	v_mfma_f32_16x16x32_bf16 v[6:9], v[156:159], v[216:219], v[6:9]
	v_mfma_f32_16x16x32_bf16 v[6:9], v[172:175], v[220:223], v[6:9]
	v_mfma_f32_16x16x32_bf16 v[14:17], v[130:133], v[216:219], v[14:17]
	v_mfma_f32_16x16x32_bf16 v[14:17], v[134:137], v[220:223], v[14:17]
	v_mfma_f32_16x16x32_bf16 v[58:61], v[176:179], v[192:195], v[58:61]
	v_mfma_f32_16x16x32_bf16 v[58:61], v[180:183], v[196:199], v[58:61]
	v_mfma_f32_16x16x32_bf16 v[50:53], v[184:187], v[192:195], v[50:53]
	v_mfma_f32_16x16x32_bf16 v[50:53], v[188:191], v[196:199], v[50:53]
	v_mfma_f32_16x16x32_bf16 v[34:37], v[184:187], v[200:203], v[34:37]
	v_mfma_f32_16x16x32_bf16 v[34:37], v[188:191], v[204:207], v[34:37]
	v_mfma_f32_16x16x32_bf16 v[42:45], v[176:179], v[200:203], v[42:45]
	v_mfma_f32_16x16x32_bf16 v[42:45], v[180:183], v[204:207], v[42:45]
	v_mfma_f32_16x16x32_bf16 v[26:29], v[176:179], v[208:211], v[26:29]
	v_mfma_f32_16x16x32_bf16 v[26:29], v[180:183], v[212:215], v[26:29]
	v_mfma_f32_16x16x32_bf16 v[18:21], v[184:187], v[208:211], v[18:21]
	v_mfma_f32_16x16x32_bf16 v[18:21], v[188:191], v[212:215], v[18:21]
	v_mfma_f32_16x16x32_bf16 v[2:5], v[184:187], v[216:219], v[2:5]
	v_mfma_f32_16x16x32_bf16 v[2:5], v[188:191], v[220:223], v[2:5]
	v_mfma_f32_16x16x32_bf16 v[10:13], v[176:179], v[216:219], v[10:13]
	v_mfma_f32_16x16x32_bf16 v[10:13], v[180:183], v[220:223], v[10:13]
	s_barrier
	s_setprio 0
	s_add_i32 s45, s45, 2
	s_add_u32 s6, s6, 0x100
	s_addc_u32 s7, s7, 0
	s_add_u32 s33, s33, 0x100
	s_addc_u32 s44, s44, 0
	s_cmp_gt_u32 s45, 61
	s_cbranch_scc0 .LBB0_143
	s_and_b64 vcc, exec, s[20:21]
	s_cbranch_vccz .LBB0_148
	s_barrier
	v_lshl_add_u32 v156, s0, 8, v163
	s_cmp_lt_i32 s54, 40
	s_mov_b64 s[0:1], -1
	s_cbranch_scc1 .LBB0_149

; #define PG8_STAGE(bufoff, gbase, voff) do { _Pragma("unroll") for (int _i = 0; _i < 2; ++_i) \
;         __builtin_amdgcn_global_load_lds((const unsigned*)((const char*)(gbase) + (voff)[_i]), (PG8_LAS unsigned*)(lds + (bufoff) + ldsw + _i * 8192), 16, 0, 0); } while (0)
; #define PG8_LDA(dst, b, h) do { _Pragma("unroll") for (int m = 0; m < 4; ++m) _Pragma("unroll") for (int k = 0; k < 2; ++k) dst[m][k] = *(const PG8_LAS bf16x8*)(lds + PG8_SA(b, h) + aoff + m * 2048 + k * 1024); } while (0)
; #define PG8_LDB(dst, b, h) do { _Pragma("unroll") for (int n = 0; n < 2; ++n) _Pragma("unroll") for (int k = 0; k < 2; ++k) dst[n][k] = *(const PG8_LAS bf16x8*)(lds + PG8_SB(b, h) + boff + n * 2048 + k * 1024); } while (0)
; #define PG8_MMA(ai, bj, At, Bt) do { __builtin_amdgcn_s_setprio(3); _Pragma("unroll") for (int m = 0; m < 4; ++m) _Pragma("unroll") for (int n = 0; n < 2; ++n) _Pragma("unroll") for (int k = 0; k < 2; ++k) \
;         acc[ai][bj][m][n] = __builtin_amdgcn_mfma_f32_16x16x32_bf16(Bt[n][k], At[m][k], acc[ai][bj][m][n], 0, 0, 0); __builtin_amdgcn_s_setprio(0); } while (0)
; #define PG8_WAIT_V(n) asm volatile("s_waitcnt vmcnt(" #n ")" ::: "memory")
; template <class Epi, class Sched, bool ALIGN_EPI = false, bool SP2 = false>
; __device__ __forceinline__ void gemm_phase(PG8_LAS unsigned char* lds, const Gemm g, const Sched& S, const Epi& E) {
;     ...
;             const bool last = (t == nt - 2);
;             const char* a1 = cA + (size_t)(t + 1) * kstep;
;             const char* a2 = last ? nA : cA + (size_t)(t + 2) * kstep; const char* b2 = last ? nB : cB + (size_t)(t + 2) * kstep;
;             const char* a3 = a2 + kstep; const char* b3 = b2 + kstep;
;             if (last && has_next) S.a_ready(nxt);
;             if constexpr (Epi::MIDK) { if (t == E.midk_step(nt)) E.midk(acc, cur, wr, wc, fr, fq); }
;             if constexpr (SP2) {
;             PG8_LDB(B0, 0, 0); PG8_LDB(B1, 0, 1); PG8_SCHED; PG8_LDA(At, 0, 0); PG8_STAGE(PG8_SA(1, 1), a1 + hstepA, voffA);
;             PG8_WAIT_V(8); PG8_WAIT_L(0); PG8_BAR; PG8_MMA(0, 0, At, B0); PG8_MMA(0, 1, At, B1); PG8_BAR; PG8_SCHED;
;             PG8_LDA(At, 0, 1); PG8_STAGE(PG8_SB(0, 0), b2, voffB); PG8_STAGE(PG8_SB(0, 1), b2 + hstepB, voffB); PG8_STAGE(PG8_SA(0, 0), a2, voffA);
;             PG8_WAIT_V(8); PG8_WAIT_L(0); PG8_BAR; PG8_MMA(1, 0, At, B0); PG8_MMA(1, 1, At, B1); PG8_BAR; PG8_SCHED;
.LBB0_478:
	ds_read_b128 v[130:133], v170
	ds_read_b128 v[134:137], v170 offset:1024
	ds_read_b128 v[138:141], v170 offset:2048
	ds_read_b128 v[142:145], v170 offset:3072
	ds_read_b128 v[164:167], v171
	ds_read_b128 v[174:177], v171 offset:1024
	ds_read_b128 v[178:181], v171 offset:2048
	ds_read_b128 v[182:185], v171 offset:3072
	s_add_u32 s36, s6, 0xfff80080
	s_addc_u32 s37, s7, -1
	s_cmp_eq_u32 s79, 4
	s_cselect_b32 s59, s27, s37
	s_cselect_b32 s58, s26, s36
	s_cselect_b32 s37, s23, s78
	s_cselect_b32 s36, s25, s77
	v_lshl_add_u64 v[218:219], s[6:7], 0, v[154:155]
	s_add_i32 m0, s31, 0xc000
	ds_read_b128 v[186:189], v172
	ds_read_b128 v[190:193], v172 offset:1024
	ds_read_b128 v[194:197], v172 offset:2048
	ds_read_b128 v[198:201], v172 offset:3072
	ds_read_b128 v[202:205], v172 offset:4096
	ds_read_b128 v[206:209], v172 offset:5120
	ds_read_b128 v[210:213], v172 offset:6144
	ds_read_b128 v[214:217], v172 offset:7168
	global_load_lds_dwordx4 v[218:219], off
	v_lshl_add_u64 v[218:219], s[6:7], 0, v[156:157]
	s_add_i32 m0, s31, 0xe000
	s_nop 0
	global_load_lds_dwordx4 v[218:219], off
	s_waitcnt vmcnt(8)
	s_waitcnt lgkmcnt(0)
	v_mfma_f32_16x16x32_bf16 v[126:129], v[130:133], v[186:189], v[126:129]
	v_mfma_f32_16x16x32_bf16 v[126:129], v[134:137], v[190:193], v[126:129]
	v_mfma_f32_16x16x32_bf16 v[122:125], v[138:141], v[186:189], v[122:125]
	v_mfma_f32_16x16x32_bf16 v[122:125], v[142:145], v[190:193], v[122:125]
	s_barrier
	s_setprio 3
	v_mfma_f32_16x16x32_bf16 v[114:117], v[138:141], v[194:197], v[114:117]
	v_mfma_f32_16x16x32_bf16 v[114:117], v[142:145], v[198:201], v[114:117]
	v_mfma_f32_16x16x32_bf16 v[118:121], v[130:133], v[194:197], v[118:121]
	v_mfma_f32_16x16x32_bf16 v[118:121], v[134:137], v[198:201], v[118:121]
	v_mfma_f32_16x16x32_bf16 v[110:113], v[130:133], v[202:205], v[110:113]
	v_mfma_f32_16x16x32_bf16 v[110:113], v[134:137], v[206:209], v[110:113]
	v_mfma_f32_16x16x32_bf16 v[102:105], v[138:141], v[202:205], v[102:105]
	v_mfma_f32_16x16x32_bf16 v[102:105], v[142:145], v[206:209], v[102:105]
	v_mfma_f32_16x16x32_bf16 v[74:77], v[138:141], v[210:213], v[74:77]
	v_mfma_f32_16x16x32_bf16 v[74:77], v[142:145], v[214:217], v[74:77]
	v_mfma_f32_16x16x32_bf16 v[78:81], v[130:133], v[210:213], v[78:81]
	v_mfma_f32_16x16x32_bf16 v[78:81], v[134:137], v[214:217], v[78:81]
	v_mfma_f32_16x16x32_bf16 v[106:109], v[164:167], v[186:189], v[106:109]
	v_mfma_f32_16x16x32_bf16 v[106:109], v[174:177], v[190:193], v[106:109]
	v_mfma_f32_16x16x32_bf16 v[98:101], v[178:181], v[186:189], v[98:101]
	v_mfma_f32_16x16x32_bf16 v[98:101], v[182:185], v[190:193], v[98:101]
	v_mfma_f32_16x16x32_bf16 v[90:93], v[178:181], v[194:197], v[90:93]
	v_mfma_f32_16x16x32_bf16 v[90:93], v[182:185], v[198:201], v[90:93]
	v_mfma_f32_16x16x32_bf16 v[94:97], v[164:167], v[194:197], v[94:97]
	v_mfma_f32_16x16x32_bf16 v[94:97], v[174:177], v[198:201], v[94:97]
	v_mfma_f32_16x16x32_bf16 v[86:89], v[164:167], v[202:205], v[86:89]
	v_mfma_f32_16x16x32_bf16 v[86:89], v[174:177], v[206:209], v[86:89]
	v_mfma_f32_16x16x32_bf16 v[82:85], v[178:181], v[202:205], v[82:85]
	v_mfma_f32_16x16x32_bf16 v[82:85], v[182:185], v[206:209], v[82:85]
	v_mfma_f32_16x16x32_bf16 v[66:69], v[178:181], v[210:213], v[66:69]
	v_mfma_f32_16x16x32_bf16 v[66:69], v[182:185], v[214:217], v[66:69]
	v_mfma_f32_16x16x32_bf16 v[70:73], v[164:167], v[210:213], v[70:73]
	v_mfma_f32_16x16x32_bf16 v[70:73], v[174:177], v[214:217], v[70:73]
	s_barrier
	s_setprio 0
	s_add_i32 s83, s72, s44
	v_lshl_add_u64 v[218:219], s[36:37], 0, v[148:149]
	s_mov_b32 m0, s83
	ds_read_b128 v[186:189], v172 offset:16384
	ds_read_b128 v[190:193], v172 offset:17408
	ds_read_b128 v[194:197], v172 offset:18432
	ds_read_b128 v[198:201], v172 offset:19456
	ds_read_b128 v[202:205], v172 offset:20480
	ds_read_b128 v[206:209], v172 offset:21504
	ds_read_b128 v[210:213], v172 offset:22528
	ds_read_b128 v[214:217], v172 offset:23552
	global_load_lds_dwordx4 v[218:219], off
	s_add_i32 m0, s83, 0x2000
	s_add_u32 s84, s36, 0x20000
	v_lshl_add_u64 v[220:221], s[36:37], 0, v[152:153]
	s_addc_u32 s85, s37, 0
	s_add_i32 s83, s73, s44
	global_load_lds_dwordx4 v[220:221], off
	v_lshl_add_u64 v[222:223], s[84:85], 0, v[148:149]
	s_mov_b32 m0, s83
	v_lshl_add_u64 v[224:225], s[58:59], 0, v[150:151]
	global_load_lds_dwordx4 v[222:223], off
	v_lshl_add_u64 v[222:223], s[84:85], 0, v[152:153]
	s_add_i32 m0, s83, 0x2000
	s_nop 0
	global_load_lds_dwordx4 v[222:223], off
	v_lshl_add_u64 v[222:223], s[58:59], 0, v[146:147]
	s_mov_b32 m0, s31
	s_nop 0
	global_load_lds_dwordx4 v[222:223], off
	s_mov_b32 m0, s45
	s_nop 0
	global_load_lds_dwordx4 v[224:225], off
	s_waitcnt vmcnt(8)
	s_waitcnt lgkmcnt(0)
	v_mfma_f32_16x16x32_bf16 v[62:65], v[130:133], v[186:189], v[62:65]
	v_mfma_f32_16x16x32_bf16 v[62:65], v[134:137], v[190:193], v[62:65]
	v_mfma_f32_16x16x32_bf16 v[58:61], v[138:141], v[186:189], v[58:61]
	v_mfma_f32_16x16x32_bf16 v[58:61], v[142:145], v[190:193], v[58:61]
	s_barrier
; #define PG8_STAGE(bufoff, gbase, voff) do { _Pragma("unroll") for (int _i = 0; _i < 2; ++_i) \
;         __builtin_amdgcn_global_load_lds((const unsigned*)((const char*)(gbase) + (voff)[_i]), (PG8_LAS unsigned*)(lds + (bufoff) + ldsw + _i * 8192), 16, 0, 0); } while (0)
; #define PG8_LDA(dst, b, h) do { _Pragma("unroll") for (int m = 0; m < 4; ++m) _Pragma("unroll") for (int k = 0; k < 2; ++k) dst[m][k] = *(const PG8_LAS bf16x8*)(lds + PG8_SA(b, h) + aoff + m * 2048 + k * 1024); } while (0)
; #define PG8_LDB(dst, b, h) do { _Pragma("unroll") for (int n = 0; n < 2; ++n) _Pragma("unroll") for (int k = 0; k < 2; ++k) dst[n][k] = *(const PG8_LAS bf16x8*)(lds + PG8_SB(b, h) + boff + n * 2048 + k * 1024); } while (0)
; #define PG8_MMA(ai, bj, At, Bt) do { __builtin_amdgcn_s_setprio(3); _Pragma("unroll") for (int m = 0; m < 4; ++m) _Pragma("unroll") for (int n = 0; n < 2; ++n) _Pragma("unroll") for (int k = 0; k < 2; ++k) \
;         acc[ai][bj][m][n] = __builtin_amdgcn_mfma_f32_16x16x32_bf16(Bt[n][k], At[m][k], acc[ai][bj][m][n], 0, 0, 0); __builtin_amdgcn_s_setprio(0); } while (0)
; #define PG8_WAIT_V(n) asm volatile("s_waitcnt vmcnt(" #n ")" ::: "memory")
; #define PG8_WAIT_L(n) asm volatile("s_waitcnt lgkmcnt(" #n ")" ::: "memory")
; #define PG8_BAR __builtin_amdgcn_s_barrier()
; #define PG8_SCHED __builtin_amdgcn_sched_barrier(0)
; template <class Epi, class Sched, bool ALIGN_EPI = false, bool SP2 = false>
; __device__ __forceinline__ void gemm_phase(PG8_LAS unsigned char* lds, const Gemm g, const Sched& S, const Epi& E) {
;     ...
;             PG8_WAIT_V(8); PG8_WAIT_L(0); PG8_BAR; PG8_MMA(1, 0, At, B0); PG8_MMA(1, 1, At, B1); PG8_BAR; PG8_SCHED;
;             PG8_LDB(B0, 1, 0); PG8_LDB(B1, 1, 1); PG8_SCHED; PG8_LDA(At, 1, 0); PG8_STAGE(PG8_SA(0, 1), a2 + hstepA, voffA);
;             PG8_WAIT_V(8); PG8_WAIT_L(0); PG8_BAR; PG8_MMA(0, 0, At, B0); PG8_MMA(0, 1, At, B1); PG8_BAR; PG8_SCHED;
	s_setprio 3
	v_mfma_f32_16x16x32_bf16 v[46:49], v[138:141], v[194:197], v[46:49]
	v_mfma_f32_16x16x32_bf16 v[46:49], v[142:145], v[198:201], v[46:49]
	v_mfma_f32_16x16x32_bf16 v[54:57], v[130:133], v[194:197], v[54:57]
	v_mfma_f32_16x16x32_bf16 v[54:57], v[134:137], v[198:201], v[54:57]
	v_mfma_f32_16x16x32_bf16 v[38:41], v[130:133], v[202:205], v[38:41]
	v_mfma_f32_16x16x32_bf16 v[38:41], v[134:137], v[206:209], v[38:41]
	v_mfma_f32_16x16x32_bf16 v[30:33], v[138:141], v[202:205], v[30:33]
	v_mfma_f32_16x16x32_bf16 v[30:33], v[142:145], v[206:209], v[30:33]
	v_mfma_f32_16x16x32_bf16 v[14:17], v[138:141], v[210:213], v[14:17]
	v_mfma_f32_16x16x32_bf16 v[14:17], v[142:145], v[214:217], v[14:17]
	v_mfma_f32_16x16x32_bf16 v[22:25], v[130:133], v[210:213], v[22:25]
	v_mfma_f32_16x16x32_bf16 v[22:25], v[134:137], v[214:217], v[22:25]
	v_mfma_f32_16x16x32_bf16 v[50:53], v[164:167], v[186:189], v[50:53]
	v_mfma_f32_16x16x32_bf16 v[50:53], v[174:177], v[190:193], v[50:53]
	v_mfma_f32_16x16x32_bf16 v[42:45], v[178:181], v[186:189], v[42:45]
	v_mfma_f32_16x16x32_bf16 v[42:45], v[182:185], v[190:193], v[42:45]
	v_mfma_f32_16x16x32_bf16 v[26:29], v[178:181], v[194:197], v[26:29]
	v_mfma_f32_16x16x32_bf16 v[26:29], v[182:185], v[198:201], v[26:29]
	v_mfma_f32_16x16x32_bf16 v[34:37], v[164:167], v[194:197], v[34:37]
	v_mfma_f32_16x16x32_bf16 v[34:37], v[174:177], v[198:201], v[34:37]
	v_mfma_f32_16x16x32_bf16 v[18:21], v[164:167], v[202:205], v[18:21]
	v_mfma_f32_16x16x32_bf16 v[18:21], v[174:177], v[206:209], v[18:21]
	v_mfma_f32_16x16x32_bf16 v[10:13], v[178:181], v[202:205], v[10:13]
	v_mfma_f32_16x16x32_bf16 v[10:13], v[182:185], v[206:209], v[10:13]
	v_mfma_f32_16x16x32_bf16 v[2:5], v[178:181], v[210:213], v[2:5]
	v_mfma_f32_16x16x32_bf16 v[2:5], v[182:185], v[214:217], v[2:5]
	v_mfma_f32_16x16x32_bf16 v[6:9], v[164:167], v[210:213], v[6:9]
	v_mfma_f32_16x16x32_bf16 v[6:9], v[174:177], v[214:217], v[6:9]
	s_barrier
	s_setprio 0
	s_add_i32 s83, 0, 0x18000
	s_add_i32 s84, 0, 0x1c000
	v_add_u32_e32 v142, s83, v168
	v_add_u32_e32 v173, s84, v168
	ds_read_b128 v[130:133], v142
	ds_read_b128 v[134:137], v142 offset:1024
	ds_read_b128 v[138:141], v142 offset:2048
	ds_read_b128 v[142:145], v142 offset:3072
	ds_read_b128 v[164:167], v173
	ds_read_b128 v[174:177], v173 offset:1024
	ds_read_b128 v[178:181], v173 offset:2048
	ds_read_b128 v[182:185], v173 offset:3072
	s_add_u32 s58, s58, 0x80000
	s_addc_u32 s59, s59, 0
	s_mov_b32 m0, s54
	v_lshl_add_u64 v[226:227], s[58:59], 0, v[146:147]
	ds_read_b128 v[186:189], v172 offset:32768
	ds_read_b128 v[190:193], v172 offset:33792
	ds_read_b128 v[194:197], v172 offset:34816
	ds_read_b128 v[198:201], v172 offset:35840
	ds_read_b128 v[202:205], v172 offset:36864
	ds_read_b128 v[206:209], v172 offset:37888
	ds_read_b128 v[210:213], v172 offset:38912
	ds_read_b128 v[214:217], v172 offset:39936
	global_load_lds_dwordx4 v[226:227], off
	v_lshl_add_u64 v[226:227], s[58:59], 0, v[150:151]
	s_mov_b32 m0, s55
	s_nop 0
	global_load_lds_dwordx4 v[226:227], off
	s_waitcnt vmcnt(8)
	s_waitcnt lgkmcnt(0)
	v_mfma_f32_16x16x32_bf16 v[126:129], v[130:133], v[186:189], v[126:129]
	v_mfma_f32_16x16x32_bf16 v[126:129], v[134:137], v[190:193], v[126:129]
	v_mfma_f32_16x16x32_bf16 v[122:125], v[138:141], v[186:189], v[122:125]
	v_mfma_f32_16x16x32_bf16 v[122:125], v[142:145], v[190:193], v[122:125]
	s_barrier
	s_setprio 3
	v_mfma_f32_16x16x32_bf16 v[114:117], v[138:141], v[194:197], v[114:117]
	v_mfma_f32_16x16x32_bf16 v[114:117], v[142:145], v[198:201], v[114:117]
	v_mfma_f32_16x16x32_bf16 v[118:121], v[130:133], v[194:197], v[118:121]
	v_mfma_f32_16x16x32_bf16 v[118:121], v[134:137], v[198:201], v[118:121]
	v_mfma_f32_16x16x32_bf16 v[110:113], v[130:133], v[202:205], v[110:113]
	v_mfma_f32_16x16x32_bf16 v[110:113], v[134:137], v[206:209], v[110:113]
	v_mfma_f32_16x16x32_bf16 v[102:105], v[138:141], v[202:205], v[102:105]
	v_mfma_f32_16x16x32_bf16 v[102:105], v[142:145], v[206:209], v[102:105]
	v_mfma_f32_16x16x32_bf16 v[74:77], v[138:141], v[210:213], v[74:77]
	v_mfma_f32_16x16x32_bf16 v[74:77], v[142:145], v[214:217], v[74:77]
	v_mfma_f32_16x16x32_bf16 v[78:81], v[130:133], v[210:213], v[78:81]
	v_mfma_f32_16x16x32_bf16 v[78:81], v[134:137], v[214:217], v[78:81]
	v_mfma_f32_16x16x32_bf16 v[106:109], v[164:167], v[186:189], v[106:109]
	v_mfma_f32_16x16x32_bf16 v[106:109], v[174:177], v[190:193], v[106:109]
	v_mfma_f32_16x16x32_bf16 v[98:101], v[178:181], v[186:189], v[98:101]
	v_mfma_f32_16x16x32_bf16 v[98:101], v[182:185], v[190:193], v[98:101]
	v_mfma_f32_16x16x32_bf16 v[90:93], v[178:181], v[194:197], v[90:93]
	v_mfma_f32_16x16x32_bf16 v[90:93], v[182:185], v[198:201], v[90:93]
	v_mfma_f32_16x16x32_bf16 v[94:97], v[164:167], v[194:197], v[94:97]
	v_mfma_f32_16x16x32_bf16 v[94:97], v[174:177], v[198:201], v[94:97]
	v_mfma_f32_16x16x32_bf16 v[86:89], v[164:167], v[202:205], v[86:89]
	v_mfma_f32_16x16x32_bf16 v[86:89], v[174:177], v[206:209], v[86:89]
	v_mfma_f32_16x16x32_bf16 v[82:85], v[178:181], v[202:205], v[82:85]
	v_mfma_f32_16x16x32_bf16 v[82:85], v[182:185], v[206:209], v[82:85]
	v_mfma_f32_16x16x32_bf16 v[66:69], v[178:181], v[210:213], v[66:69]
	v_mfma_f32_16x16x32_bf16 v[66:69], v[182:185], v[214:217], v[66:69]
	v_mfma_f32_16x16x32_bf16 v[70:73], v[164:167], v[210:213], v[70:73]
	v_mfma_f32_16x16x32_bf16 v[70:73], v[174:177], v[214:217], v[70:73]
	s_barrier
; #define PG8_STAGE(bufoff, gbase, voff) do { _Pragma("unroll") for (int _i = 0; _i < 2; ++_i) \
;         __builtin_amdgcn_global_load_lds((const unsigned*)((const char*)(gbase) + (voff)[_i]), (PG8_LAS unsigned*)(lds + (bufoff) + ldsw + _i * 8192), 16, 0, 0); } while (0)
; #define PG8_LDA(dst, b, h) do { _Pragma("unroll") for (int m = 0; m < 4; ++m) _Pragma("unroll") for (int k = 0; k < 2; ++k) dst[m][k] = *(const PG8_LAS bf16x8*)(lds + PG8_SA(b, h) + aoff + m * 2048 + k * 1024); } while (0)
; #define PG8_MMA(ai, bj, At, Bt) do { __builtin_amdgcn_s_setprio(3); _Pragma("unroll") for (int m = 0; m < 4; ++m) _Pragma("unroll") for (int n = 0; n < 2; ++n) _Pragma("unroll") for (int k = 0; k < 2; ++k) \
;         acc[ai][bj][m][n] = __builtin_amdgcn_mfma_f32_16x16x32_bf16(Bt[n][k], At[m][k], acc[ai][bj][m][n], 0, 0, 0); __builtin_amdgcn_s_setprio(0); } while (0)
; #define PG8_WAIT_V(n) asm volatile("s_waitcnt vmcnt(" #n ")" ::: "memory")
; #define PG8_WAIT_L(n) asm volatile("s_waitcnt lgkmcnt(" #n ")" ::: "memory")
; #define PG8_BAR __builtin_amdgcn_s_barrier()
; #define PG8_SCHED __builtin_amdgcn_sched_barrier(0)
; template <class Epi, class Sched, bool ALIGN_EPI = false, bool SP2 = false>
; __device__ __forceinline__ void gemm_phase(PG8_LAS unsigned char* lds, const Gemm g, const Sched& S, const Epi& E) {
;     ...
;             PG8_LDA(At, 1, 1); PG8_STAGE(PG8_SB(1, 0), b3, voffB); PG8_STAGE(PG8_SB(1, 1), b3 + hstepB, voffB); PG8_STAGE(PG8_SA(1, 0), a3, voffA);
;             PG8_WAIT_V(8); PG8_WAIT_L(0); PG8_BAR; PG8_MMA(1, 0, At, B0); PG8_MMA(1, 1, At, B1); PG8_BAR; PG8_SCHED;
	s_setprio 0
	s_add_i32 s58, s83, s44
	v_lshl_add_u64 v[218:219], v[218:219], 0, s[18:19]
	s_mov_b32 m0, s58
	ds_read_b128 v[186:189], v172 offset:49152
	ds_read_b128 v[190:193], v172 offset:50176
	ds_read_b128 v[194:197], v172 offset:51200
	ds_read_b128 v[198:201], v172 offset:52224
	ds_read_b128 v[202:205], v172 offset:53248
	ds_read_b128 v[206:209], v172 offset:54272
	ds_read_b128 v[210:213], v172 offset:55296
	ds_read_b128 v[214:217], v172 offset:56320
	global_load_lds_dwordx4 v[218:219], off
	s_add_i32 m0, s58, 0x2000
	s_add_u32 s36, s36, 0x20080
	v_lshl_add_u64 v[218:219], v[220:221], 0, s[18:19]
	s_addc_u32 s37, s37, 0
	s_add_i32 s58, s84, s44
	global_load_lds_dwordx4 v[218:219], off
	v_lshl_add_u64 v[218:219], s[36:37], 0, v[148:149]
	s_mov_b32 m0, s58
	s_nop 0
	global_load_lds_dwordx4 v[218:219], off
	v_lshl_add_u64 v[218:219], s[36:37], 0, v[152:153]
	s_add_i32 m0, s58, 0x2000
	s_nop 0
	global_load_lds_dwordx4 v[218:219], off
	v_lshl_add_u64 v[218:219], v[222:223], 0, s[18:19]
	s_mov_b32 m0, s63
	s_nop 0
	global_load_lds_dwordx4 v[218:219], off
	v_lshl_add_u64 v[218:219], v[224:225], 0, s[18:19]
	s_mov_b32 m0, s66
	s_nop 0
	global_load_lds_dwordx4 v[218:219], off
	s_waitcnt vmcnt(8)
	s_waitcnt lgkmcnt(0)
	v_mfma_f32_16x16x32_bf16 v[62:65], v[130:133], v[186:189], v[62:65]
	v_mfma_f32_16x16x32_bf16 v[62:65], v[134:137], v[190:193], v[62:65]
	v_mfma_f32_16x16x32_bf16 v[58:61], v[138:141], v[186:189], v[58:61]
	v_mfma_f32_16x16x32_bf16 v[58:61], v[142:145], v[190:193], v[58:61]
	s_barrier
	s_setprio 3
	v_mfma_f32_16x16x32_bf16 v[46:49], v[138:141], v[194:197], v[46:49]
	v_mfma_f32_16x16x32_bf16 v[46:49], v[142:145], v[198:201], v[46:49]
	v_mfma_f32_16x16x32_bf16 v[54:57], v[130:133], v[194:197], v[54:57]
	v_mfma_f32_16x16x32_bf16 v[54:57], v[134:137], v[198:201], v[54:57]
	v_mfma_f32_16x16x32_bf16 v[38:41], v[130:133], v[202:205], v[38:41]
	v_mfma_f32_16x16x32_bf16 v[38:41], v[134:137], v[206:209], v[38:41]
	v_mfma_f32_16x16x32_bf16 v[30:33], v[138:141], v[202:205], v[30:33]
	v_mfma_f32_16x16x32_bf16 v[30:33], v[142:145], v[206:209], v[30:33]
	v_mfma_f32_16x16x32_bf16 v[14:17], v[138:141], v[210:213], v[14:17]
	v_mfma_f32_16x16x32_bf16 v[14:17], v[142:145], v[214:217], v[14:17]
	v_mfma_f32_16x16x32_bf16 v[22:25], v[130:133], v[210:213], v[22:25]
	v_mfma_f32_16x16x32_bf16 v[22:25], v[134:137], v[214:217], v[22:25]
	v_mfma_f32_16x16x32_bf16 v[50:53], v[164:167], v[186:189], v[50:53]
	v_mfma_f32_16x16x32_bf16 v[50:53], v[174:177], v[190:193], v[50:53]
	v_mfma_f32_16x16x32_bf16 v[42:45], v[178:181], v[186:189], v[42:45]
	v_mfma_f32_16x16x32_bf16 v[42:45], v[182:185], v[190:193], v[42:45]
	v_mfma_f32_16x16x32_bf16 v[26:29], v[178:181], v[194:197], v[26:29]
	v_mfma_f32_16x16x32_bf16 v[26:29], v[182:185], v[198:201], v[26:29]
	v_mfma_f32_16x16x32_bf16 v[34:37], v[164:167], v[194:197], v[34:37]
	v_mfma_f32_16x16x32_bf16 v[34:37], v[174:177], v[198:201], v[34:37]
	v_mfma_f32_16x16x32_bf16 v[18:21], v[164:167], v[202:205], v[18:21]
	v_mfma_f32_16x16x32_bf16 v[18:21], v[174:177], v[206:209], v[18:21]
	v_mfma_f32_16x16x32_bf16 v[10:13], v[178:181], v[202:205], v[10:13]
	v_mfma_f32_16x16x32_bf16 v[10:13], v[182:185], v[206:209], v[10:13]
	v_mfma_f32_16x16x32_bf16 v[2:5], v[178:181], v[210:213], v[2:5]
	v_mfma_f32_16x16x32_bf16 v[2:5], v[182:185], v[214:217], v[2:5]
	v_mfma_f32_16x16x32_bf16 v[6:9], v[164:167], v[210:213], v[6:9]
	v_mfma_f32_16x16x32_bf16 v[6:9], v[174:177], v[214:217], v[6:9]
	s_barrier
	s_setprio 0
	s_add_i32 s79, s79, 2
	s_add_u32 s6, s6, 0x100
	s_addc_u32 s7, s7, 0
	s_add_u32 s77, s77, 0x100
	s_addc_u32 s78, s78, 0
	s_cmp_gt_u32 s79, 5
	s_cbranch_scc0 .LBB0_478
	s_and_b64 vcc, exec, s[20:21]
	s_cbranch_vccz .LBB0_481
	s_barrier

; #define PG8_STAGE(bufoff, gbase, voff) do { _Pragma("unroll") for (int _i = 0; _i < 2; ++_i) \
;         __builtin_amdgcn_global_load_lds((const unsigned*)((const char*)(gbase) + (voff)[_i]), (PG8_LAS unsigned*)(lds + (bufoff) + ldsw + _i * 8192), 16, 0, 0); } while (0)
; #define PG8_LDA(dst, b, h) do { _Pragma("unroll") for (int m = 0; m < 4; ++m) _Pragma("unroll") for (int k = 0; k < 2; ++k) dst[m][k] = *(const PG8_LAS bf16x8*)(lds + PG8_SA(b, h) + aoff + m * 2048 + k * 1024); } while (0)
; #define PG8_LDB(dst, b, h) do { _Pragma("unroll") for (int n = 0; n < 2; ++n) _Pragma("unroll") for (int k = 0; k < 2; ++k) dst[n][k] = *(const PG8_LAS bf16x8*)(lds + PG8_SB(b, h) + boff + n * 2048 + k * 1024); } while (0)
; #define PG8_MMA(ai, bj, At, Bt) do { __builtin_amdgcn_s_setprio(3); _Pragma("unroll") for (int m = 0; m < 4; ++m) _Pragma("unroll") for (int n = 0; n < 2; ++n) _Pragma("unroll") for (int k = 0; k < 2; ++k) \
;         acc[ai][bj][m][n] = __builtin_amdgcn_mfma_f32_16x16x32_bf16(Bt[n][k], At[m][k], acc[ai][bj][m][n], 0, 0, 0); __builtin_amdgcn_s_setprio(0); } while (0)
; #define PG8_WAIT_V(n) asm volatile("s_waitcnt vmcnt(" #n ")" ::: "memory")
; template <class Epi, class Sched, bool ALIGN_EPI = false, bool SP2 = false>
; __device__ __forceinline__ void gemm_phase(PG8_LAS unsigned char* lds, const Gemm g, const Sched& S, const Epi& E) {
;     ...
;             const bool last = (t == nt - 2);
;             const char* a1 = cA + (size_t)(t + 1) * kstep;
;             const char* a2 = last ? nA : cA + (size_t)(t + 2) * kstep; const char* b2 = last ? nB : cB + (size_t)(t + 2) * kstep;
;             const char* a3 = a2 + kstep; const char* b3 = b2 + kstep;
;             if (last && has_next) S.a_ready(nxt);
;             if constexpr (Epi::MIDK) { if (t == E.midk_step(nt)) E.midk(acc, cur, wr, wc, fr, fq); }
;             if constexpr (SP2) {
;             PG8_LDB(B0, 0, 0); PG8_LDB(B1, 0, 1); PG8_SCHED; PG8_LDA(At, 0, 0); PG8_STAGE(PG8_SA(1, 1), a1 + hstepA, voffA);
;             PG8_WAIT_V(8); PG8_WAIT_L(0); PG8_BAR; PG8_MMA(0, 0, At, B0); PG8_MMA(0, 1, At, B1); PG8_BAR; PG8_SCHED;
;             PG8_LDA(At, 0, 1); PG8_STAGE(PG8_SB(0, 0), b2, voffB); PG8_STAGE(PG8_SB(0, 1), b2 + hstepB, voffB); PG8_STAGE(PG8_SA(0, 0), a2, voffA);
;             PG8_WAIT_V(8); PG8_WAIT_L(0); PG8_BAR; PG8_MMA(1, 0, At, B0); PG8_MMA(1, 1, At, B1); PG8_BAR; PG8_SCHED;
.LBB0_727:
	v_add_u32_e32 v160, s66, v157
	ds_read_b128 v[130:133], v160
	ds_read_b128 v[164:167], v160 offset:1024
	ds_read_b128 v[168:171], v160 offset:2048
	ds_read_b128 v[172:175], v160 offset:3072
	v_add_u32_e32 v160, s67, v157
	s_add_u32 s0, s28, s30
	ds_read_b128 v[176:179], v160
	ds_read_b128 v[180:183], v160 offset:1024
	ds_read_b128 v[184:187], v160 offset:2048
	ds_read_b128 v[188:191], v160 offset:3072
	s_addc_u32 s1, s29, s31
	s_add_u32 s0, s0, 0x100
	s_addc_u32 s1, s1, 0
	s_add_u32 s84, s79, s30
	s_addc_u32 s85, s81, s31
	s_cmpk_eq_i32 s30, 0x1f00
	s_cselect_b32 s37, s23, s1
	s_cselect_b32 s36, s72, s0
	s_cselect_b32 s1, s75, s85
	s_cselect_b32 s0, s76, s84
	v_lshl_add_u64 v[160:161], v[150:151], 0, s[30:31]
	s_add_i32 m0, s44, 0xc000
	ds_read_b128 v[192:195], v159
	ds_read_b128 v[196:199], v159 offset:1024
	ds_read_b128 v[200:203], v159 offset:2048
	ds_read_b128 v[204:207], v159 offset:3072
	ds_read_b128 v[208:211], v159 offset:4096
	ds_read_b128 v[212:215], v159 offset:5120
	ds_read_b128 v[216:219], v159 offset:6144
	ds_read_b128 v[220:223], v159 offset:7168
	global_load_lds_dwordx4 v[160:161], off
	v_lshl_add_u64 v[160:161], v[152:153], 0, s[30:31]
	s_add_i32 m0, s44, 0xe000
	s_nop 0
	global_load_lds_dwordx4 v[160:161], off
	s_waitcnt vmcnt(8)
	s_waitcnt lgkmcnt(0)
	v_mfma_f32_16x16x32_bf16 v[126:129], v[130:133], v[192:195], v[126:129]
	v_mfma_f32_16x16x32_bf16 v[126:129], v[164:167], v[196:199], v[126:129]
	v_mfma_f32_16x16x32_bf16 v[122:125], v[168:171], v[192:195], v[122:125]
	v_mfma_f32_16x16x32_bf16 v[122:125], v[172:175], v[196:199], v[122:125]
	s_barrier
	s_setprio 3
	v_mfma_f32_16x16x32_bf16 v[106:109], v[168:171], v[200:203], v[106:109]
	v_mfma_f32_16x16x32_bf16 v[106:109], v[172:175], v[204:207], v[106:109]
	v_mfma_f32_16x16x32_bf16 v[110:113], v[130:133], v[200:203], v[110:113]
	v_mfma_f32_16x16x32_bf16 v[110:113], v[164:167], v[204:207], v[110:113]
	v_mfma_f32_16x16x32_bf16 v[94:97], v[130:133], v[208:211], v[94:97]
	v_mfma_f32_16x16x32_bf16 v[94:97], v[164:167], v[212:215], v[94:97]
	v_mfma_f32_16x16x32_bf16 v[90:93], v[168:171], v[208:211], v[90:93]
	v_mfma_f32_16x16x32_bf16 v[90:93], v[172:175], v[212:215], v[90:93]
	v_mfma_f32_16x16x32_bf16 v[74:77], v[168:171], v[216:219], v[74:77]
	v_mfma_f32_16x16x32_bf16 v[74:77], v[172:175], v[220:223], v[74:77]
	v_mfma_f32_16x16x32_bf16 v[78:81], v[130:133], v[216:219], v[78:81]
	v_mfma_f32_16x16x32_bf16 v[78:81], v[164:167], v[220:223], v[78:81]
	v_mfma_f32_16x16x32_bf16 v[118:121], v[176:179], v[192:195], v[118:121]
	v_mfma_f32_16x16x32_bf16 v[118:121], v[180:183], v[196:199], v[118:121]
	v_mfma_f32_16x16x32_bf16 v[114:117], v[184:187], v[192:195], v[114:117]
	v_mfma_f32_16x16x32_bf16 v[114:117], v[188:191], v[196:199], v[114:117]
	v_mfma_f32_16x16x32_bf16 v[98:101], v[184:187], v[200:203], v[98:101]
	v_mfma_f32_16x16x32_bf16 v[98:101], v[188:191], v[204:207], v[98:101]
	v_mfma_f32_16x16x32_bf16 v[102:105], v[176:179], v[200:203], v[102:105]
	v_mfma_f32_16x16x32_bf16 v[102:105], v[180:183], v[204:207], v[102:105]
	v_mfma_f32_16x16x32_bf16 v[86:89], v[176:179], v[208:211], v[86:89]
	v_mfma_f32_16x16x32_bf16 v[86:89], v[180:183], v[212:215], v[86:89]
	v_mfma_f32_16x16x32_bf16 v[82:85], v[184:187], v[208:211], v[82:85]
	v_mfma_f32_16x16x32_bf16 v[82:85], v[188:191], v[212:215], v[82:85]
	v_mfma_f32_16x16x32_bf16 v[66:69], v[184:187], v[216:219], v[66:69]
	v_mfma_f32_16x16x32_bf16 v[66:69], v[188:191], v[220:223], v[66:69]
	v_mfma_f32_16x16x32_bf16 v[70:73], v[176:179], v[216:219], v[70:73]
	v_mfma_f32_16x16x32_bf16 v[70:73], v[180:183], v[220:223], v[70:73]
	s_barrier
	s_setprio 0
	s_add_i32 s84, s66, s33
	v_lshl_add_u64 v[160:161], s[0:1], 0, v[136:137]
	s_mov_b32 m0, s84
	ds_read_b128 v[192:195], v159 offset:16384
	ds_read_b128 v[196:199], v159 offset:17408
	ds_read_b128 v[200:203], v159 offset:18432
	ds_read_b128 v[204:207], v159 offset:19456
	ds_read_b128 v[208:211], v159 offset:20480
	ds_read_b128 v[212:215], v159 offset:21504
	ds_read_b128 v[216:219], v159 offset:22528
	ds_read_b128 v[220:223], v159 offset:23552
	global_load_lds_dwordx4 v[160:161], off
	s_add_i32 m0, s84, 0x2000
	s_add_u32 s84, s0, 0x100000
	v_lshl_add_u64 v[224:225], s[0:1], 0, v[140:141]
	s_addc_u32 s85, s1, 0
	s_add_i32 s86, s67, s33
	global_load_lds_dwordx4 v[224:225], off
	v_lshl_add_u64 v[226:227], s[84:85], 0, v[136:137]
	s_mov_b32 m0, s86
	v_lshl_add_u64 v[228:229], s[36:37], 0, v[138:139]
	global_load_lds_dwordx4 v[226:227], off
	v_lshl_add_u64 v[226:227], s[84:85], 0, v[140:141]
	s_add_i32 m0, s86, 0x2000
	s_nop 0
	global_load_lds_dwordx4 v[226:227], off
	v_lshl_add_u64 v[226:227], s[36:37], 0, v[134:135]
	s_mov_b32 m0, s44
	s_nop 0
	global_load_lds_dwordx4 v[226:227], off
	s_mov_b32 m0, s45
	s_nop 0
	global_load_lds_dwordx4 v[228:229], off
	s_waitcnt vmcnt(8)
	s_waitcnt lgkmcnt(0)
	v_mfma_f32_16x16x32_bf16 v[62:65], v[130:133], v[192:195], v[62:65]
	v_mfma_f32_16x16x32_bf16 v[62:65], v[164:167], v[196:199], v[62:65]
	v_mfma_f32_16x16x32_bf16 v[58:61], v[168:171], v[192:195], v[58:61]
	v_mfma_f32_16x16x32_bf16 v[58:61], v[172:175], v[196:199], v[58:61]
	s_barrier
; #define PG8_STAGE(bufoff, gbase, voff) do { _Pragma("unroll") for (int _i = 0; _i < 2; ++_i) \
;         __builtin_amdgcn_global_load_lds((const unsigned*)((const char*)(gbase) + (voff)[_i]), (PG8_LAS unsigned*)(lds + (bufoff) + ldsw + _i * 8192), 16, 0, 0); } while (0)
; #define PG8_LDA(dst, b, h) do { _Pragma("unroll") for (int m = 0; m < 4; ++m) _Pragma("unroll") for (int k = 0; k < 2; ++k) dst[m][k] = *(const PG8_LAS bf16x8*)(lds + PG8_SA(b, h) + aoff + m * 2048 + k * 1024); } while (0)
; #define PG8_LDB(dst, b, h) do { _Pragma("unroll") for (int n = 0; n < 2; ++n) _Pragma("unroll") for (int k = 0; k < 2; ++k) dst[n][k] = *(const PG8_LAS bf16x8*)(lds + PG8_SB(b, h) + boff + n * 2048 + k * 1024); } while (0)
; #define PG8_MMA(ai, bj, At, Bt) do { __builtin_amdgcn_s_setprio(3); _Pragma("unroll") for (int m = 0; m < 4; ++m) _Pragma("unroll") for (int n = 0; n < 2; ++n) _Pragma("unroll") for (int k = 0; k < 2; ++k) \
;         acc[ai][bj][m][n] = __builtin_amdgcn_mfma_f32_16x16x32_bf16(Bt[n][k], At[m][k], acc[ai][bj][m][n], 0, 0, 0); __builtin_amdgcn_s_setprio(0); } while (0)
; #define PG8_WAIT_V(n) asm volatile("s_waitcnt vmcnt(" #n ")" ::: "memory")
; #define PG8_WAIT_L(n) asm volatile("s_waitcnt lgkmcnt(" #n ")" ::: "memory")
; #define PG8_BAR __builtin_amdgcn_s_barrier()
; #define PG8_SCHED __builtin_amdgcn_sched_barrier(0)
; template <class Epi, class Sched, bool ALIGN_EPI = false, bool SP2 = false>
; __device__ __forceinline__ void gemm_phase(PG8_LAS unsigned char* lds, const Gemm g, const Sched& S, const Epi& E) {
;     ...
;             PG8_WAIT_V(8); PG8_WAIT_L(0); PG8_BAR; PG8_MMA(1, 0, At, B0); PG8_MMA(1, 1, At, B1); PG8_BAR; PG8_SCHED;
;             PG8_LDB(B0, 1, 0); PG8_LDB(B1, 1, 1); PG8_SCHED; PG8_LDA(At, 1, 0); PG8_STAGE(PG8_SA(0, 1), a2 + hstepA, voffA);
;             PG8_WAIT_V(8); PG8_WAIT_L(0); PG8_BAR; PG8_MMA(0, 0, At, B0); PG8_MMA(0, 1, At, B1); PG8_BAR; PG8_SCHED;
	s_setprio 3
	v_mfma_f32_16x16x32_bf16 v[42:45], v[168:171], v[200:203], v[42:45]
	v_mfma_f32_16x16x32_bf16 v[42:45], v[172:175], v[204:207], v[42:45]
	v_mfma_f32_16x16x32_bf16 v[46:49], v[130:133], v[200:203], v[46:49]
	v_mfma_f32_16x16x32_bf16 v[46:49], v[164:167], v[204:207], v[46:49]
	v_mfma_f32_16x16x32_bf16 v[30:33], v[130:133], v[208:211], v[30:33]
	v_mfma_f32_16x16x32_bf16 v[30:33], v[164:167], v[212:215], v[30:33]
	v_mfma_f32_16x16x32_bf16 v[26:29], v[168:171], v[208:211], v[26:29]
	v_mfma_f32_16x16x32_bf16 v[26:29], v[172:175], v[212:215], v[26:29]
	v_mfma_f32_16x16x32_bf16 v[10:13], v[168:171], v[216:219], v[10:13]
	v_mfma_f32_16x16x32_bf16 v[10:13], v[172:175], v[220:223], v[10:13]
	v_mfma_f32_16x16x32_bf16 v[14:17], v[130:133], v[216:219], v[14:17]
	v_mfma_f32_16x16x32_bf16 v[14:17], v[164:167], v[220:223], v[14:17]
	v_mfma_f32_16x16x32_bf16 v[54:57], v[176:179], v[192:195], v[54:57]
	v_mfma_f32_16x16x32_bf16 v[54:57], v[180:183], v[196:199], v[54:57]
	v_mfma_f32_16x16x32_bf16 v[50:53], v[184:187], v[192:195], v[50:53]
	v_mfma_f32_16x16x32_bf16 v[50:53], v[188:191], v[196:199], v[50:53]
	v_mfma_f32_16x16x32_bf16 v[34:37], v[184:187], v[200:203], v[34:37]
	v_mfma_f32_16x16x32_bf16 v[34:37], v[188:191], v[204:207], v[34:37]
	v_mfma_f32_16x16x32_bf16 v[38:41], v[176:179], v[200:203], v[38:41]
	v_mfma_f32_16x16x32_bf16 v[38:41], v[180:183], v[204:207], v[38:41]
	v_mfma_f32_16x16x32_bf16 v[22:25], v[176:179], v[208:211], v[22:25]
	v_mfma_f32_16x16x32_bf16 v[22:25], v[180:183], v[212:215], v[22:25]
	v_mfma_f32_16x16x32_bf16 v[18:21], v[184:187], v[208:211], v[18:21]
	v_mfma_f32_16x16x32_bf16 v[18:21], v[188:191], v[212:215], v[18:21]
	v_mfma_f32_16x16x32_bf16 v[2:5], v[184:187], v[216:219], v[2:5]
	v_mfma_f32_16x16x32_bf16 v[2:5], v[188:191], v[220:223], v[2:5]
	v_mfma_f32_16x16x32_bf16 v[6:9], v[176:179], v[216:219], v[6:9]
	v_mfma_f32_16x16x32_bf16 v[6:9], v[180:183], v[220:223], v[6:9]
	s_barrier
	s_setprio 0
	s_add_i32 s84, 0, 0x18000
	v_add_u32_e32 v163, s84, v157
	s_add_i32 s85, 0, 0x1c000
	ds_read_b128 v[130:133], v163
	ds_read_b128 v[164:167], v163 offset:1024
	ds_read_b128 v[168:171], v163 offset:2048
	ds_read_b128 v[172:175], v163 offset:3072
	v_add_u32_e32 v163, s85, v157
	ds_read_b128 v[176:179], v163
	ds_read_b128 v[180:183], v163 offset:1024
	ds_read_b128 v[184:187], v163 offset:2048
	ds_read_b128 v[188:191], v163 offset:3072
	s_add_u32 s36, s36, 0x100000
	s_addc_u32 s37, s37, 0
	s_mov_b32 m0, s54
	v_lshl_add_u64 v[230:231], s[36:37], 0, v[134:135]
	ds_read_b128 v[192:195], v159 offset:32768
	ds_read_b128 v[196:199], v159 offset:33792
	ds_read_b128 v[200:203], v159 offset:34816
	ds_read_b128 v[204:207], v159 offset:35840
	ds_read_b128 v[208:211], v159 offset:36864
	ds_read_b128 v[212:215], v159 offset:37888
	ds_read_b128 v[216:219], v159 offset:38912
	ds_read_b128 v[220:223], v159 offset:39936
	global_load_lds_dwordx4 v[230:231], off
	v_lshl_add_u64 v[230:231], s[36:37], 0, v[138:139]
	s_mov_b32 m0, s55
	s_nop 0
	global_load_lds_dwordx4 v[230:231], off
	s_waitcnt vmcnt(8)
	s_waitcnt lgkmcnt(0)
	v_mfma_f32_16x16x32_bf16 v[126:129], v[130:133], v[192:195], v[126:129]
	v_mfma_f32_16x16x32_bf16 v[126:129], v[164:167], v[196:199], v[126:129]
	v_mfma_f32_16x16x32_bf16 v[122:125], v[168:171], v[192:195], v[122:125]
	v_mfma_f32_16x16x32_bf16 v[122:125], v[172:175], v[196:199], v[122:125]
	s_barrier
	s_setprio 3
	v_mfma_f32_16x16x32_bf16 v[106:109], v[168:171], v[200:203], v[106:109]
	v_mfma_f32_16x16x32_bf16 v[106:109], v[172:175], v[204:207], v[106:109]
	v_mfma_f32_16x16x32_bf16 v[110:113], v[130:133], v[200:203], v[110:113]
	v_mfma_f32_16x16x32_bf16 v[110:113], v[164:167], v[204:207], v[110:113]
	v_mfma_f32_16x16x32_bf16 v[94:97], v[130:133], v[208:211], v[94:97]
	v_mfma_f32_16x16x32_bf16 v[94:97], v[164:167], v[212:215], v[94:97]
	v_mfma_f32_16x16x32_bf16 v[90:93], v[168:171], v[208:211], v[90:93]
	v_mfma_f32_16x16x32_bf16 v[90:93], v[172:175], v[212:215], v[90:93]
	v_mfma_f32_16x16x32_bf16 v[74:77], v[168:171], v[216:219], v[74:77]
	v_mfma_f32_16x16x32_bf16 v[74:77], v[172:175], v[220:223], v[74:77]
	v_mfma_f32_16x16x32_bf16 v[78:81], v[130:133], v[216:219], v[78:81]
	v_mfma_f32_16x16x32_bf16 v[78:81], v[164:167], v[220:223], v[78:81]
	v_mfma_f32_16x16x32_bf16 v[118:121], v[176:179], v[192:195], v[118:121]
	v_mfma_f32_16x16x32_bf16 v[118:121], v[180:183], v[196:199], v[118:121]
	v_mfma_f32_16x16x32_bf16 v[114:117], v[184:187], v[192:195], v[114:117]
	v_mfma_f32_16x16x32_bf16 v[114:117], v[188:191], v[196:199], v[114:117]
	v_mfma_f32_16x16x32_bf16 v[98:101], v[184:187], v[200:203], v[98:101]
	v_mfma_f32_16x16x32_bf16 v[98:101], v[188:191], v[204:207], v[98:101]
	v_mfma_f32_16x16x32_bf16 v[102:105], v[176:179], v[200:203], v[102:105]
	v_mfma_f32_16x16x32_bf16 v[102:105], v[180:183], v[204:207], v[102:105]
	v_mfma_f32_16x16x32_bf16 v[86:89], v[176:179], v[208:211], v[86:89]
	v_mfma_f32_16x16x32_bf16 v[86:89], v[180:183], v[212:215], v[86:89]
	v_mfma_f32_16x16x32_bf16 v[82:85], v[184:187], v[208:211], v[82:85]
	v_mfma_f32_16x16x32_bf16 v[82:85], v[188:191], v[212:215], v[82:85]
	v_mfma_f32_16x16x32_bf16 v[66:69], v[184:187], v[216:219], v[66:69]
	v_mfma_f32_16x16x32_bf16 v[66:69], v[188:191], v[220:223], v[66:69]
	v_mfma_f32_16x16x32_bf16 v[70:73], v[176:179], v[216:219], v[70:73]
	v_mfma_f32_16x16x32_bf16 v[70:73], v[180:183], v[220:223], v[70:73]
	s_barrier
; #define PG8_STAGE(bufoff, gbase, voff) do { _Pragma("unroll") for (int _i = 0; _i < 2; ++_i) \
;         __builtin_amdgcn_global_load_lds((const unsigned*)((const char*)(gbase) + (voff)[_i]), (PG8_LAS unsigned*)(lds + (bufoff) + ldsw + _i * 8192), 16, 0, 0); } while (0)
; #define PG8_LDA(dst, b, h) do { _Pragma("unroll") for (int m = 0; m < 4; ++m) _Pragma("unroll") for (int k = 0; k < 2; ++k) dst[m][k] = *(const PG8_LAS bf16x8*)(lds + PG8_SA(b, h) + aoff + m * 2048 + k * 1024); } while (0)
; #define PG8_MMA(ai, bj, At, Bt) do { __builtin_amdgcn_s_setprio(3); _Pragma("unroll") for (int m = 0; m < 4; ++m) _Pragma("unroll") for (int n = 0; n < 2; ++n) _Pragma("unroll") for (int k = 0; k < 2; ++k) \
;         acc[ai][bj][m][n] = __builtin_amdgcn_mfma_f32_16x16x32_bf16(Bt[n][k], At[m][k], acc[ai][bj][m][n], 0, 0, 0); __builtin_amdgcn_s_setprio(0); } while (0)
; #define PG8_WAIT_V(n) asm volatile("s_waitcnt vmcnt(" #n ")" ::: "memory")
; #define PG8_WAIT_L(n) asm volatile("s_waitcnt lgkmcnt(" #n ")" ::: "memory")
; #define PG8_BAR __builtin_amdgcn_s_barrier()
; #define PG8_SCHED __builtin_amdgcn_sched_barrier(0)
; template <class Epi, class Sched, bool ALIGN_EPI = false, bool SP2 = false>
; __device__ __forceinline__ void gemm_phase(PG8_LAS unsigned char* lds, const Gemm g, const Sched& S, const Epi& E) {
;     ...
;             PG8_LDA(At, 1, 1); PG8_STAGE(PG8_SB(1, 0), b3, voffB); PG8_STAGE(PG8_SB(1, 1), b3 + hstepB, voffB); PG8_STAGE(PG8_SA(1, 0), a3, voffA);
;             PG8_WAIT_V(8); PG8_WAIT_L(0); PG8_BAR; PG8_MMA(1, 0, At, B0); PG8_MMA(1, 1, At, B1); PG8_BAR; PG8_SCHED;
	s_setprio 0
	s_add_i32 s36, s84, s33
	v_lshl_add_u64 v[160:161], v[160:161], 0, s[10:11]
	s_mov_b32 m0, s36
	ds_read_b128 v[192:195], v159 offset:49152
	ds_read_b128 v[196:199], v159 offset:50176
	ds_read_b128 v[200:203], v159 offset:51200
	ds_read_b128 v[204:207], v159 offset:52224
	ds_read_b128 v[208:211], v159 offset:53248
	ds_read_b128 v[212:215], v159 offset:54272
	ds_read_b128 v[216:219], v159 offset:55296
	ds_read_b128 v[220:223], v159 offset:56320
	global_load_lds_dwordx4 v[160:161], off
	s_add_i32 m0, s36, 0x2000
	s_add_u32 s0, s0, 0x100080
	v_lshl_add_u64 v[160:161], v[224:225], 0, s[10:11]
	s_addc_u32 s1, s1, 0
	s_add_i32 s36, s85, s33
	global_load_lds_dwordx4 v[160:161], off
	v_lshl_add_u64 v[160:161], s[0:1], 0, v[136:137]
	s_mov_b32 m0, s36
	s_nop 0
	global_load_lds_dwordx4 v[160:161], off
	v_lshl_add_u64 v[160:161], s[0:1], 0, v[140:141]
	s_add_i32 m0, s36, 0x2000
	s_nop 0
	global_load_lds_dwordx4 v[160:161], off
	v_lshl_add_u64 v[160:161], v[226:227], 0, s[10:11]
	s_mov_b32 m0, s61
	s_nop 0
	global_load_lds_dwordx4 v[160:161], off
	v_lshl_add_u64 v[160:161], v[228:229], 0, s[10:11]
	s_mov_b32 m0, s62
	s_nop 0
	global_load_lds_dwordx4 v[160:161], off
	s_waitcnt vmcnt(8)
	s_waitcnt lgkmcnt(0)
	v_mfma_f32_16x16x32_bf16 v[62:65], v[130:133], v[192:195], v[62:65]
	v_mfma_f32_16x16x32_bf16 v[62:65], v[164:167], v[196:199], v[62:65]
	v_mfma_f32_16x16x32_bf16 v[58:61], v[168:171], v[192:195], v[58:61]
	v_mfma_f32_16x16x32_bf16 v[58:61], v[172:175], v[196:199], v[58:61]
	s_barrier
	s_setprio 3
	v_mfma_f32_16x16x32_bf16 v[42:45], v[168:171], v[200:203], v[42:45]
	v_mfma_f32_16x16x32_bf16 v[42:45], v[172:175], v[204:207], v[42:45]
	v_mfma_f32_16x16x32_bf16 v[46:49], v[130:133], v[200:203], v[46:49]
	v_mfma_f32_16x16x32_bf16 v[46:49], v[164:167], v[204:207], v[46:49]
	v_mfma_f32_16x16x32_bf16 v[30:33], v[130:133], v[208:211], v[30:33]
	v_mfma_f32_16x16x32_bf16 v[30:33], v[164:167], v[212:215], v[30:33]
	v_mfma_f32_16x16x32_bf16 v[26:29], v[168:171], v[208:211], v[26:29]
	v_mfma_f32_16x16x32_bf16 v[26:29], v[172:175], v[212:215], v[26:29]
	v_mfma_f32_16x16x32_bf16 v[10:13], v[168:171], v[216:219], v[10:13]
	v_mfma_f32_16x16x32_bf16 v[10:13], v[172:175], v[220:223], v[10:13]
	v_mfma_f32_16x16x32_bf16 v[14:17], v[130:133], v[216:219], v[14:17]
	v_mfma_f32_16x16x32_bf16 v[14:17], v[164:167], v[220:223], v[14:17]
	v_mfma_f32_16x16x32_bf16 v[54:57], v[176:179], v[192:195], v[54:57]
	v_mfma_f32_16x16x32_bf16 v[54:57], v[180:183], v[196:199], v[54:57]
	v_mfma_f32_16x16x32_bf16 v[50:53], v[184:187], v[192:195], v[50:53]
	v_mfma_f32_16x16x32_bf16 v[50:53], v[188:191], v[196:199], v[50:53]
	v_mfma_f32_16x16x32_bf16 v[34:37], v[184:187], v[200:203], v[34:37]
	v_mfma_f32_16x16x32_bf16 v[34:37], v[188:191], v[204:207], v[34:37]
	v_mfma_f32_16x16x32_bf16 v[38:41], v[176:179], v[200:203], v[38:41]
	v_mfma_f32_16x16x32_bf16 v[38:41], v[180:183], v[204:207], v[38:41]
	v_mfma_f32_16x16x32_bf16 v[22:25], v[176:179], v[208:211], v[22:25]
	v_mfma_f32_16x16x32_bf16 v[22:25], v[180:183], v[212:215], v[22:25]
	v_mfma_f32_16x16x32_bf16 v[18:21], v[184:187], v[208:211], v[18:21]
	v_mfma_f32_16x16x32_bf16 v[18:21], v[188:191], v[212:215], v[18:21]
	v_mfma_f32_16x16x32_bf16 v[2:5], v[184:187], v[216:219], v[2:5]
	v_mfma_f32_16x16x32_bf16 v[2:5], v[188:191], v[220:223], v[2:5]
	v_mfma_f32_16x16x32_bf16 v[6:9], v[176:179], v[216:219], v[6:9]
	v_mfma_f32_16x16x32_bf16 v[6:9], v[180:183], v[220:223], v[6:9]
	s_barrier
	s_setprio 0
	s_add_i32 s83, s83, 2
	s_add_u32 s30, s30, 0x100
	s_addc_u32 s31, s31, 0
	s_cmp_gt_u32 s83, 61
	s_cbranch_scc1 .LBB0_730

; #define PG8_STAGE(bufoff, gbase, voff) do { _Pragma("unroll") for (int _i = 0; _i < 2; ++_i) \
;         __builtin_amdgcn_global_load_lds((const unsigned*)((const char*)(gbase) + (voff)[_i]), (PG8_LAS unsigned*)(lds + (bufoff) + ldsw + _i * 8192), 16, 0, 0); } while (0)
; #define PG8_LDA(dst, b, h) do { _Pragma("unroll") for (int m = 0; m < 4; ++m) _Pragma("unroll") for (int k = 0; k < 2; ++k) dst[m][k] = *(const PG8_LAS bf16x8*)(lds + PG8_SA(b, h) + aoff + m * 2048 + k * 1024); } while (0)
; #define PG8_LDB(dst, b, h) do { _Pragma("unroll") for (int n = 0; n < 2; ++n) _Pragma("unroll") for (int k = 0; k < 2; ++k) dst[n][k] = *(const PG8_LAS bf16x8*)(lds + PG8_SB(b, h) + boff + n * 2048 + k * 1024); } while (0)
; #define PG8_MMA(ai, bj, At, Bt) do { __builtin_amdgcn_s_setprio(3); _Pragma("unroll") for (int m = 0; m < 4; ++m) _Pragma("unroll") for (int n = 0; n < 2; ++n) _Pragma("unroll") for (int k = 0; k < 2; ++k) \
;         acc[ai][bj][m][n] = __builtin_amdgcn_mfma_f32_16x16x32_bf16(Bt[n][k], At[m][k], acc[ai][bj][m][n], 0, 0, 0); __builtin_amdgcn_s_setprio(0); } while (0)
; #define PG8_WAIT_V(n) asm volatile("s_waitcnt vmcnt(" #n ")" ::: "memory")
; #define PG8_WAIT_L(n) asm volatile("s_waitcnt lgkmcnt(" #n ")" ::: "memory")
; #define PG8_BAR __builtin_amdgcn_s_barrier()
; #define PG8_SCHED __builtin_amdgcn_sched_barrier(0)
; template <class Epi, class Sched, bool ALIGN_EPI = false, bool SP2 = false>
; __device__ __forceinline__ void gemm_phase(PG8_LAS unsigned char* lds, const Gemm g, const Sched& S, const Epi& E) {
;     ...
;             const char* a2 = last ? nA : cA + (size_t)(t + 2) * kstep; const char* b2 = last ? nB : cB + (size_t)(t + 2) * kstep;
;             const char* a3 = a2 + kstep; const char* b3 = b2 + kstep;
;             if (last && has_next) S.a_ready(nxt);
;             if constexpr (Epi::MIDK) { if (t == E.midk_step(nt)) E.midk(acc, cur, wr, wc, fr, fq); }
;             if constexpr (SP2) {
;             PG8_LDB(B0, 0, 0); PG8_LDB(B1, 0, 1); PG8_SCHED; PG8_LDA(At, 0, 0); PG8_STAGE(PG8_SA(1, 1), a1 + hstepA, voffA);
;             PG8_WAIT_V(8); PG8_WAIT_L(0); PG8_BAR; PG8_MMA(0, 0, At, B0); PG8_MMA(0, 1, At, B1); PG8_BAR; PG8_SCHED;
;             PG8_LDA(At, 0, 1); PG8_STAGE(PG8_SB(0, 0), b2, voffB); PG8_STAGE(PG8_SB(0, 1), b2 + hstepB, voffB); PG8_STAGE(PG8_SA(0, 0), a2, voffA);
.LBB0_808:
	v_add_u32_e32 v3, s65, v186
	ds_read_b128 v[134:137], v3
	ds_read_b128 v[138:141], v3 offset:1024
	ds_read_b128 v[142:145], v3 offset:2048
	ds_read_b128 v[146:149], v3 offset:3072
	v_add_u32_e32 v3, s66, v186
	s_add_u32 s36, s28, s30
	ds_read_b128 v[150:153], v3
	ds_read_b128 v[154:157], v3 offset:1024
	ds_read_b128 v[158:161], v3 offset:2048
	ds_read_b128 v[190:193], v3 offset:3072
	s_addc_u32 s37, s29, s31
	s_add_u32 s36, s36, 0x100
	s_addc_u32 s37, s37, 0
	s_add_u32 s86, s83, s30
	s_addc_u32 s87, s84, s31
	s_cmpk_eq_i32 s30, 0x1f00
	s_cselect_b32 s41, s23, s37
	s_cselect_b32 s40, s75, s36
	s_cselect_b32 s37, s77, s87
	s_cselect_b32 s36, s78, s86
	v_lshl_add_u64 v[4:5], v[180:181], 0, s[30:31]
	s_add_i32 m0, s42, 0xc000
	ds_read_b128 v[194:197], v188
	ds_read_b128 v[198:201], v188 offset:1024
	ds_read_b128 v[202:205], v188 offset:2048
	ds_read_b128 v[206:209], v188 offset:3072
	ds_read_b128 v[210:213], v188 offset:4096
	ds_read_b128 v[214:217], v188 offset:5120
	ds_read_b128 v[218:221], v188 offset:6144
	ds_read_b128 v[222:225], v188 offset:7168
	global_load_lds_dwordx4 v[4:5], off
	v_lshl_add_u64 v[4:5], v[182:183], 0, s[30:31]
	s_add_i32 m0, s42, 0xe000
	s_nop 0
	global_load_lds_dwordx4 v[4:5], off
	s_waitcnt vmcnt(8)
	s_waitcnt lgkmcnt(0)
	v_mfma_f32_16x16x32_bf16 v[130:133], v[134:137], v[194:197], v[130:133]
	v_mfma_f32_16x16x32_bf16 v[130:133], v[138:141], v[198:201], v[130:133]
	v_mfma_f32_16x16x32_bf16 v[126:129], v[142:145], v[194:197], v[126:129]
	v_mfma_f32_16x16x32_bf16 v[126:129], v[146:149], v[198:201], v[126:129]
	s_barrier
	s_setprio 3
	v_mfma_f32_16x16x32_bf16 v[110:113], v[142:145], v[202:205], v[110:113]
	v_mfma_f32_16x16x32_bf16 v[110:113], v[146:149], v[206:209], v[110:113]
	v_mfma_f32_16x16x32_bf16 v[114:117], v[134:137], v[202:205], v[114:117]
	v_mfma_f32_16x16x32_bf16 v[114:117], v[138:141], v[206:209], v[114:117]
	v_mfma_f32_16x16x32_bf16 v[98:101], v[134:137], v[210:213], v[98:101]
	v_mfma_f32_16x16x32_bf16 v[98:101], v[138:141], v[214:217], v[98:101]
	v_mfma_f32_16x16x32_bf16 v[94:97], v[142:145], v[210:213], v[94:97]
	v_mfma_f32_16x16x32_bf16 v[94:97], v[146:149], v[214:217], v[94:97]
	v_mfma_f32_16x16x32_bf16 v[78:81], v[142:145], v[218:221], v[78:81]
	v_mfma_f32_16x16x32_bf16 v[78:81], v[146:149], v[222:225], v[78:81]
	v_mfma_f32_16x16x32_bf16 v[82:85], v[134:137], v[218:221], v[82:85]
	v_mfma_f32_16x16x32_bf16 v[82:85], v[138:141], v[222:225], v[82:85]
	v_mfma_f32_16x16x32_bf16 v[122:125], v[150:153], v[194:197], v[122:125]
	v_mfma_f32_16x16x32_bf16 v[122:125], v[154:157], v[198:201], v[122:125]
	v_mfma_f32_16x16x32_bf16 v[118:121], v[158:161], v[194:197], v[118:121]
	v_mfma_f32_16x16x32_bf16 v[118:121], v[190:193], v[198:201], v[118:121]
	v_mfma_f32_16x16x32_bf16 v[102:105], v[158:161], v[202:205], v[102:105]
	v_mfma_f32_16x16x32_bf16 v[102:105], v[190:193], v[206:209], v[102:105]
	v_mfma_f32_16x16x32_bf16 v[106:109], v[150:153], v[202:205], v[106:109]
	v_mfma_f32_16x16x32_bf16 v[106:109], v[154:157], v[206:209], v[106:109]
	v_mfma_f32_16x16x32_bf16 v[90:93], v[150:153], v[210:213], v[90:93]
	v_mfma_f32_16x16x32_bf16 v[90:93], v[154:157], v[214:217], v[90:93]
	v_mfma_f32_16x16x32_bf16 v[86:89], v[158:161], v[210:213], v[86:89]
	v_mfma_f32_16x16x32_bf16 v[86:89], v[190:193], v[214:217], v[86:89]
	v_mfma_f32_16x16x32_bf16 v[70:73], v[158:161], v[218:221], v[70:73]
	v_mfma_f32_16x16x32_bf16 v[70:73], v[190:193], v[222:225], v[70:73]
	v_mfma_f32_16x16x32_bf16 v[74:77], v[150:153], v[218:221], v[74:77]
	v_mfma_f32_16x16x32_bf16 v[74:77], v[154:157], v[222:225], v[74:77]
	s_barrier
	s_setprio 0
	s_add_i32 s86, s65, s33
	v_lshl_add_u64 v[226:227], s[36:37], 0, v[166:167]
	s_mov_b32 m0, s86
	ds_read_b128 v[194:197], v188 offset:16384
	ds_read_b128 v[198:201], v188 offset:17408
	ds_read_b128 v[202:205], v188 offset:18432
	ds_read_b128 v[206:209], v188 offset:19456
	ds_read_b128 v[210:213], v188 offset:20480
	ds_read_b128 v[214:217], v188 offset:21504
	ds_read_b128 v[218:221], v188 offset:22528
	ds_read_b128 v[222:225], v188 offset:23552
	global_load_lds_dwordx4 v[226:227], off
	s_add_i32 m0, s86, 0x2000
	s_add_u32 s86, s36, 0x100000
	v_lshl_add_u64 v[228:229], s[36:37], 0, v[170:171]
	s_addc_u32 s87, s37, 0
	s_add_i32 s88, s66, s33
	global_load_lds_dwordx4 v[228:229], off
	v_lshl_add_u64 v[4:5], s[86:87], 0, v[166:167]
	s_mov_b32 m0, s88
	v_lshl_add_u64 v[230:231], s[40:41], 0, v[164:165]
	global_load_lds_dwordx4 v[4:5], off
	v_lshl_add_u64 v[4:5], s[86:87], 0, v[170:171]
	s_add_i32 m0, s88, 0x2000
	v_lshl_add_u64 v[232:233], s[40:41], 0, v[168:169]
	global_load_lds_dwordx4 v[4:5], off
	s_mov_b32 m0, s42
	s_nop 0
	global_load_lds_dwordx4 v[230:231], off
	s_mov_b32 m0, s43
	s_nop 0
	global_load_lds_dwordx4 v[232:233], off
	s_waitcnt vmcnt(8)
	s_waitcnt lgkmcnt(0)
	v_mfma_f32_16x16x32_bf16 v[66:69], v[134:137], v[194:197], v[66:69]
	v_mfma_f32_16x16x32_bf16 v[66:69], v[138:141], v[198:201], v[66:69]
	v_mfma_f32_16x16x32_bf16 v[62:65], v[142:145], v[194:197], v[62:65]
	v_mfma_f32_16x16x32_bf16 v[62:65], v[146:149], v[198:201], v[62:65]
	s_barrier
; #define PG8_STAGE(bufoff, gbase, voff) do { _Pragma("unroll") for (int _i = 0; _i < 2; ++_i) \
;         __builtin_amdgcn_global_load_lds((const unsigned*)((const char*)(gbase) + (voff)[_i]), (PG8_LAS unsigned*)(lds + (bufoff) + ldsw + _i * 8192), 16, 0, 0); } while (0)
; #define PG8_LDA(dst, b, h) do { _Pragma("unroll") for (int m = 0; m < 4; ++m) _Pragma("unroll") for (int k = 0; k < 2; ++k) dst[m][k] = *(const PG8_LAS bf16x8*)(lds + PG8_SA(b, h) + aoff + m * 2048 + k * 1024); } while (0)
; #define PG8_LDB(dst, b, h) do { _Pragma("unroll") for (int n = 0; n < 2; ++n) _Pragma("unroll") for (int k = 0; k < 2; ++k) dst[n][k] = *(const PG8_LAS bf16x8*)(lds + PG8_SB(b, h) + boff + n * 2048 + k * 1024); } while (0)
; #define PG8_MMA(ai, bj, At, Bt) do { __builtin_amdgcn_s_setprio(3); _Pragma("unroll") for (int m = 0; m < 4; ++m) _Pragma("unroll") for (int n = 0; n < 2; ++n) _Pragma("unroll") for (int k = 0; k < 2; ++k) \
;         acc[ai][bj][m][n] = __builtin_amdgcn_mfma_f32_16x16x32_bf16(Bt[n][k], At[m][k], acc[ai][bj][m][n], 0, 0, 0); __builtin_amdgcn_s_setprio(0); } while (0)
; #define PG8_WAIT_V(n) asm volatile("s_waitcnt vmcnt(" #n ")" ::: "memory")
; #define PG8_WAIT_L(n) asm volatile("s_waitcnt lgkmcnt(" #n ")" ::: "memory")
; #define PG8_BAR __builtin_amdgcn_s_barrier()
; #define PG8_SCHED __builtin_amdgcn_sched_barrier(0)
; template <class Epi, class Sched, bool ALIGN_EPI = false, bool SP2 = false>
; __device__ __forceinline__ void gemm_phase(PG8_LAS unsigned char* lds, const Gemm g, const Sched& S, const Epi& E) {
;     ...
;             PG8_WAIT_V(8); PG8_WAIT_L(0); PG8_BAR; PG8_MMA(1, 0, At, B0); PG8_MMA(1, 1, At, B1); PG8_BAR; PG8_SCHED;
;             PG8_LDB(B0, 1, 0); PG8_LDB(B1, 1, 1); PG8_SCHED; PG8_LDA(At, 1, 0); PG8_STAGE(PG8_SA(0, 1), a2 + hstepA, voffA);
;             PG8_WAIT_V(8); PG8_WAIT_L(0); PG8_BAR; PG8_MMA(0, 0, At, B0); PG8_MMA(0, 1, At, B1); PG8_BAR; PG8_SCHED;
	s_setprio 3
	v_mfma_f32_16x16x32_bf16 v[46:49], v[142:145], v[202:205], v[46:49]
	v_mfma_f32_16x16x32_bf16 v[46:49], v[146:149], v[206:209], v[46:49]
	v_mfma_f32_16x16x32_bf16 v[50:53], v[134:137], v[202:205], v[50:53]
	v_mfma_f32_16x16x32_bf16 v[50:53], v[138:141], v[206:209], v[50:53]
	v_mfma_f32_16x16x32_bf16 v[34:37], v[134:137], v[210:213], v[34:37]
	v_mfma_f32_16x16x32_bf16 v[34:37], v[138:141], v[214:217], v[34:37]
	v_mfma_f32_16x16x32_bf16 v[30:33], v[142:145], v[210:213], v[30:33]
	v_mfma_f32_16x16x32_bf16 v[30:33], v[146:149], v[214:217], v[30:33]
	v_mfma_f32_16x16x32_bf16 v[14:17], v[142:145], v[218:221], v[14:17]
	v_mfma_f32_16x16x32_bf16 v[14:17], v[146:149], v[222:225], v[14:17]
	v_mfma_f32_16x16x32_bf16 v[18:21], v[134:137], v[218:221], v[18:21]
	v_mfma_f32_16x16x32_bf16 v[18:21], v[138:141], v[222:225], v[18:21]
	v_mfma_f32_16x16x32_bf16 v[58:61], v[150:153], v[194:197], v[58:61]
	v_mfma_f32_16x16x32_bf16 v[58:61], v[154:157], v[198:201], v[58:61]
	v_mfma_f32_16x16x32_bf16 v[54:57], v[158:161], v[194:197], v[54:57]
	v_mfma_f32_16x16x32_bf16 v[54:57], v[190:193], v[198:201], v[54:57]
	v_mfma_f32_16x16x32_bf16 v[38:41], v[158:161], v[202:205], v[38:41]
	v_mfma_f32_16x16x32_bf16 v[38:41], v[190:193], v[206:209], v[38:41]
	v_mfma_f32_16x16x32_bf16 v[42:45], v[150:153], v[202:205], v[42:45]
	v_mfma_f32_16x16x32_bf16 v[42:45], v[154:157], v[206:209], v[42:45]
	v_mfma_f32_16x16x32_bf16 v[26:29], v[150:153], v[210:213], v[26:29]
	v_mfma_f32_16x16x32_bf16 v[26:29], v[154:157], v[214:217], v[26:29]
	v_mfma_f32_16x16x32_bf16 v[22:25], v[158:161], v[210:213], v[22:25]
	v_mfma_f32_16x16x32_bf16 v[22:25], v[190:193], v[214:217], v[22:25]
	v_mfma_f32_16x16x32_bf16 v[4:7], v[158:161], v[218:221], v[6:9]
	v_mfma_f32_16x16x32_bf16 v[4:7], v[190:193], v[222:225], v[4:7]
	v_mfma_f32_16x16x32_bf16 v[10:13], v[150:153], v[218:221], v[10:13]
	v_mfma_f32_16x16x32_bf16 v[10:13], v[154:157], v[222:225], v[10:13]
	s_barrier
	s_setprio 0
	s_add_i32 s86, 0, 0x18000
	v_add_u32_e32 v3, s86, v186
	s_add_i32 s87, 0, 0x1c000
	ds_read_b128 v[134:137], v3
	ds_read_b128 v[138:141], v3 offset:1024
	ds_read_b128 v[142:145], v3 offset:2048
	ds_read_b128 v[146:149], v3 offset:3072
	v_add_u32_e32 v3, s87, v186
	ds_read_b128 v[150:153], v3
	ds_read_b128 v[154:157], v3 offset:1024
	ds_read_b128 v[158:161], v3 offset:2048
	ds_read_b128 v[190:193], v3 offset:3072
	s_add_u32 s40, s40, 0x100000
	s_addc_u32 s41, s41, 0
	s_mov_b32 m0, s44
	v_lshl_add_u64 v[8:9], s[40:41], 0, v[164:165]
	ds_read_b128 v[194:197], v188 offset:32768
	ds_read_b128 v[198:201], v188 offset:33792
	ds_read_b128 v[202:205], v188 offset:34816
	ds_read_b128 v[206:209], v188 offset:35840
	ds_read_b128 v[210:213], v188 offset:36864
	ds_read_b128 v[214:217], v188 offset:37888
	ds_read_b128 v[218:221], v188 offset:38912
	ds_read_b128 v[222:225], v188 offset:39936
	global_load_lds_dwordx4 v[8:9], off
	v_lshl_add_u64 v[8:9], s[40:41], 0, v[168:169]
	s_mov_b32 m0, s45
	s_nop 0
	global_load_lds_dwordx4 v[8:9], off
	s_waitcnt vmcnt(8)
	s_waitcnt lgkmcnt(0)
	v_mfma_f32_16x16x32_bf16 v[130:133], v[134:137], v[194:197], v[130:133]
	v_mfma_f32_16x16x32_bf16 v[130:133], v[138:141], v[198:201], v[130:133]
	v_mfma_f32_16x16x32_bf16 v[126:129], v[142:145], v[194:197], v[126:129]
	v_mfma_f32_16x16x32_bf16 v[126:129], v[146:149], v[198:201], v[126:129]
	s_barrier
	s_setprio 3
	v_mfma_f32_16x16x32_bf16 v[110:113], v[142:145], v[202:205], v[110:113]
	v_mfma_f32_16x16x32_bf16 v[110:113], v[146:149], v[206:209], v[110:113]
	v_mfma_f32_16x16x32_bf16 v[114:117], v[134:137], v[202:205], v[114:117]
	v_mfma_f32_16x16x32_bf16 v[114:117], v[138:141], v[206:209], v[114:117]
	v_mfma_f32_16x16x32_bf16 v[98:101], v[134:137], v[210:213], v[98:101]
	v_mfma_f32_16x16x32_bf16 v[98:101], v[138:141], v[214:217], v[98:101]
	v_mfma_f32_16x16x32_bf16 v[94:97], v[142:145], v[210:213], v[94:97]
	v_mfma_f32_16x16x32_bf16 v[94:97], v[146:149], v[214:217], v[94:97]
	v_mfma_f32_16x16x32_bf16 v[78:81], v[142:145], v[218:221], v[78:81]
	v_mfma_f32_16x16x32_bf16 v[78:81], v[146:149], v[222:225], v[78:81]
	v_mfma_f32_16x16x32_bf16 v[82:85], v[134:137], v[218:221], v[82:85]
	v_mfma_f32_16x16x32_bf16 v[82:85], v[138:141], v[222:225], v[82:85]
	v_mfma_f32_16x16x32_bf16 v[122:125], v[150:153], v[194:197], v[122:125]
	v_mfma_f32_16x16x32_bf16 v[122:125], v[154:157], v[198:201], v[122:125]
	v_mfma_f32_16x16x32_bf16 v[118:121], v[158:161], v[194:197], v[118:121]
	v_mfma_f32_16x16x32_bf16 v[118:121], v[190:193], v[198:201], v[118:121]
	v_mfma_f32_16x16x32_bf16 v[102:105], v[158:161], v[202:205], v[102:105]
	v_mfma_f32_16x16x32_bf16 v[102:105], v[190:193], v[206:209], v[102:105]
	v_mfma_f32_16x16x32_bf16 v[106:109], v[150:153], v[202:205], v[106:109]
	v_mfma_f32_16x16x32_bf16 v[106:109], v[154:157], v[206:209], v[106:109]
	v_mfma_f32_16x16x32_bf16 v[90:93], v[150:153], v[210:213], v[90:93]
	v_mfma_f32_16x16x32_bf16 v[90:93], v[154:157], v[214:217], v[90:93]
	v_mfma_f32_16x16x32_bf16 v[86:89], v[158:161], v[210:213], v[86:89]
	v_mfma_f32_16x16x32_bf16 v[86:89], v[190:193], v[214:217], v[86:89]
	v_mfma_f32_16x16x32_bf16 v[70:73], v[158:161], v[218:221], v[70:73]
	v_mfma_f32_16x16x32_bf16 v[70:73], v[190:193], v[222:225], v[70:73]
	v_mfma_f32_16x16x32_bf16 v[74:77], v[150:153], v[218:221], v[74:77]
	v_mfma_f32_16x16x32_bf16 v[74:77], v[154:157], v[222:225], v[74:77]
	s_barrier
; #define PG8_STAGE(bufoff, gbase, voff) do { _Pragma("unroll") for (int _i = 0; _i < 2; ++_i) \
;         __builtin_amdgcn_global_load_lds((const unsigned*)((const char*)(gbase) + (voff)[_i]), (PG8_LAS unsigned*)(lds + (bufoff) + ldsw + _i * 8192), 16, 0, 0); } while (0)
; #define PG8_LDA(dst, b, h) do { _Pragma("unroll") for (int m = 0; m < 4; ++m) _Pragma("unroll") for (int k = 0; k < 2; ++k) dst[m][k] = *(const PG8_LAS bf16x8*)(lds + PG8_SA(b, h) + aoff + m * 2048 + k * 1024); } while (0)
; #define PG8_MMA(ai, bj, At, Bt) do { __builtin_amdgcn_s_setprio(3); _Pragma("unroll") for (int m = 0; m < 4; ++m) _Pragma("unroll") for (int n = 0; n < 2; ++n) _Pragma("unroll") for (int k = 0; k < 2; ++k) \
;         acc[ai][bj][m][n] = __builtin_amdgcn_mfma_f32_16x16x32_bf16(Bt[n][k], At[m][k], acc[ai][bj][m][n], 0, 0, 0); __builtin_amdgcn_s_setprio(0); } while (0)
; #define PG8_WAIT_V(n) asm volatile("s_waitcnt vmcnt(" #n ")" ::: "memory")
; #define PG8_WAIT_L(n) asm volatile("s_waitcnt lgkmcnt(" #n ")" ::: "memory")
; #define PG8_BAR __builtin_amdgcn_s_barrier()
; #define PG8_SCHED __builtin_amdgcn_sched_barrier(0)
; template <class Epi, class Sched, bool ALIGN_EPI = false, bool SP2 = false>
; __device__ __forceinline__ void gemm_phase(PG8_LAS unsigned char* lds, const Gemm g, const Sched& S, const Epi& E) {
;     ...
;             PG8_LDA(At, 1, 1); PG8_STAGE(PG8_SB(1, 0), b3, voffB); PG8_STAGE(PG8_SB(1, 1), b3 + hstepB, voffB); PG8_STAGE(PG8_SA(1, 0), a3, voffA);
;             PG8_WAIT_V(8); PG8_WAIT_L(0); PG8_BAR; PG8_MMA(1, 0, At, B0); PG8_MMA(1, 1, At, B1); PG8_BAR; PG8_SCHED;
	s_setprio 0
	s_add_i32 s40, s86, s33
	v_lshl_add_u64 v[8:9], v[226:227], 0, s[10:11]
	s_mov_b32 m0, s40
	ds_read_b128 v[194:197], v188 offset:49152
	ds_read_b128 v[198:201], v188 offset:50176
	ds_read_b128 v[202:205], v188 offset:51200
	ds_read_b128 v[206:209], v188 offset:52224
	ds_read_b128 v[210:213], v188 offset:53248
	ds_read_b128 v[214:217], v188 offset:54272
	ds_read_b128 v[218:221], v188 offset:55296
	ds_read_b128 v[222:225], v188 offset:56320
	global_load_lds_dwordx4 v[8:9], off
	s_add_i32 m0, s40, 0x2000
	s_add_u32 s36, s36, 0x100080
	v_lshl_add_u64 v[8:9], v[228:229], 0, s[10:11]
	s_addc_u32 s37, s37, 0
	s_add_i32 s40, s87, s33
	global_load_lds_dwordx4 v[8:9], off
	v_lshl_add_u64 v[8:9], s[36:37], 0, v[166:167]
	s_mov_b32 m0, s40
	s_nop 0
	global_load_lds_dwordx4 v[8:9], off
	v_lshl_add_u64 v[8:9], s[36:37], 0, v[170:171]
	s_add_i32 m0, s40, 0x2000
	s_nop 0
	global_load_lds_dwordx4 v[8:9], off
	v_lshl_add_u64 v[8:9], v[230:231], 0, s[10:11]
	s_mov_b32 m0, s60
	s_nop 0
	global_load_lds_dwordx4 v[8:9], off
	v_lshl_add_u64 v[8:9], v[232:233], 0, s[10:11]
	s_mov_b32 m0, s61
	s_nop 0
	global_load_lds_dwordx4 v[8:9], off
	s_waitcnt vmcnt(8)
	s_waitcnt lgkmcnt(0)
	v_mfma_f32_16x16x32_bf16 v[66:69], v[134:137], v[194:197], v[66:69]
	v_mfma_f32_16x16x32_bf16 v[66:69], v[138:141], v[198:201], v[66:69]
	v_mfma_f32_16x16x32_bf16 v[62:65], v[142:145], v[194:197], v[62:65]
	v_mfma_f32_16x16x32_bf16 v[62:65], v[146:149], v[198:201], v[62:65]
	s_barrier
	s_setprio 3
	v_mfma_f32_16x16x32_bf16 v[46:49], v[142:145], v[202:205], v[46:49]
	v_mfma_f32_16x16x32_bf16 v[46:49], v[146:149], v[206:209], v[46:49]
	v_mfma_f32_16x16x32_bf16 v[50:53], v[134:137], v[202:205], v[50:53]
	v_mfma_f32_16x16x32_bf16 v[50:53], v[138:141], v[206:209], v[50:53]
	v_mfma_f32_16x16x32_bf16 v[34:37], v[134:137], v[210:213], v[34:37]
	v_mfma_f32_16x16x32_bf16 v[34:37], v[138:141], v[214:217], v[34:37]
	v_mfma_f32_16x16x32_bf16 v[30:33], v[142:145], v[210:213], v[30:33]
	v_mfma_f32_16x16x32_bf16 v[30:33], v[146:149], v[214:217], v[30:33]
	v_mfma_f32_16x16x32_bf16 v[14:17], v[142:145], v[218:221], v[14:17]
	v_mfma_f32_16x16x32_bf16 v[14:17], v[146:149], v[222:225], v[14:17]
	v_mfma_f32_16x16x32_bf16 v[18:21], v[134:137], v[218:221], v[18:21]
	v_mfma_f32_16x16x32_bf16 v[18:21], v[138:141], v[222:225], v[18:21]
	v_mfma_f32_16x16x32_bf16 v[58:61], v[150:153], v[194:197], v[58:61]
	v_mfma_f32_16x16x32_bf16 v[54:57], v[158:161], v[194:197], v[54:57]
	v_mfma_f32_16x16x32_bf16 v[42:45], v[150:153], v[202:205], v[42:45]
	v_mfma_f32_16x16x32_bf16 v[38:41], v[158:161], v[202:205], v[38:41]
	v_mfma_f32_16x16x32_bf16 v[26:29], v[150:153], v[210:213], v[26:29]
	v_mfma_f32_16x16x32_bf16 v[22:25], v[158:161], v[210:213], v[22:25]
	v_mfma_f32_16x16x32_bf16 v[8:11], v[150:153], v[218:221], v[10:13]
	v_mfma_f32_16x16x32_bf16 v[4:7], v[158:161], v[218:221], v[4:7]
	v_mfma_f32_16x16x32_bf16 v[58:61], v[154:157], v[198:201], v[58:61]
	v_mfma_f32_16x16x32_bf16 v[54:57], v[190:193], v[198:201], v[54:57]
	v_mfma_f32_16x16x32_bf16 v[42:45], v[154:157], v[206:209], v[42:45]
	v_mfma_f32_16x16x32_bf16 v[38:41], v[190:193], v[206:209], v[38:41]
	v_mfma_f32_16x16x32_bf16 v[26:29], v[154:157], v[214:217], v[26:29]
	v_mfma_f32_16x16x32_bf16 v[22:25], v[190:193], v[214:217], v[22:25]
	v_mfma_f32_16x16x32_bf16 v[10:13], v[154:157], v[222:225], v[8:11]
	v_mfma_f32_16x16x32_bf16 v[6:9], v[190:193], v[222:225], v[4:7]
	s_barrier
	s_setprio 0
	s_add_i32 s85, s85, 2
	s_add_u32 s30, s30, 0x100
	s_addc_u32 s31, s31, 0
	s_cmp_gt_u32 s85, 61
	s_cbranch_scc1 .LBB0_811

; #define PG8_STAGE(bufoff, gbase, voff) do { _Pragma("unroll") for (int _i = 0; _i < 2; ++_i) \
;         __builtin_amdgcn_global_load_lds((const unsigned*)((const char*)(gbase) + (voff)[_i]), (PG8_LAS unsigned*)(lds + (bufoff) + ldsw + _i * 8192), 16, 0, 0); } while (0)
; #define PG8_LDA(dst, b, h) do { _Pragma("unroll") for (int m = 0; m < 4; ++m) _Pragma("unroll") for (int k = 0; k < 2; ++k) dst[m][k] = *(const PG8_LAS bf16x8*)(lds + PG8_SA(b, h) + aoff + m * 2048 + k * 1024); } while (0)
; #define PG8_LDB(dst, b, h) do { _Pragma("unroll") for (int n = 0; n < 2; ++n) _Pragma("unroll") for (int k = 0; k < 2; ++k) dst[n][k] = *(const PG8_LAS bf16x8*)(lds + PG8_SB(b, h) + boff + n * 2048 + k * 1024); } while (0)
; #define PG8_MMA(ai, bj, At, Bt) do { __builtin_amdgcn_s_setprio(3); _Pragma("unroll") for (int m = 0; m < 4; ++m) _Pragma("unroll") for (int n = 0; n < 2; ++n) _Pragma("unroll") for (int k = 0; k < 2; ++k) \
;         acc[ai][bj][m][n] = __builtin_amdgcn_mfma_f32_16x16x32_bf16(Bt[n][k], At[m][k], acc[ai][bj][m][n], 0, 0, 0); __builtin_amdgcn_s_setprio(0); } while (0)
; #define PG8_WAIT_V(n) asm volatile("s_waitcnt vmcnt(" #n ")" ::: "memory")
; #define PG8_WAIT_L(n) asm volatile("s_waitcnt lgkmcnt(" #n ")" ::: "memory")
; #define PG8_BAR __builtin_amdgcn_s_barrier()
; #define PG8_SCHED __builtin_amdgcn_sched_barrier(0)
; template <class Epi, class Sched, bool ALIGN_EPI = false, bool SP2 = false>
; __device__ __forceinline__ void gemm_phase(PG8_LAS unsigned char* lds, const Gemm g, const Sched& S, const Epi& E) {
;     ...
;             const char* a2 = last ? nA : cA + (size_t)(t + 2) * kstep; const char* b2 = last ? nB : cB + (size_t)(t + 2) * kstep;
;             const char* a3 = a2 + kstep; const char* b3 = b2 + kstep;
;             if (last && has_next) S.a_ready(nxt);
;             if constexpr (Epi::MIDK) { if (t == E.midk_step(nt)) E.midk(acc, cur, wr, wc, fr, fq); }
;             if constexpr (SP2) {
;             PG8_LDB(B0, 0, 0); PG8_LDB(B1, 0, 1); PG8_SCHED; PG8_LDA(At, 0, 0); PG8_STAGE(PG8_SA(1, 1), a1 + hstepA, voffA);
;             PG8_WAIT_V(8); PG8_WAIT_L(0); PG8_BAR; PG8_MMA(0, 0, At, B0); PG8_MMA(0, 1, At, B1); PG8_BAR; PG8_SCHED;
;             PG8_LDA(At, 0, 1); PG8_STAGE(PG8_SB(0, 0), b2, voffB); PG8_STAGE(PG8_SB(0, 1), b2 + hstepB, voffB); PG8_STAGE(PG8_SA(0, 0), a2, voffA);
.LBB0_908:
	ds_read_b128 v[158:161], v155
	ds_read_b128 v[164:167], v155 offset:1024
	ds_read_b128 v[168:171], v155 offset:2048
	ds_read_b128 v[172:175], v155 offset:3072
	ds_read_b128 v[176:179], v156
	ds_read_b128 v[180:183], v156 offset:1024
	ds_read_b128 v[184:187], v156 offset:2048
	ds_read_b128 v[188:191], v156 offset:3072
	s_add_u32 s26, s24, 0xfff00080
	s_addc_u32 s27, s25, -1
	s_cmp_eq_u32 s55, 60
	s_cselect_b32 s29, s17, s27
	s_cselect_b32 s28, s47, s26
	s_cselect_b32 s27, s15, s54
	s_cselect_b32 s26, s52, s53
	v_lshl_add_u64 v[146:147], s[24:25], 0, v[138:139]
	s_add_i32 m0, s23, 0xc000
	ds_read_b128 v[192:195], v157
	ds_read_b128 v[196:199], v157 offset:1024
	ds_read_b128 v[200:203], v157 offset:2048
	ds_read_b128 v[204:207], v157 offset:3072
	ds_read_b128 v[208:211], v157 offset:4096
	ds_read_b128 v[212:215], v157 offset:5120
	ds_read_b128 v[216:219], v157 offset:6144
	ds_read_b128 v[220:223], v157 offset:7168
	global_load_lds_dwordx4 v[146:147], off
	v_lshl_add_u64 v[146:147], s[24:25], 0, v[140:141]
	s_add_i32 m0, s23, 0xe000
	s_nop 0
	global_load_lds_dwordx4 v[146:147], off
	s_waitcnt vmcnt(8)
	s_waitcnt lgkmcnt(0)
	v_mfma_f32_16x16x32_bf16 v[126:129], v[158:161], v[192:195], v[126:129]
	v_mfma_f32_16x16x32_bf16 v[126:129], v[164:167], v[196:199], v[126:129]
	v_mfma_f32_16x16x32_bf16 v[122:125], v[168:171], v[192:195], v[122:125]
	v_mfma_f32_16x16x32_bf16 v[122:125], v[172:175], v[196:199], v[122:125]
	s_barrier
	s_setprio 3
	v_mfma_f32_16x16x32_bf16 v[106:109], v[168:171], v[200:203], v[106:109]
	v_mfma_f32_16x16x32_bf16 v[106:109], v[172:175], v[204:207], v[106:109]
	v_mfma_f32_16x16x32_bf16 v[114:117], v[158:161], v[200:203], v[114:117]
	v_mfma_f32_16x16x32_bf16 v[114:117], v[164:167], v[204:207], v[114:117]
	v_mfma_f32_16x16x32_bf16 v[98:101], v[158:161], v[208:211], v[98:101]
	v_mfma_f32_16x16x32_bf16 v[98:101], v[164:167], v[212:215], v[98:101]
	v_mfma_f32_16x16x32_bf16 v[90:93], v[168:171], v[208:211], v[90:93]
	v_mfma_f32_16x16x32_bf16 v[90:93], v[172:175], v[212:215], v[90:93]
	v_mfma_f32_16x16x32_bf16 v[74:77], v[168:171], v[216:219], v[74:77]
	v_mfma_f32_16x16x32_bf16 v[74:77], v[172:175], v[220:223], v[74:77]
	v_mfma_f32_16x16x32_bf16 v[82:85], v[158:161], v[216:219], v[82:85]
	v_mfma_f32_16x16x32_bf16 v[82:85], v[164:167], v[220:223], v[82:85]
	v_mfma_f32_16x16x32_bf16 v[118:121], v[176:179], v[192:195], v[118:121]
	v_mfma_f32_16x16x32_bf16 v[118:121], v[180:183], v[196:199], v[118:121]
	v_mfma_f32_16x16x32_bf16 v[110:113], v[184:187], v[192:195], v[110:113]
	v_mfma_f32_16x16x32_bf16 v[110:113], v[188:191], v[196:199], v[110:113]
	v_mfma_f32_16x16x32_bf16 v[94:97], v[184:187], v[200:203], v[94:97]
	v_mfma_f32_16x16x32_bf16 v[94:97], v[188:191], v[204:207], v[94:97]
	v_mfma_f32_16x16x32_bf16 v[102:105], v[176:179], v[200:203], v[102:105]
	v_mfma_f32_16x16x32_bf16 v[102:105], v[180:183], v[204:207], v[102:105]
	v_mfma_f32_16x16x32_bf16 v[86:89], v[176:179], v[208:211], v[86:89]
	v_mfma_f32_16x16x32_bf16 v[86:89], v[180:183], v[212:215], v[86:89]
	v_mfma_f32_16x16x32_bf16 v[78:81], v[184:187], v[208:211], v[78:81]
	v_mfma_f32_16x16x32_bf16 v[78:81], v[188:191], v[212:215], v[78:81]
	v_mfma_f32_16x16x32_bf16 v[66:69], v[184:187], v[216:219], v[66:69]
	v_mfma_f32_16x16x32_bf16 v[66:69], v[188:191], v[220:223], v[66:69]
	v_mfma_f32_16x16x32_bf16 v[70:73], v[176:179], v[216:219], v[70:73]
	v_mfma_f32_16x16x32_bf16 v[70:73], v[180:183], v[220:223], v[70:73]
	s_barrier
	s_setprio 0
	s_add_i32 s56, s42, s30
	v_lshl_add_u64 v[146:147], s[26:27], 0, v[134:135]
	s_mov_b32 m0, s56
	ds_read_b128 v[192:195], v157 offset:16384
	ds_read_b128 v[196:199], v157 offset:17408
	ds_read_b128 v[200:203], v157 offset:18432
	ds_read_b128 v[204:207], v157 offset:19456
	ds_read_b128 v[208:211], v157 offset:20480
	ds_read_b128 v[212:215], v157 offset:21504
	ds_read_b128 v[216:219], v157 offset:22528
	ds_read_b128 v[220:223], v157 offset:23552
	global_load_lds_dwordx4 v[146:147], off
	s_add_i32 m0, s56, 0x2000
	s_add_u32 s56, s26, 0x100000
	v_lshl_add_u64 v[224:225], s[26:27], 0, v[130:131]
	s_addc_u32 s57, s27, 0
	s_add_i32 s58, s43, s30
	global_load_lds_dwordx4 v[224:225], off
	v_lshl_add_u64 v[226:227], s[56:57], 0, v[134:135]
	s_mov_b32 m0, s58
	v_lshl_add_u64 v[228:229], s[28:29], 0, v[132:133]
	global_load_lds_dwordx4 v[226:227], off
	v_lshl_add_u64 v[226:227], s[56:57], 0, v[130:131]
	s_add_i32 m0, s58, 0x2000
	s_nop 0
	global_load_lds_dwordx4 v[226:227], off
	v_lshl_add_u64 v[226:227], s[28:29], 0, v[136:137]
	s_mov_b32 m0, s23
	s_nop 0
	global_load_lds_dwordx4 v[226:227], off
	s_mov_b32 m0, s33
	s_nop 0
	global_load_lds_dwordx4 v[228:229], off
	s_waitcnt vmcnt(8)
	s_waitcnt lgkmcnt(0)
	v_mfma_f32_16x16x32_bf16 v[62:65], v[158:161], v[192:195], v[62:65]
	v_mfma_f32_16x16x32_bf16 v[62:65], v[164:167], v[196:199], v[62:65]
	v_mfma_f32_16x16x32_bf16 v[58:61], v[168:171], v[192:195], v[58:61]
	v_mfma_f32_16x16x32_bf16 v[58:61], v[172:175], v[196:199], v[58:61]
	s_barrier
; #define PG8_STAGE(bufoff, gbase, voff) do { _Pragma("unroll") for (int _i = 0; _i < 2; ++_i) \
;         __builtin_amdgcn_global_load_lds((const unsigned*)((const char*)(gbase) + (voff)[_i]), (PG8_LAS unsigned*)(lds + (bufoff) + ldsw + _i * 8192), 16, 0, 0); } while (0)
; #define PG8_LDA(dst, b, h) do { _Pragma("unroll") for (int m = 0; m < 4; ++m) _Pragma("unroll") for (int k = 0; k < 2; ++k) dst[m][k] = *(const PG8_LAS bf16x8*)(lds + PG8_SA(b, h) + aoff + m * 2048 + k * 1024); } while (0)
; #define PG8_LDB(dst, b, h) do { _Pragma("unroll") for (int n = 0; n < 2; ++n) _Pragma("unroll") for (int k = 0; k < 2; ++k) dst[n][k] = *(const PG8_LAS bf16x8*)(lds + PG8_SB(b, h) + boff + n * 2048 + k * 1024); } while (0)
; #define PG8_MMA(ai, bj, At, Bt) do { __builtin_amdgcn_s_setprio(3); _Pragma("unroll") for (int m = 0; m < 4; ++m) _Pragma("unroll") for (int n = 0; n < 2; ++n) _Pragma("unroll") for (int k = 0; k < 2; ++k) \
;         acc[ai][bj][m][n] = __builtin_amdgcn_mfma_f32_16x16x32_bf16(Bt[n][k], At[m][k], acc[ai][bj][m][n], 0, 0, 0); __builtin_amdgcn_s_setprio(0); } while (0)
; #define PG8_WAIT_V(n) asm volatile("s_waitcnt vmcnt(" #n ")" ::: "memory")
; #define PG8_WAIT_L(n) asm volatile("s_waitcnt lgkmcnt(" #n ")" ::: "memory")
; #define PG8_BAR __builtin_amdgcn_s_barrier()
; #define PG8_SCHED __builtin_amdgcn_sched_barrier(0)
; template <class Epi, class Sched, bool ALIGN_EPI = false, bool SP2 = false>
; __device__ __forceinline__ void gemm_phase(PG8_LAS unsigned char* lds, const Gemm g, const Sched& S, const Epi& E) {
;     ...
;             PG8_WAIT_V(8); PG8_WAIT_L(0); PG8_BAR; PG8_MMA(1, 0, At, B0); PG8_MMA(1, 1, At, B1); PG8_BAR; PG8_SCHED;
;             PG8_LDB(B0, 1, 0); PG8_LDB(B1, 1, 1); PG8_SCHED; PG8_LDA(At, 1, 0); PG8_STAGE(PG8_SA(0, 1), a2 + hstepA, voffA);
;             PG8_WAIT_V(8); PG8_WAIT_L(0); PG8_BAR; PG8_MMA(0, 0, At, B0); PG8_MMA(0, 1, At, B1); PG8_BAR; PG8_SCHED;
	s_setprio 3
	v_mfma_f32_16x16x32_bf16 v[42:45], v[168:171], v[200:203], v[42:45]
	v_mfma_f32_16x16x32_bf16 v[42:45], v[172:175], v[204:207], v[42:45]
	v_mfma_f32_16x16x32_bf16 v[50:53], v[158:161], v[200:203], v[50:53]
	v_mfma_f32_16x16x32_bf16 v[50:53], v[164:167], v[204:207], v[50:53]
	v_mfma_f32_16x16x32_bf16 v[34:37], v[158:161], v[208:211], v[34:37]
	v_mfma_f32_16x16x32_bf16 v[34:37], v[164:167], v[212:215], v[34:37]
	v_mfma_f32_16x16x32_bf16 v[26:29], v[168:171], v[208:211], v[26:29]
	v_mfma_f32_16x16x32_bf16 v[26:29], v[172:175], v[212:215], v[26:29]
	v_mfma_f32_16x16x32_bf16 v[10:13], v[168:171], v[216:219], v[10:13]
	v_mfma_f32_16x16x32_bf16 v[10:13], v[172:175], v[220:223], v[10:13]
	v_mfma_f32_16x16x32_bf16 v[14:17], v[158:161], v[216:219], v[14:17]
	v_mfma_f32_16x16x32_bf16 v[14:17], v[164:167], v[220:223], v[14:17]
	v_mfma_f32_16x16x32_bf16 v[54:57], v[176:179], v[192:195], v[54:57]
	v_mfma_f32_16x16x32_bf16 v[54:57], v[180:183], v[196:199], v[54:57]
	v_mfma_f32_16x16x32_bf16 v[46:49], v[184:187], v[192:195], v[46:49]
	v_mfma_f32_16x16x32_bf16 v[46:49], v[188:191], v[196:199], v[46:49]
	v_mfma_f32_16x16x32_bf16 v[30:33], v[184:187], v[200:203], v[30:33]
	v_mfma_f32_16x16x32_bf16 v[30:33], v[188:191], v[204:207], v[30:33]
	v_mfma_f32_16x16x32_bf16 v[38:41], v[176:179], v[200:203], v[38:41]
	v_mfma_f32_16x16x32_bf16 v[38:41], v[180:183], v[204:207], v[38:41]
	v_mfma_f32_16x16x32_bf16 v[22:25], v[176:179], v[208:211], v[22:25]
	v_mfma_f32_16x16x32_bf16 v[22:25], v[180:183], v[212:215], v[22:25]
	v_mfma_f32_16x16x32_bf16 v[18:21], v[184:187], v[208:211], v[18:21]
	v_mfma_f32_16x16x32_bf16 v[18:21], v[188:191], v[212:215], v[18:21]
	v_mfma_f32_16x16x32_bf16 v[2:5], v[184:187], v[216:219], v[2:5]
	v_mfma_f32_16x16x32_bf16 v[2:5], v[188:191], v[220:223], v[2:5]
	v_mfma_f32_16x16x32_bf16 v[6:9], v[176:179], v[216:219], v[6:9]
	v_mfma_f32_16x16x32_bf16 v[6:9], v[180:183], v[220:223], v[6:9]
	s_barrier
	s_setprio 0
	s_add_i32 s56, 0, 0x18000
	v_add_u32_e32 v148, s56, v151
	s_add_i32 s57, 0, 0x1c000
	ds_read_b128 v[158:161], v148
	ds_read_b128 v[164:167], v148 offset:1024
	ds_read_b128 v[168:171], v148 offset:2048
	ds_read_b128 v[172:175], v148 offset:3072
	v_add_u32_e32 v148, s57, v151
	ds_read_b128 v[176:179], v148
	ds_read_b128 v[180:183], v148 offset:1024
	ds_read_b128 v[184:187], v148 offset:2048
	ds_read_b128 v[188:191], v148 offset:3072
	s_add_u32 s28, s28, 0x100000
	s_addc_u32 s29, s29, 0
	s_mov_b32 m0, s36
	v_lshl_add_u64 v[230:231], s[28:29], 0, v[136:137]
	ds_read_b128 v[192:195], v157 offset:32768
	ds_read_b128 v[196:199], v157 offset:33792
	ds_read_b128 v[200:203], v157 offset:34816
	ds_read_b128 v[204:207], v157 offset:35840
	ds_read_b128 v[208:211], v157 offset:36864
	ds_read_b128 v[212:215], v157 offset:37888
	ds_read_b128 v[216:219], v157 offset:38912
	ds_read_b128 v[220:223], v157 offset:39936
	global_load_lds_dwordx4 v[230:231], off
	v_lshl_add_u64 v[230:231], s[28:29], 0, v[132:133]
	s_mov_b32 m0, s37
	s_nop 0
	global_load_lds_dwordx4 v[230:231], off
	s_waitcnt vmcnt(8)
	s_waitcnt lgkmcnt(0)
	v_mfma_f32_16x16x32_bf16 v[126:129], v[158:161], v[192:195], v[126:129]
	v_mfma_f32_16x16x32_bf16 v[126:129], v[164:167], v[196:199], v[126:129]
	v_mfma_f32_16x16x32_bf16 v[122:125], v[168:171], v[192:195], v[122:125]
	v_mfma_f32_16x16x32_bf16 v[122:125], v[172:175], v[196:199], v[122:125]
	s_barrier
	s_setprio 3
	v_mfma_f32_16x16x32_bf16 v[106:109], v[168:171], v[200:203], v[106:109]
	v_mfma_f32_16x16x32_bf16 v[106:109], v[172:175], v[204:207], v[106:109]
	v_mfma_f32_16x16x32_bf16 v[114:117], v[158:161], v[200:203], v[114:117]
	v_mfma_f32_16x16x32_bf16 v[114:117], v[164:167], v[204:207], v[114:117]
	v_mfma_f32_16x16x32_bf16 v[98:101], v[158:161], v[208:211], v[98:101]
	v_mfma_f32_16x16x32_bf16 v[98:101], v[164:167], v[212:215], v[98:101]
	v_mfma_f32_16x16x32_bf16 v[90:93], v[168:171], v[208:211], v[90:93]
	v_mfma_f32_16x16x32_bf16 v[90:93], v[172:175], v[212:215], v[90:93]
	v_mfma_f32_16x16x32_bf16 v[74:77], v[168:171], v[216:219], v[74:77]
	v_mfma_f32_16x16x32_bf16 v[74:77], v[172:175], v[220:223], v[74:77]
	v_mfma_f32_16x16x32_bf16 v[82:85], v[158:161], v[216:219], v[82:85]
	v_mfma_f32_16x16x32_bf16 v[82:85], v[164:167], v[220:223], v[82:85]
	v_mfma_f32_16x16x32_bf16 v[118:121], v[176:179], v[192:195], v[118:121]
	v_mfma_f32_16x16x32_bf16 v[118:121], v[180:183], v[196:199], v[118:121]
	v_mfma_f32_16x16x32_bf16 v[110:113], v[184:187], v[192:195], v[110:113]
	v_mfma_f32_16x16x32_bf16 v[110:113], v[188:191], v[196:199], v[110:113]
	v_mfma_f32_16x16x32_bf16 v[94:97], v[184:187], v[200:203], v[94:97]
	v_mfma_f32_16x16x32_bf16 v[94:97], v[188:191], v[204:207], v[94:97]
	v_mfma_f32_16x16x32_bf16 v[102:105], v[176:179], v[200:203], v[102:105]
	v_mfma_f32_16x16x32_bf16 v[102:105], v[180:183], v[204:207], v[102:105]
	v_mfma_f32_16x16x32_bf16 v[86:89], v[176:179], v[208:211], v[86:89]
	v_mfma_f32_16x16x32_bf16 v[86:89], v[180:183], v[212:215], v[86:89]
	v_mfma_f32_16x16x32_bf16 v[78:81], v[184:187], v[208:211], v[78:81]
	v_mfma_f32_16x16x32_bf16 v[78:81], v[188:191], v[212:215], v[78:81]
	v_mfma_f32_16x16x32_bf16 v[66:69], v[184:187], v[216:219], v[66:69]
	v_mfma_f32_16x16x32_bf16 v[66:69], v[188:191], v[220:223], v[66:69]
	v_mfma_f32_16x16x32_bf16 v[70:73], v[176:179], v[216:219], v[70:73]
	v_mfma_f32_16x16x32_bf16 v[70:73], v[180:183], v[220:223], v[70:73]
	s_barrier
; #define PG8_STAGE(bufoff, gbase, voff) do { _Pragma("unroll") for (int _i = 0; _i < 2; ++_i) \
;         __builtin_amdgcn_global_load_lds((const unsigned*)((const char*)(gbase) + (voff)[_i]), (PG8_LAS unsigned*)(lds + (bufoff) + ldsw + _i * 8192), 16, 0, 0); } while (0)
; #define PG8_LDA(dst, b, h) do { _Pragma("unroll") for (int m = 0; m < 4; ++m) _Pragma("unroll") for (int k = 0; k < 2; ++k) dst[m][k] = *(const PG8_LAS bf16x8*)(lds + PG8_SA(b, h) + aoff + m * 2048 + k * 1024); } while (0)
; #define PG8_MMA(ai, bj, At, Bt) do { __builtin_amdgcn_s_setprio(3); _Pragma("unroll") for (int m = 0; m < 4; ++m) _Pragma("unroll") for (int n = 0; n < 2; ++n) _Pragma("unroll") for (int k = 0; k < 2; ++k) \
;         acc[ai][bj][m][n] = __builtin_amdgcn_mfma_f32_16x16x32_bf16(Bt[n][k], At[m][k], acc[ai][bj][m][n], 0, 0, 0); __builtin_amdgcn_s_setprio(0); } while (0)
; #define PG8_WAIT_V(n) asm volatile("s_waitcnt vmcnt(" #n ")" ::: "memory")
; #define PG8_WAIT_L(n) asm volatile("s_waitcnt lgkmcnt(" #n ")" ::: "memory")
; #define PG8_BAR __builtin_amdgcn_s_barrier()
; #define PG8_SCHED __builtin_amdgcn_sched_barrier(0)
; template <class Epi, class Sched, bool ALIGN_EPI = false, bool SP2 = false>
; __device__ __forceinline__ void gemm_phase(PG8_LAS unsigned char* lds, const Gemm g, const Sched& S, const Epi& E) {
;     ...
;             PG8_LDA(At, 1, 1); PG8_STAGE(PG8_SB(1, 0), b3, voffB); PG8_STAGE(PG8_SB(1, 1), b3 + hstepB, voffB); PG8_STAGE(PG8_SA(1, 0), a3, voffA);
;             PG8_WAIT_V(8); PG8_WAIT_L(0); PG8_BAR; PG8_MMA(1, 0, At, B0); PG8_MMA(1, 1, At, B1); PG8_BAR; PG8_SCHED;
;     ...
;         if constexpr (ALIGN_EPI) { if (wr == 0) PG8_BAR; }
	s_setprio 0
	s_add_i32 s28, s56, s30
	v_lshl_add_u64 v[146:147], v[146:147], 0, s[12:13]
	s_mov_b32 m0, s28
	ds_read_b128 v[192:195], v157 offset:49152
	ds_read_b128 v[196:199], v157 offset:50176
	ds_read_b128 v[200:203], v157 offset:51200
	ds_read_b128 v[204:207], v157 offset:52224
	ds_read_b128 v[208:211], v157 offset:53248
	ds_read_b128 v[212:215], v157 offset:54272
	ds_read_b128 v[216:219], v157 offset:55296
	ds_read_b128 v[220:223], v157 offset:56320
	global_load_lds_dwordx4 v[146:147], off
	s_add_i32 m0, s28, 0x2000
	s_add_u32 s26, s26, 0x100080
	v_lshl_add_u64 v[146:147], v[224:225], 0, s[12:13]
	s_addc_u32 s27, s27, 0
	s_add_i32 s28, s57, s30
	global_load_lds_dwordx4 v[146:147], off
	v_lshl_add_u64 v[146:147], s[26:27], 0, v[134:135]
	s_mov_b32 m0, s28
	s_nop 0
	global_load_lds_dwordx4 v[146:147], off
	v_lshl_add_u64 v[146:147], s[26:27], 0, v[130:131]
	s_add_i32 m0, s28, 0x2000
	s_nop 0
	global_load_lds_dwordx4 v[146:147], off
	v_lshl_add_u64 v[146:147], v[226:227], 0, s[12:13]
	s_mov_b32 m0, s39
	s_nop 0
	global_load_lds_dwordx4 v[146:147], off
	v_lshl_add_u64 v[146:147], v[228:229], 0, s[12:13]
	s_mov_b32 m0, s40
	s_nop 0
	global_load_lds_dwordx4 v[146:147], off
	s_waitcnt vmcnt(8)
	s_waitcnt lgkmcnt(0)
	v_mfma_f32_16x16x32_bf16 v[62:65], v[158:161], v[192:195], v[62:65]
	v_mfma_f32_16x16x32_bf16 v[62:65], v[164:167], v[196:199], v[62:65]
	v_mfma_f32_16x16x32_bf16 v[58:61], v[168:171], v[192:195], v[58:61]
	v_mfma_f32_16x16x32_bf16 v[58:61], v[172:175], v[196:199], v[58:61]
	s_barrier
	s_setprio 3
	v_mfma_f32_16x16x32_bf16 v[42:45], v[168:171], v[200:203], v[42:45]
	v_mfma_f32_16x16x32_bf16 v[42:45], v[172:175], v[204:207], v[42:45]
	v_mfma_f32_16x16x32_bf16 v[50:53], v[158:161], v[200:203], v[50:53]
	v_mfma_f32_16x16x32_bf16 v[50:53], v[164:167], v[204:207], v[50:53]
	v_mfma_f32_16x16x32_bf16 v[34:37], v[158:161], v[208:211], v[34:37]
	v_mfma_f32_16x16x32_bf16 v[34:37], v[164:167], v[212:215], v[34:37]
	v_mfma_f32_16x16x32_bf16 v[26:29], v[168:171], v[208:211], v[26:29]
	v_mfma_f32_16x16x32_bf16 v[26:29], v[172:175], v[212:215], v[26:29]
	v_mfma_f32_16x16x32_bf16 v[10:13], v[168:171], v[216:219], v[10:13]
	v_mfma_f32_16x16x32_bf16 v[10:13], v[172:175], v[220:223], v[10:13]
	v_mfma_f32_16x16x32_bf16 v[14:17], v[158:161], v[216:219], v[14:17]
	v_mfma_f32_16x16x32_bf16 v[14:17], v[164:167], v[220:223], v[14:17]
	v_mfma_f32_16x16x32_bf16 v[54:57], v[176:179], v[192:195], v[54:57]
	v_mfma_f32_16x16x32_bf16 v[54:57], v[180:183], v[196:199], v[54:57]
	v_mfma_f32_16x16x32_bf16 v[46:49], v[184:187], v[192:195], v[46:49]
	v_mfma_f32_16x16x32_bf16 v[46:49], v[188:191], v[196:199], v[46:49]
	v_mfma_f32_16x16x32_bf16 v[30:33], v[184:187], v[200:203], v[30:33]
	v_mfma_f32_16x16x32_bf16 v[30:33], v[188:191], v[204:207], v[30:33]
	v_mfma_f32_16x16x32_bf16 v[38:41], v[176:179], v[200:203], v[38:41]
	v_mfma_f32_16x16x32_bf16 v[38:41], v[180:183], v[204:207], v[38:41]
	v_mfma_f32_16x16x32_bf16 v[22:25], v[176:179], v[208:211], v[22:25]
	v_mfma_f32_16x16x32_bf16 v[22:25], v[180:183], v[212:215], v[22:25]
	v_mfma_f32_16x16x32_bf16 v[18:21], v[184:187], v[208:211], v[18:21]
	v_mfma_f32_16x16x32_bf16 v[18:21], v[188:191], v[212:215], v[18:21]
	v_mfma_f32_16x16x32_bf16 v[2:5], v[184:187], v[216:219], v[2:5]
	v_mfma_f32_16x16x32_bf16 v[2:5], v[188:191], v[220:223], v[2:5]
	v_mfma_f32_16x16x32_bf16 v[6:9], v[176:179], v[216:219], v[6:9]
	v_mfma_f32_16x16x32_bf16 v[6:9], v[180:183], v[220:223], v[6:9]
	s_barrier
	s_setprio 0
	s_add_i32 s55, s55, 2
	s_add_u32 s24, s24, 0x100
	s_addc_u32 s25, s25, 0
	s_add_u32 s53, s53, 0x100
	s_addc_u32 s54, s54, 0
	s_cmp_gt_u32 s55, 61
	s_cbranch_scc0 .LBB0_908
	s_and_b64 vcc, exec, s[0:1]
	s_cbranch_vccz .LBB0_911
	s_barrier

; #define PG8_STAGE(bufoff, gbase, voff) do { _Pragma("unroll") for (int _i = 0; _i < 2; ++_i) \
;         __builtin_amdgcn_global_load_lds((const unsigned*)((const char*)(gbase) + (voff)[_i]), (PG8_LAS unsigned*)(lds + (bufoff) + ldsw + _i * 8192), 16, 0, 0); } while (0)
; #define PG8_LDA(dst, b, h) do { _Pragma("unroll") for (int m = 0; m < 4; ++m) _Pragma("unroll") for (int k = 0; k < 2; ++k) dst[m][k] = *(const PG8_LAS bf16x8*)(lds + PG8_SA(b, h) + aoff + m * 2048 + k * 1024); } while (0)
; #define PG8_LDB(dst, b, h) do { _Pragma("unroll") for (int n = 0; n < 2; ++n) _Pragma("unroll") for (int k = 0; k < 2; ++k) dst[n][k] = *(const PG8_LAS bf16x8*)(lds + PG8_SB(b, h) + boff + n * 2048 + k * 1024); } while (0)
; #define PG8_MMA(ai, bj, At, Bt) do { __builtin_amdgcn_s_setprio(3); _Pragma("unroll") for (int m = 0; m < 4; ++m) _Pragma("unroll") for (int n = 0; n < 2; ++n) _Pragma("unroll") for (int k = 0; k < 2; ++k) \
;         acc[ai][bj][m][n] = __builtin_amdgcn_mfma_f32_16x16x32_bf16(Bt[n][k], At[m][k], acc[ai][bj][m][n], 0, 0, 0); __builtin_amdgcn_s_setprio(0); } while (0)
; #define PG8_WAIT_V(n) asm volatile("s_waitcnt vmcnt(" #n ")" ::: "memory")
; #define PG8_WAIT_L(n) asm volatile("s_waitcnt lgkmcnt(" #n ")" ::: "memory")
; #define PG8_BAR __builtin_amdgcn_s_barrier()
; #define PG8_SCHED __builtin_amdgcn_sched_barrier(0)
; template <class Epi, class Sched, bool ALIGN_EPI = false, bool SP2 = false>
; __device__ __forceinline__ void gemm_phase(PG8_LAS unsigned char* lds, const Gemm g, const Sched& S, const Epi& E) {
;     ...
;             const char* a2 = last ? nA : cA + (size_t)(t + 2) * kstep; const char* b2 = last ? nB : cB + (size_t)(t + 2) * kstep;
;             const char* a3 = a2 + kstep; const char* b3 = b2 + kstep;
;             if (last && has_next) S.a_ready(nxt);
;             if constexpr (Epi::MIDK) { if (t == E.midk_step(nt)) E.midk(acc, cur, wr, wc, fr, fq); }
;             if constexpr (SP2) {
;             PG8_LDB(B0, 0, 0); PG8_LDB(B1, 0, 1); PG8_SCHED; PG8_LDA(At, 0, 0); PG8_STAGE(PG8_SA(1, 1), a1 + hstepA, voffA);
;             PG8_WAIT_V(8); PG8_WAIT_L(0); PG8_BAR; PG8_MMA(0, 0, At, B0); PG8_MMA(0, 1, At, B1); PG8_BAR; PG8_SCHED;
;             PG8_LDA(At, 0, 1); PG8_STAGE(PG8_SB(0, 0), b2, voffB); PG8_STAGE(PG8_SB(0, 1), b2 + hstepB, voffB); PG8_STAGE(PG8_SA(0, 0), a2, voffA);
.LBB0_975:
	v_add_u32_e32 v144, s46, v206
	v_add_u32_e32 v160, s47, v206
	s_add_u32 s28, s2, s12
	ds_read_b128 v[132:135], v144
	ds_read_b128 v[136:139], v144 offset:1024
	ds_read_b128 v[140:143], v144 offset:2048
	ds_read_b128 v[144:147], v144 offset:3072
	ds_read_b128 v[148:151], v160
	ds_read_b128 v[152:155], v160 offset:1024
	ds_read_b128 v[156:159], v160 offset:2048
	ds_read_b128 v[160:163], v160 offset:3072
	s_addc_u32 s29, s3, s13
	s_add_u32 s28, s28, 0x21500100
	s_addc_u32 s29, s29, 0
	s_add_u32 s81, s44, s12
	s_addc_u32 s82, s45, s13
	s_cmpk_eq_i32 s12, 0x5500
	s_cselect_b32 s31, s1, s29
	s_cselect_b32 s30, s0, s28
	s_cselect_b32 s29, s11, s82
	s_cselect_b32 s28, s10, s81
	s_mov_b32 m0, s71
	v_lshl_add_u64 v[234:235], v[2:3], 0, s[12:13]
	ds_read_b128 v[164:167], v207
	ds_read_b128 v[168:171], v207 offset:1024
	ds_read_b128 v[210:213], v207 offset:2048
	ds_read_b128 v[214:217], v207 offset:3072
	ds_read_b128 v[218:221], v207 offset:4096
	ds_read_b128 v[222:225], v207 offset:5120
	ds_read_b128 v[226:229], v207 offset:6144
	ds_read_b128 v[230:233], v207 offset:7168
	global_load_lds_dwordx4 v[234:235], off
	v_lshl_add_u64 v[234:235], v[200:201], 0, s[12:13]
	s_mov_b32 m0, s72
	s_nop 0
	global_load_lds_dwordx4 v[234:235], off
	s_waitcnt vmcnt(8)
	s_waitcnt lgkmcnt(0)
	v_mfma_f32_16x16x32_bf16 v[128:131], v[132:135], v[164:167], v[128:131]
	v_mfma_f32_16x16x32_bf16 v[128:131], v[136:139], v[168:171], v[128:131]
	v_mfma_f32_16x16x32_bf16 v[124:127], v[140:143], v[164:167], v[124:127]
	v_mfma_f32_16x16x32_bf16 v[124:127], v[144:147], v[168:171], v[124:127]
	s_barrier
	s_setprio 3
	v_mfma_f32_16x16x32_bf16 v[96:99], v[140:143], v[210:213], v[96:99]
	v_mfma_f32_16x16x32_bf16 v[96:99], v[144:147], v[214:217], v[96:99]
	v_mfma_f32_16x16x32_bf16 v[100:103], v[132:135], v[210:213], v[100:103]
	v_mfma_f32_16x16x32_bf16 v[100:103], v[136:139], v[214:217], v[100:103]
	v_mfma_f32_16x16x32_bf16 v[112:115], v[132:135], v[218:221], v[112:115]
	v_mfma_f32_16x16x32_bf16 v[112:115], v[136:139], v[222:225], v[112:115]
	v_mfma_f32_16x16x32_bf16 v[108:111], v[140:143], v[218:221], v[108:111]
	v_mfma_f32_16x16x32_bf16 v[108:111], v[144:147], v[222:225], v[108:111]
	v_mfma_f32_16x16x32_bf16 v[76:79], v[140:143], v[226:229], v[76:79]
	v_mfma_f32_16x16x32_bf16 v[76:79], v[144:147], v[230:233], v[76:79]
	v_mfma_f32_16x16x32_bf16 v[80:83], v[132:135], v[226:229], v[80:83]
	v_mfma_f32_16x16x32_bf16 v[80:83], v[136:139], v[230:233], v[80:83]
	v_mfma_f32_16x16x32_bf16 v[120:123], v[148:151], v[164:167], v[120:123]
	v_mfma_f32_16x16x32_bf16 v[120:123], v[152:155], v[168:171], v[120:123]
	v_mfma_f32_16x16x32_bf16 v[116:119], v[156:159], v[164:167], v[116:119]
	v_mfma_f32_16x16x32_bf16 v[116:119], v[160:163], v[168:171], v[116:119]
	v_mfma_f32_16x16x32_bf16 v[88:91], v[156:159], v[210:213], v[88:91]
	v_mfma_f32_16x16x32_bf16 v[88:91], v[160:163], v[214:217], v[88:91]
	v_mfma_f32_16x16x32_bf16 v[92:95], v[148:151], v[210:213], v[92:95]
	v_mfma_f32_16x16x32_bf16 v[92:95], v[152:155], v[214:217], v[92:95]
	v_mfma_f32_16x16x32_bf16 v[104:107], v[148:151], v[218:221], v[104:107]
	v_mfma_f32_16x16x32_bf16 v[104:107], v[152:155], v[222:225], v[104:107]
	v_mfma_f32_16x16x32_bf16 v[84:87], v[156:159], v[218:221], v[84:87]
	v_mfma_f32_16x16x32_bf16 v[84:87], v[160:163], v[222:225], v[84:87]
	v_mfma_f32_16x16x32_bf16 v[68:71], v[156:159], v[226:229], v[68:71]
	v_mfma_f32_16x16x32_bf16 v[68:71], v[160:163], v[230:233], v[68:71]
	v_mfma_f32_16x16x32_bf16 v[72:75], v[148:151], v[226:229], v[72:75]
	v_mfma_f32_16x16x32_bf16 v[72:75], v[152:155], v[230:233], v[72:75]
	s_barrier
	s_setprio 0
	s_mov_b32 m0, s73
	v_lshl_add_u64 v[234:235], s[28:29], 0, v[174:175]
	s_add_u32 s82, s28, 0x2b0000
	ds_read_b128 v[164:167], v207 offset:16384
	ds_read_b128 v[168:171], v207 offset:17408
	ds_read_b128 v[210:213], v207 offset:18432
	ds_read_b128 v[214:217], v207 offset:19456
	ds_read_b128 v[218:221], v207 offset:20480
	ds_read_b128 v[222:225], v207 offset:21504
	ds_read_b128 v[226:229], v207 offset:22528
	ds_read_b128 v[230:233], v207 offset:23552
	global_load_lds_dwordx4 v[234:235], off
	v_lshl_add_u64 v[236:237], s[28:29], 0, v[178:179]
	s_mov_b32 m0, s74
	s_addc_u32 s83, s29, 0
	global_load_lds_dwordx4 v[236:237], off
	v_lshl_add_u64 v[238:239], s[82:83], 0, v[174:175]
	s_mov_b32 m0, s75
	v_lshl_add_u64 v[240:241], s[30:31], 0, v[176:177]
	global_load_lds_dwordx4 v[238:239], off
	v_lshl_add_u64 v[238:239], s[82:83], 0, v[178:179]
	s_mov_b32 m0, s76
	s_nop 0
	global_load_lds_dwordx4 v[238:239], off
	v_lshl_add_u64 v[238:239], s[30:31], 0, v[172:173]
	s_mov_b32 m0, s42
	s_nop 0
	global_load_lds_dwordx4 v[238:239], off
	s_mov_b32 m0, s54
	s_nop 0
	global_load_lds_dwordx4 v[240:241], off
	s_waitcnt vmcnt(8)
	s_waitcnt lgkmcnt(0)
	v_mfma_f32_16x16x32_bf16 v[64:67], v[132:135], v[164:167], v[64:67]
	v_mfma_f32_16x16x32_bf16 v[64:67], v[136:139], v[168:171], v[64:67]
	v_mfma_f32_16x16x32_bf16 v[60:63], v[140:143], v[164:167], v[60:63]
	v_mfma_f32_16x16x32_bf16 v[60:63], v[144:147], v[168:171], v[60:63]
	s_barrier
; #define PG8_STAGE(bufoff, gbase, voff) do { _Pragma("unroll") for (int _i = 0; _i < 2; ++_i) \
;         __builtin_amdgcn_global_load_lds((const unsigned*)((const char*)(gbase) + (voff)[_i]), (PG8_LAS unsigned*)(lds + (bufoff) + ldsw + _i * 8192), 16, 0, 0); } while (0)
; #define PG8_LDA(dst, b, h) do { _Pragma("unroll") for (int m = 0; m < 4; ++m) _Pragma("unroll") for (int k = 0; k < 2; ++k) dst[m][k] = *(const PG8_LAS bf16x8*)(lds + PG8_SA(b, h) + aoff + m * 2048 + k * 1024); } while (0)
; #define PG8_LDB(dst, b, h) do { _Pragma("unroll") for (int n = 0; n < 2; ++n) _Pragma("unroll") for (int k = 0; k < 2; ++k) dst[n][k] = *(const PG8_LAS bf16x8*)(lds + PG8_SB(b, h) + boff + n * 2048 + k * 1024); } while (0)
; #define PG8_MMA(ai, bj, At, Bt) do { __builtin_amdgcn_s_setprio(3); _Pragma("unroll") for (int m = 0; m < 4; ++m) _Pragma("unroll") for (int n = 0; n < 2; ++n) _Pragma("unroll") for (int k = 0; k < 2; ++k) \
;         acc[ai][bj][m][n] = __builtin_amdgcn_mfma_f32_16x16x32_bf16(Bt[n][k], At[m][k], acc[ai][bj][m][n], 0, 0, 0); __builtin_amdgcn_s_setprio(0); } while (0)
; #define PG8_WAIT_V(n) asm volatile("s_waitcnt vmcnt(" #n ")" ::: "memory")
; #define PG8_WAIT_L(n) asm volatile("s_waitcnt lgkmcnt(" #n ")" ::: "memory")
; #define PG8_BAR __builtin_amdgcn_s_barrier()
; #define PG8_SCHED __builtin_amdgcn_sched_barrier(0)
; template <class Epi, class Sched, bool ALIGN_EPI = false, bool SP2 = false>
; __device__ __forceinline__ void gemm_phase(PG8_LAS unsigned char* lds, const Gemm g, const Sched& S, const Epi& E) {
;     ...
;             PG8_WAIT_V(8); PG8_WAIT_L(0); PG8_BAR; PG8_MMA(1, 0, At, B0); PG8_MMA(1, 1, At, B1); PG8_BAR; PG8_SCHED;
;             PG8_LDB(B0, 1, 0); PG8_LDB(B1, 1, 1); PG8_SCHED; PG8_LDA(At, 1, 0); PG8_STAGE(PG8_SA(0, 1), a2 + hstepA, voffA);
;             PG8_WAIT_V(8); PG8_WAIT_L(0); PG8_BAR; PG8_MMA(0, 0, At, B0); PG8_MMA(0, 1, At, B1); PG8_BAR; PG8_SCHED;
	s_setprio 3
	v_mfma_f32_16x16x32_bf16 v[44:47], v[140:143], v[210:213], v[44:47]
	v_mfma_f32_16x16x32_bf16 v[44:47], v[144:147], v[214:217], v[44:47]
	v_mfma_f32_16x16x32_bf16 v[48:51], v[132:135], v[210:213], v[48:51]
	v_mfma_f32_16x16x32_bf16 v[48:51], v[136:139], v[214:217], v[48:51]
	v_mfma_f32_16x16x32_bf16 v[32:35], v[132:135], v[218:221], v[32:35]
	v_mfma_f32_16x16x32_bf16 v[32:35], v[136:139], v[222:225], v[32:35]
	v_mfma_f32_16x16x32_bf16 v[28:31], v[140:143], v[218:221], v[28:31]
	v_mfma_f32_16x16x32_bf16 v[28:31], v[144:147], v[222:225], v[28:31]
	v_mfma_f32_16x16x32_bf16 v[12:15], v[140:143], v[226:229], v[12:15]
	v_mfma_f32_16x16x32_bf16 v[12:15], v[144:147], v[230:233], v[12:15]
	v_mfma_f32_16x16x32_bf16 v[16:19], v[132:135], v[226:229], v[16:19]
	v_mfma_f32_16x16x32_bf16 v[16:19], v[136:139], v[230:233], v[16:19]
	v_mfma_f32_16x16x32_bf16 v[56:59], v[148:151], v[164:167], v[56:59]
	v_mfma_f32_16x16x32_bf16 v[56:59], v[152:155], v[168:171], v[56:59]
	v_mfma_f32_16x16x32_bf16 v[52:55], v[156:159], v[164:167], v[52:55]
	v_mfma_f32_16x16x32_bf16 v[52:55], v[160:163], v[168:171], v[52:55]
	v_mfma_f32_16x16x32_bf16 v[36:39], v[156:159], v[210:213], v[36:39]
	v_mfma_f32_16x16x32_bf16 v[36:39], v[160:163], v[214:217], v[36:39]
	v_mfma_f32_16x16x32_bf16 v[40:43], v[148:151], v[210:213], v[40:43]
	v_mfma_f32_16x16x32_bf16 v[40:43], v[152:155], v[214:217], v[40:43]
	v_mfma_f32_16x16x32_bf16 v[24:27], v[148:151], v[218:221], v[24:27]
	v_mfma_f32_16x16x32_bf16 v[24:27], v[152:155], v[222:225], v[24:27]
	v_mfma_f32_16x16x32_bf16 v[20:23], v[156:159], v[218:221], v[20:23]
	v_mfma_f32_16x16x32_bf16 v[20:23], v[160:163], v[222:225], v[20:23]
	v_mfma_f32_16x16x32_bf16 v[4:7], v[156:159], v[226:229], v[4:7]
	v_mfma_f32_16x16x32_bf16 v[4:7], v[160:163], v[230:233], v[4:7]
	v_mfma_f32_16x16x32_bf16 v[8:11], v[148:151], v[226:229], v[8:11]
	v_mfma_f32_16x16x32_bf16 v[8:11], v[152:155], v[230:233], v[8:11]
	s_barrier
	s_setprio 0
	v_add_u32_e32 v144, s52, v206
	v_add_u32_e32 v160, s53, v206
	ds_read_b128 v[132:135], v144
	ds_read_b128 v[136:139], v144 offset:1024
	ds_read_b128 v[140:143], v144 offset:2048
	ds_read_b128 v[144:147], v144 offset:3072
	ds_read_b128 v[148:151], v160
	ds_read_b128 v[152:155], v160 offset:1024
	ds_read_b128 v[156:159], v160 offset:2048
	ds_read_b128 v[160:163], v160 offset:3072
	s_add_u32 s30, s30, 0x2b0000
	s_addc_u32 s31, s31, 0
	s_mov_b32 m0, s55
	v_lshl_add_u64 v[242:243], s[30:31], 0, v[172:173]
	ds_read_b128 v[164:167], v207 offset:32768
	ds_read_b128 v[168:171], v207 offset:33792
	ds_read_b128 v[210:213], v207 offset:34816
	ds_read_b128 v[214:217], v207 offset:35840
	ds_read_b128 v[218:221], v207 offset:36864
	ds_read_b128 v[222:225], v207 offset:37888
	ds_read_b128 v[226:229], v207 offset:38912
	ds_read_b128 v[230:233], v207 offset:39936
	global_load_lds_dwordx4 v[242:243], off
	v_lshl_add_u64 v[242:243], s[30:31], 0, v[176:177]
	s_mov_b32 m0, s56
	s_nop 0
	global_load_lds_dwordx4 v[242:243], off
	s_waitcnt vmcnt(8)
	s_waitcnt lgkmcnt(0)
	v_mfma_f32_16x16x32_bf16 v[128:131], v[132:135], v[164:167], v[128:131]
	v_mfma_f32_16x16x32_bf16 v[128:131], v[136:139], v[168:171], v[128:131]
	v_mfma_f32_16x16x32_bf16 v[124:127], v[140:143], v[164:167], v[124:127]
	v_mfma_f32_16x16x32_bf16 v[124:127], v[144:147], v[168:171], v[124:127]
	s_barrier
	s_setprio 3
	v_mfma_f32_16x16x32_bf16 v[96:99], v[140:143], v[210:213], v[96:99]
	v_mfma_f32_16x16x32_bf16 v[96:99], v[144:147], v[214:217], v[96:99]
	v_mfma_f32_16x16x32_bf16 v[100:103], v[132:135], v[210:213], v[100:103]
	v_mfma_f32_16x16x32_bf16 v[100:103], v[136:139], v[214:217], v[100:103]
	v_mfma_f32_16x16x32_bf16 v[112:115], v[132:135], v[218:221], v[112:115]
	v_mfma_f32_16x16x32_bf16 v[112:115], v[136:139], v[222:225], v[112:115]
	v_mfma_f32_16x16x32_bf16 v[108:111], v[140:143], v[218:221], v[108:111]
	v_mfma_f32_16x16x32_bf16 v[108:111], v[144:147], v[222:225], v[108:111]
	v_mfma_f32_16x16x32_bf16 v[76:79], v[140:143], v[226:229], v[76:79]
	v_mfma_f32_16x16x32_bf16 v[76:79], v[144:147], v[230:233], v[76:79]
	v_mfma_f32_16x16x32_bf16 v[80:83], v[132:135], v[226:229], v[80:83]
	v_mfma_f32_16x16x32_bf16 v[80:83], v[136:139], v[230:233], v[80:83]
	v_mfma_f32_16x16x32_bf16 v[120:123], v[148:151], v[164:167], v[120:123]
	v_mfma_f32_16x16x32_bf16 v[120:123], v[152:155], v[168:171], v[120:123]
	v_mfma_f32_16x16x32_bf16 v[116:119], v[156:159], v[164:167], v[116:119]
	v_mfma_f32_16x16x32_bf16 v[116:119], v[160:163], v[168:171], v[116:119]
	v_mfma_f32_16x16x32_bf16 v[88:91], v[156:159], v[210:213], v[88:91]
	v_mfma_f32_16x16x32_bf16 v[88:91], v[160:163], v[214:217], v[88:91]
	v_mfma_f32_16x16x32_bf16 v[92:95], v[148:151], v[210:213], v[92:95]
	v_mfma_f32_16x16x32_bf16 v[92:95], v[152:155], v[214:217], v[92:95]
	v_mfma_f32_16x16x32_bf16 v[104:107], v[148:151], v[218:221], v[104:107]
	v_mfma_f32_16x16x32_bf16 v[104:107], v[152:155], v[222:225], v[104:107]
	v_mfma_f32_16x16x32_bf16 v[84:87], v[156:159], v[218:221], v[84:87]
	v_mfma_f32_16x16x32_bf16 v[84:87], v[160:163], v[222:225], v[84:87]
	v_mfma_f32_16x16x32_bf16 v[68:71], v[156:159], v[226:229], v[68:71]
	v_mfma_f32_16x16x32_bf16 v[68:71], v[160:163], v[230:233], v[68:71]
	v_mfma_f32_16x16x32_bf16 v[72:75], v[148:151], v[226:229], v[72:75]
	v_mfma_f32_16x16x32_bf16 v[72:75], v[152:155], v[230:233], v[72:75]
	s_barrier
; #define PG8_STAGE(bufoff, gbase, voff) do { _Pragma("unroll") for (int _i = 0; _i < 2; ++_i) \
;         __builtin_amdgcn_global_load_lds((const unsigned*)((const char*)(gbase) + (voff)[_i]), (PG8_LAS unsigned*)(lds + (bufoff) + ldsw + _i * 8192), 16, 0, 0); } while (0)
; #define PG8_LDA(dst, b, h) do { _Pragma("unroll") for (int m = 0; m < 4; ++m) _Pragma("unroll") for (int k = 0; k < 2; ++k) dst[m][k] = *(const PG8_LAS bf16x8*)(lds + PG8_SA(b, h) + aoff + m * 2048 + k * 1024); } while (0)
; #define PG8_MMA(ai, bj, At, Bt) do { __builtin_amdgcn_s_setprio(3); _Pragma("unroll") for (int m = 0; m < 4; ++m) _Pragma("unroll") for (int n = 0; n < 2; ++n) _Pragma("unroll") for (int k = 0; k < 2; ++k) \
;         acc[ai][bj][m][n] = __builtin_amdgcn_mfma_f32_16x16x32_bf16(Bt[n][k], At[m][k], acc[ai][bj][m][n], 0, 0, 0); __builtin_amdgcn_s_setprio(0); } while (0)
; #define PG8_WAIT_V(n) asm volatile("s_waitcnt vmcnt(" #n ")" ::: "memory")
; #define PG8_WAIT_L(n) asm volatile("s_waitcnt lgkmcnt(" #n ")" ::: "memory")
; #define PG8_BAR __builtin_amdgcn_s_barrier()
; #define PG8_SCHED __builtin_amdgcn_sched_barrier(0)
; template <class Epi, class Sched, bool ALIGN_EPI = false, bool SP2 = false>
; __device__ __forceinline__ void gemm_phase(PG8_LAS unsigned char* lds, const Gemm g, const Sched& S, const Epi& E) {
;     ...
;             PG8_LDA(At, 1, 1); PG8_STAGE(PG8_SB(1, 0), b3, voffB); PG8_STAGE(PG8_SB(1, 1), b3 + hstepB, voffB); PG8_STAGE(PG8_SA(1, 0), a3, voffA);
;             PG8_WAIT_V(8); PG8_WAIT_L(0); PG8_BAR; PG8_MMA(1, 0, At, B0); PG8_MMA(1, 1, At, B1); PG8_BAR; PG8_SCHED;
	s_setprio 0
	s_mov_b32 m0, s77
	v_lshl_add_u64 v[234:235], v[234:235], 0, s[4:5]
	s_add_u32 s28, s28, 0x2b0080
	ds_read_b128 v[164:167], v207 offset:49152
	ds_read_b128 v[168:171], v207 offset:50176
	ds_read_b128 v[210:213], v207 offset:51200
	ds_read_b128 v[214:217], v207 offset:52224
	ds_read_b128 v[218:221], v207 offset:53248
	ds_read_b128 v[222:225], v207 offset:54272
	ds_read_b128 v[226:229], v207 offset:55296
	ds_read_b128 v[230:233], v207 offset:56320
	global_load_lds_dwordx4 v[234:235], off
	v_lshl_add_u64 v[234:235], v[236:237], 0, s[4:5]
	s_mov_b32 m0, s78
	s_addc_u32 s29, s29, 0
	global_load_lds_dwordx4 v[234:235], off
	v_lshl_add_u64 v[234:235], s[28:29], 0, v[174:175]
	s_mov_b32 m0, s79
	s_nop 0
	global_load_lds_dwordx4 v[234:235], off
	v_lshl_add_u64 v[234:235], s[28:29], 0, v[178:179]
	s_mov_b32 m0, s80
	s_nop 0
	global_load_lds_dwordx4 v[234:235], off
	v_lshl_add_u64 v[234:235], v[238:239], 0, s[4:5]
	s_mov_b32 m0, s57
	s_nop 0
	global_load_lds_dwordx4 v[234:235], off
	v_lshl_add_u64 v[234:235], v[240:241], 0, s[4:5]
	s_mov_b32 m0, s58
	s_nop 0
	global_load_lds_dwordx4 v[234:235], off
	s_waitcnt vmcnt(8)
	s_waitcnt lgkmcnt(0)
	v_mfma_f32_16x16x32_bf16 v[64:67], v[132:135], v[164:167], v[64:67]
	v_mfma_f32_16x16x32_bf16 v[64:67], v[136:139], v[168:171], v[64:67]
	v_mfma_f32_16x16x32_bf16 v[60:63], v[140:143], v[164:167], v[60:63]
	v_mfma_f32_16x16x32_bf16 v[60:63], v[144:147], v[168:171], v[60:63]
	s_barrier
	s_setprio 3
	v_mfma_f32_16x16x32_bf16 v[44:47], v[140:143], v[210:213], v[44:47]
	v_mfma_f32_16x16x32_bf16 v[44:47], v[144:147], v[214:217], v[44:47]
	v_mfma_f32_16x16x32_bf16 v[48:51], v[132:135], v[210:213], v[48:51]
	v_mfma_f32_16x16x32_bf16 v[48:51], v[136:139], v[214:217], v[48:51]
	v_mfma_f32_16x16x32_bf16 v[32:35], v[132:135], v[218:221], v[32:35]
	v_mfma_f32_16x16x32_bf16 v[32:35], v[136:139], v[222:225], v[32:35]
	v_mfma_f32_16x16x32_bf16 v[28:31], v[140:143], v[218:221], v[28:31]
	v_mfma_f32_16x16x32_bf16 v[28:31], v[144:147], v[222:225], v[28:31]
	v_mfma_f32_16x16x32_bf16 v[12:15], v[140:143], v[226:229], v[12:15]
	v_mfma_f32_16x16x32_bf16 v[12:15], v[144:147], v[230:233], v[12:15]
	v_mfma_f32_16x16x32_bf16 v[16:19], v[132:135], v[226:229], v[16:19]
	v_mfma_f32_16x16x32_bf16 v[16:19], v[136:139], v[230:233], v[16:19]
	v_mfma_f32_16x16x32_bf16 v[56:59], v[148:151], v[164:167], v[56:59]
	v_mfma_f32_16x16x32_bf16 v[56:59], v[152:155], v[168:171], v[56:59]
	v_mfma_f32_16x16x32_bf16 v[52:55], v[156:159], v[164:167], v[52:55]
	v_mfma_f32_16x16x32_bf16 v[52:55], v[160:163], v[168:171], v[52:55]
	v_mfma_f32_16x16x32_bf16 v[36:39], v[156:159], v[210:213], v[36:39]
	v_mfma_f32_16x16x32_bf16 v[36:39], v[160:163], v[214:217], v[36:39]
	v_mfma_f32_16x16x32_bf16 v[40:43], v[148:151], v[210:213], v[40:43]
	v_mfma_f32_16x16x32_bf16 v[40:43], v[152:155], v[214:217], v[40:43]
	v_mfma_f32_16x16x32_bf16 v[24:27], v[148:151], v[218:221], v[24:27]
	v_mfma_f32_16x16x32_bf16 v[24:27], v[152:155], v[222:225], v[24:27]
	v_mfma_f32_16x16x32_bf16 v[20:23], v[156:159], v[218:221], v[20:23]
	v_mfma_f32_16x16x32_bf16 v[20:23], v[160:163], v[222:225], v[20:23]
	v_mfma_f32_16x16x32_bf16 v[4:7], v[156:159], v[226:229], v[4:7]
	v_mfma_f32_16x16x32_bf16 v[4:7], v[160:163], v[230:233], v[4:7]
	v_mfma_f32_16x16x32_bf16 v[8:11], v[148:151], v[226:229], v[8:11]
	v_mfma_f32_16x16x32_bf16 v[8:11], v[152:155], v[230:233], v[8:11]
	s_barrier
	s_setprio 0
	s_add_i32 s61, s61, 2
	s_add_u32 s12, s12, 0x100
	s_addc_u32 s13, s13, 0
	s_cmpk_gt_u32 s61, 0xa9
	s_cbranch_scc1 .LBB0_978

; #define PG8_STAGE(bufoff, gbase, voff) do { _Pragma("unroll") for (int _i = 0; _i < 2; ++_i) \
;         __builtin_amdgcn_global_load_lds((const unsigned*)((const char*)(gbase) + (voff)[_i]), (PG8_LAS unsigned*)(lds + (bufoff) + ldsw + _i * 8192), 16, 0, 0); } while (0)
; #define PG8_LDA(dst, b, h) do { _Pragma("unroll") for (int m = 0; m < 4; ++m) _Pragma("unroll") for (int k = 0; k < 2; ++k) dst[m][k] = *(const PG8_LAS bf16x8*)(lds + PG8_SA(b, h) + aoff + m * 2048 + k * 1024); } while (0)
; #define PG8_LDB(dst, b, h) do { _Pragma("unroll") for (int n = 0; n < 2; ++n) _Pragma("unroll") for (int k = 0; k < 2; ++k) dst[n][k] = *(const PG8_LAS bf16x8*)(lds + PG8_SB(b, h) + boff + n * 2048 + k * 1024); } while (0)
; #define PG8_MMA(ai, bj, At, Bt) do { __builtin_amdgcn_s_setprio(3); _Pragma("unroll") for (int m = 0; m < 4; ++m) _Pragma("unroll") for (int n = 0; n < 2; ++n) _Pragma("unroll") for (int k = 0; k < 2; ++k) \
;         acc[ai][bj][m][n] = __builtin_amdgcn_mfma_f32_16x16x32_bf16(Bt[n][k], At[m][k], acc[ai][bj][m][n], 0, 0, 0); __builtin_amdgcn_s_setprio(0); } while (0)
; #define PG8_WAIT_V(n) asm volatile("s_waitcnt vmcnt(" #n ")" ::: "memory")
; #define PG8_WAIT_L(n) asm volatile("s_waitcnt lgkmcnt(" #n ")" ::: "memory")
; #define PG8_BAR __builtin_amdgcn_s_barrier()
; #define PG8_SCHED __builtin_amdgcn_sched_barrier(0)
; template <class Epi, class Sched, bool ALIGN_EPI = false, bool SP2 = false>
; __device__ __forceinline__ void gemm_phase(PG8_LAS unsigned char* lds, const Gemm g, const Sched& S, const Epi& E) {
;     ...
;             const char* a2 = last ? nA : cA + (size_t)(t + 2) * kstep; const char* b2 = last ? nB : cB + (size_t)(t + 2) * kstep;
;             const char* a3 = a2 + kstep; const char* b3 = b2 + kstep;
;             if (last && has_next) S.a_ready(nxt);
;             if constexpr (Epi::MIDK) { if (t == E.midk_step(nt)) E.midk(acc, cur, wr, wc, fr, fq); }
;             if constexpr (SP2) {
;             PG8_LDB(B0, 0, 0); PG8_LDB(B1, 0, 1); PG8_SCHED; PG8_LDA(At, 0, 0); PG8_STAGE(PG8_SA(1, 1), a1 + hstepA, voffA);
;             PG8_WAIT_V(8); PG8_WAIT_L(0); PG8_BAR; PG8_MMA(0, 0, At, B0); PG8_MMA(0, 1, At, B1); PG8_BAR; PG8_SCHED;
;             PG8_LDA(At, 0, 1); PG8_STAGE(PG8_SB(0, 0), b2, voffB); PG8_STAGE(PG8_SB(0, 1), b2 + hstepB, voffB); PG8_STAGE(PG8_SA(0, 0), a2, voffA);
.LBB0_1018:
	v_add_u32_e32 v142, s46, v189
	v_add_u32_e32 v158, s47, v189
	s_add_u32 s40, s20, s22
	ds_read_b128 v[130:133], v142
	ds_read_b128 v[134:137], v142 offset:1024
	ds_read_b128 v[138:141], v142 offset:2048
	ds_read_b128 v[142:145], v142 offset:3072
	ds_read_b128 v[146:149], v158
	ds_read_b128 v[150:153], v158 offset:1024
	ds_read_b128 v[154:157], v158 offset:2048
	ds_read_b128 v[158:161], v158 offset:3072
	s_addc_u32 s41, s21, s23
	s_add_u32 s40, s40, 0x21500100
	s_addc_u32 s41, s41, 0
	s_add_u32 s87, s44, s22
	s_addc_u32 s88, s45, s23
	s_cmpk_eq_i32 s22, 0x5500
	s_cselect_b32 s43, s17, s41
	s_cselect_b32 s42, s16, s40
	s_cselect_b32 s41, s11, s88
	s_cselect_b32 s40, s10, s87
	s_mov_b32 m0, s77
	v_lshl_add_u64 v[186:187], v[0:1], 0, s[22:23]
	ds_read_b128 v[162:165], v180
	ds_read_b128 v[166:169], v180 offset:1024
	ds_read_b128 v[182:185], v180 offset:2048
	ds_read_b128 v[190:193], v180 offset:3072
	ds_read_b128 v[194:197], v180 offset:4096
	ds_read_b128 v[208:211], v180 offset:5120
	ds_read_b128 v[212:215], v180 offset:6144
	ds_read_b128 v[216:219], v180 offset:7168
	global_load_lds_dwordx4 v[186:187], off
	v_lshl_add_u64 v[186:187], v[170:171], 0, s[22:23]
	s_mov_b32 m0, s78
	s_nop 0
	global_load_lds_dwordx4 v[186:187], off
	s_waitcnt vmcnt(8)
	s_waitcnt lgkmcnt(0)
	v_mfma_f32_16x16x32_bf16 v[126:129], v[130:133], v[162:165], v[126:129]
	v_mfma_f32_16x16x32_bf16 v[126:129], v[134:137], v[166:169], v[126:129]
	v_mfma_f32_16x16x32_bf16 v[122:125], v[138:141], v[162:165], v[122:125]
	v_mfma_f32_16x16x32_bf16 v[122:125], v[142:145], v[166:169], v[122:125]
	s_barrier
	s_setprio 3
	v_mfma_f32_16x16x32_bf16 v[94:97], v[138:141], v[182:185], v[94:97]
	v_mfma_f32_16x16x32_bf16 v[94:97], v[142:145], v[190:193], v[94:97]
	v_mfma_f32_16x16x32_bf16 v[98:101], v[130:133], v[182:185], v[98:101]
	v_mfma_f32_16x16x32_bf16 v[98:101], v[134:137], v[190:193], v[98:101]
	v_mfma_f32_16x16x32_bf16 v[110:113], v[130:133], v[194:197], v[110:113]
	v_mfma_f32_16x16x32_bf16 v[110:113], v[134:137], v[208:211], v[110:113]
	v_mfma_f32_16x16x32_bf16 v[106:109], v[138:141], v[194:197], v[106:109]
	v_mfma_f32_16x16x32_bf16 v[106:109], v[142:145], v[208:211], v[106:109]
	v_mfma_f32_16x16x32_bf16 v[74:77], v[138:141], v[212:215], v[74:77]
	v_mfma_f32_16x16x32_bf16 v[74:77], v[142:145], v[216:219], v[74:77]
	v_mfma_f32_16x16x32_bf16 v[78:81], v[130:133], v[212:215], v[78:81]
	v_mfma_f32_16x16x32_bf16 v[78:81], v[134:137], v[216:219], v[78:81]
	v_mfma_f32_16x16x32_bf16 v[118:121], v[146:149], v[162:165], v[118:121]
	v_mfma_f32_16x16x32_bf16 v[118:121], v[150:153], v[166:169], v[118:121]
	v_mfma_f32_16x16x32_bf16 v[114:117], v[154:157], v[162:165], v[114:117]
	v_mfma_f32_16x16x32_bf16 v[114:117], v[158:161], v[166:169], v[114:117]
	v_mfma_f32_16x16x32_bf16 v[86:89], v[154:157], v[182:185], v[86:89]
	v_mfma_f32_16x16x32_bf16 v[86:89], v[158:161], v[190:193], v[86:89]
	v_mfma_f32_16x16x32_bf16 v[90:93], v[146:149], v[182:185], v[90:93]
	v_mfma_f32_16x16x32_bf16 v[90:93], v[150:153], v[190:193], v[90:93]
	v_mfma_f32_16x16x32_bf16 v[102:105], v[146:149], v[194:197], v[102:105]
	v_mfma_f32_16x16x32_bf16 v[102:105], v[150:153], v[208:211], v[102:105]
	v_mfma_f32_16x16x32_bf16 v[82:85], v[154:157], v[194:197], v[82:85]
	v_mfma_f32_16x16x32_bf16 v[82:85], v[158:161], v[208:211], v[82:85]
	v_mfma_f32_16x16x32_bf16 v[66:69], v[154:157], v[212:215], v[66:69]
	v_mfma_f32_16x16x32_bf16 v[66:69], v[158:161], v[216:219], v[66:69]
	v_mfma_f32_16x16x32_bf16 v[70:73], v[146:149], v[212:215], v[70:73]
	v_mfma_f32_16x16x32_bf16 v[70:73], v[150:153], v[216:219], v[70:73]
	s_barrier
	s_setprio 0
	s_mov_b32 m0, s79
	v_lshl_add_u64 v[186:187], s[40:41], 0, v[174:175]
	s_add_u32 s88, s40, 0x2b0000
	ds_read_b128 v[162:165], v180 offset:16384
	ds_read_b128 v[166:169], v180 offset:17408
	ds_read_b128 v[182:185], v180 offset:18432
	ds_read_b128 v[190:193], v180 offset:19456
	ds_read_b128 v[194:197], v180 offset:20480
	ds_read_b128 v[208:211], v180 offset:21504
	ds_read_b128 v[212:215], v180 offset:22528
	ds_read_b128 v[216:219], v180 offset:23552
	global_load_lds_dwordx4 v[186:187], off
	v_lshl_add_u64 v[198:199], s[40:41], 0, v[178:179]
	s_mov_b32 m0, s80
	s_addc_u32 s89, s41, 0
	global_load_lds_dwordx4 v[198:199], off
	v_lshl_add_u64 v[204:205], s[88:89], 0, v[174:175]
	s_mov_b32 m0, s81
	v_lshl_add_u64 v[220:221], s[42:43], 0, v[176:177]
	global_load_lds_dwordx4 v[204:205], off
	v_lshl_add_u64 v[204:205], s[88:89], 0, v[178:179]
	s_mov_b32 m0, s82
	s_nop 0
	global_load_lds_dwordx4 v[204:205], off
	v_lshl_add_u64 v[204:205], s[42:43], 0, v[172:173]
	s_mov_b32 m0, s58
	s_nop 0
	global_load_lds_dwordx4 v[204:205], off
	s_mov_b32 m0, s60
	s_nop 0
	global_load_lds_dwordx4 v[220:221], off
	s_waitcnt vmcnt(8)
	s_waitcnt lgkmcnt(0)
	v_mfma_f32_16x16x32_bf16 v[62:65], v[130:133], v[162:165], v[62:65]
	v_mfma_f32_16x16x32_bf16 v[62:65], v[134:137], v[166:169], v[62:65]
	v_mfma_f32_16x16x32_bf16 v[58:61], v[138:141], v[162:165], v[58:61]
	v_mfma_f32_16x16x32_bf16 v[58:61], v[142:145], v[166:169], v[58:61]
	s_barrier
; #define PG8_STAGE(bufoff, gbase, voff) do { _Pragma("unroll") for (int _i = 0; _i < 2; ++_i) \
;         __builtin_amdgcn_global_load_lds((const unsigned*)((const char*)(gbase) + (voff)[_i]), (PG8_LAS unsigned*)(lds + (bufoff) + ldsw + _i * 8192), 16, 0, 0); } while (0)
; #define PG8_LDA(dst, b, h) do { _Pragma("unroll") for (int m = 0; m < 4; ++m) _Pragma("unroll") for (int k = 0; k < 2; ++k) dst[m][k] = *(const PG8_LAS bf16x8*)(lds + PG8_SA(b, h) + aoff + m * 2048 + k * 1024); } while (0)
; #define PG8_LDB(dst, b, h) do { _Pragma("unroll") for (int n = 0; n < 2; ++n) _Pragma("unroll") for (int k = 0; k < 2; ++k) dst[n][k] = *(const PG8_LAS bf16x8*)(lds + PG8_SB(b, h) + boff + n * 2048 + k * 1024); } while (0)
; #define PG8_MMA(ai, bj, At, Bt) do { __builtin_amdgcn_s_setprio(3); _Pragma("unroll") for (int m = 0; m < 4; ++m) _Pragma("unroll") for (int n = 0; n < 2; ++n) _Pragma("unroll") for (int k = 0; k < 2; ++k) \
;         acc[ai][bj][m][n] = __builtin_amdgcn_mfma_f32_16x16x32_bf16(Bt[n][k], At[m][k], acc[ai][bj][m][n], 0, 0, 0); __builtin_amdgcn_s_setprio(0); } while (0)
; #define PG8_WAIT_V(n) asm volatile("s_waitcnt vmcnt(" #n ")" ::: "memory")
; #define PG8_WAIT_L(n) asm volatile("s_waitcnt lgkmcnt(" #n ")" ::: "memory")
; #define PG8_BAR __builtin_amdgcn_s_barrier()
; #define PG8_SCHED __builtin_amdgcn_sched_barrier(0)
; template <class Epi, class Sched, bool ALIGN_EPI = false, bool SP2 = false>
; __device__ __forceinline__ void gemm_phase(PG8_LAS unsigned char* lds, const Gemm g, const Sched& S, const Epi& E) {
;     ...
;             PG8_WAIT_V(8); PG8_WAIT_L(0); PG8_BAR; PG8_MMA(1, 0, At, B0); PG8_MMA(1, 1, At, B1); PG8_BAR; PG8_SCHED;
;             PG8_LDB(B0, 1, 0); PG8_LDB(B1, 1, 1); PG8_SCHED; PG8_LDA(At, 1, 0); PG8_STAGE(PG8_SA(0, 1), a2 + hstepA, voffA);
;             PG8_WAIT_V(8); PG8_WAIT_L(0); PG8_BAR; PG8_MMA(0, 0, At, B0); PG8_MMA(0, 1, At, B1); PG8_BAR; PG8_SCHED;
	s_setprio 3
	v_mfma_f32_16x16x32_bf16 v[42:45], v[138:141], v[182:185], v[42:45]
	v_mfma_f32_16x16x32_bf16 v[42:45], v[142:145], v[190:193], v[42:45]
	v_mfma_f32_16x16x32_bf16 v[46:49], v[130:133], v[182:185], v[46:49]
	v_mfma_f32_16x16x32_bf16 v[46:49], v[134:137], v[190:193], v[46:49]
	v_mfma_f32_16x16x32_bf16 v[30:33], v[130:133], v[194:197], v[30:33]
	v_mfma_f32_16x16x32_bf16 v[30:33], v[134:137], v[208:211], v[30:33]
	v_mfma_f32_16x16x32_bf16 v[26:29], v[138:141], v[194:197], v[26:29]
	v_mfma_f32_16x16x32_bf16 v[26:29], v[142:145], v[208:211], v[26:29]
	v_mfma_f32_16x16x32_bf16 v[10:13], v[138:141], v[212:215], v[10:13]
	v_mfma_f32_16x16x32_bf16 v[10:13], v[142:145], v[216:219], v[10:13]
	v_mfma_f32_16x16x32_bf16 v[14:17], v[130:133], v[212:215], v[14:17]
	v_mfma_f32_16x16x32_bf16 v[14:17], v[134:137], v[216:219], v[14:17]
	v_mfma_f32_16x16x32_bf16 v[54:57], v[146:149], v[162:165], v[54:57]
	v_mfma_f32_16x16x32_bf16 v[54:57], v[150:153], v[166:169], v[54:57]
	v_mfma_f32_16x16x32_bf16 v[50:53], v[154:157], v[162:165], v[50:53]
	v_mfma_f32_16x16x32_bf16 v[50:53], v[158:161], v[166:169], v[50:53]
	v_mfma_f32_16x16x32_bf16 v[34:37], v[154:157], v[182:185], v[34:37]
	v_mfma_f32_16x16x32_bf16 v[34:37], v[158:161], v[190:193], v[34:37]
	v_mfma_f32_16x16x32_bf16 v[38:41], v[146:149], v[182:185], v[38:41]
	v_mfma_f32_16x16x32_bf16 v[38:41], v[150:153], v[190:193], v[38:41]
	v_mfma_f32_16x16x32_bf16 v[22:25], v[146:149], v[194:197], v[22:25]
	v_mfma_f32_16x16x32_bf16 v[22:25], v[150:153], v[208:211], v[22:25]
	v_mfma_f32_16x16x32_bf16 v[18:21], v[154:157], v[194:197], v[18:21]
	v_mfma_f32_16x16x32_bf16 v[18:21], v[158:161], v[208:211], v[18:21]
	v_mfma_f32_16x16x32_bf16 v[2:5], v[154:157], v[212:215], v[2:5]
	v_mfma_f32_16x16x32_bf16 v[2:5], v[158:161], v[216:219], v[2:5]
	v_mfma_f32_16x16x32_bf16 v[6:9], v[146:149], v[212:215], v[6:9]
	v_mfma_f32_16x16x32_bf16 v[6:9], v[150:153], v[216:219], v[6:9]
	s_barrier
	s_setprio 0
	v_add_u32_e32 v142, s52, v189
	v_add_u32_e32 v158, s53, v189
	ds_read_b128 v[130:133], v142
	ds_read_b128 v[134:137], v142 offset:1024
	ds_read_b128 v[138:141], v142 offset:2048
	ds_read_b128 v[142:145], v142 offset:3072
	ds_read_b128 v[146:149], v158
	ds_read_b128 v[150:153], v158 offset:1024
	ds_read_b128 v[154:157], v158 offset:2048
	ds_read_b128 v[158:161], v158 offset:3072
	s_add_u32 s42, s42, 0x2b0000
	s_addc_u32 s43, s43, 0
	s_mov_b32 m0, s61
	v_lshl_add_u64 v[222:223], s[42:43], 0, v[172:173]
	ds_read_b128 v[162:165], v180 offset:32768
	ds_read_b128 v[166:169], v180 offset:33792
	ds_read_b128 v[182:185], v180 offset:34816
	ds_read_b128 v[190:193], v180 offset:35840
	ds_read_b128 v[194:197], v180 offset:36864
	ds_read_b128 v[208:211], v180 offset:37888
	ds_read_b128 v[212:215], v180 offset:38912
	ds_read_b128 v[216:219], v180 offset:39936
	global_load_lds_dwordx4 v[222:223], off
	v_lshl_add_u64 v[222:223], s[42:43], 0, v[176:177]
	s_mov_b32 m0, s62
	s_nop 0
	global_load_lds_dwordx4 v[222:223], off
	s_waitcnt vmcnt(8)
	s_waitcnt lgkmcnt(0)
	v_mfma_f32_16x16x32_bf16 v[126:129], v[130:133], v[162:165], v[126:129]
	v_mfma_f32_16x16x32_bf16 v[126:129], v[134:137], v[166:169], v[126:129]
	v_mfma_f32_16x16x32_bf16 v[122:125], v[138:141], v[162:165], v[122:125]
	v_mfma_f32_16x16x32_bf16 v[122:125], v[142:145], v[166:169], v[122:125]
	s_barrier
	s_setprio 3
	v_mfma_f32_16x16x32_bf16 v[94:97], v[138:141], v[182:185], v[94:97]
	v_mfma_f32_16x16x32_bf16 v[94:97], v[142:145], v[190:193], v[94:97]
	v_mfma_f32_16x16x32_bf16 v[98:101], v[130:133], v[182:185], v[98:101]
	v_mfma_f32_16x16x32_bf16 v[98:101], v[134:137], v[190:193], v[98:101]
	v_mfma_f32_16x16x32_bf16 v[110:113], v[130:133], v[194:197], v[110:113]
	v_mfma_f32_16x16x32_bf16 v[110:113], v[134:137], v[208:211], v[110:113]
	v_mfma_f32_16x16x32_bf16 v[106:109], v[138:141], v[194:197], v[106:109]
	v_mfma_f32_16x16x32_bf16 v[106:109], v[142:145], v[208:211], v[106:109]
	v_mfma_f32_16x16x32_bf16 v[74:77], v[138:141], v[212:215], v[74:77]
	v_mfma_f32_16x16x32_bf16 v[74:77], v[142:145], v[216:219], v[74:77]
	v_mfma_f32_16x16x32_bf16 v[78:81], v[130:133], v[212:215], v[78:81]
	v_mfma_f32_16x16x32_bf16 v[78:81], v[134:137], v[216:219], v[78:81]
	v_mfma_f32_16x16x32_bf16 v[118:121], v[146:149], v[162:165], v[118:121]
	v_mfma_f32_16x16x32_bf16 v[118:121], v[150:153], v[166:169], v[118:121]
	v_mfma_f32_16x16x32_bf16 v[114:117], v[154:157], v[162:165], v[114:117]
	v_mfma_f32_16x16x32_bf16 v[114:117], v[158:161], v[166:169], v[114:117]
	v_mfma_f32_16x16x32_bf16 v[86:89], v[154:157], v[182:185], v[86:89]
	v_mfma_f32_16x16x32_bf16 v[86:89], v[158:161], v[190:193], v[86:89]
	v_mfma_f32_16x16x32_bf16 v[90:93], v[146:149], v[182:185], v[90:93]
	v_mfma_f32_16x16x32_bf16 v[90:93], v[150:153], v[190:193], v[90:93]
	v_mfma_f32_16x16x32_bf16 v[102:105], v[146:149], v[194:197], v[102:105]
	v_mfma_f32_16x16x32_bf16 v[102:105], v[150:153], v[208:211], v[102:105]
	v_mfma_f32_16x16x32_bf16 v[82:85], v[154:157], v[194:197], v[82:85]
	v_mfma_f32_16x16x32_bf16 v[82:85], v[158:161], v[208:211], v[82:85]
	v_mfma_f32_16x16x32_bf16 v[66:69], v[154:157], v[212:215], v[66:69]
	v_mfma_f32_16x16x32_bf16 v[66:69], v[158:161], v[216:219], v[66:69]
	v_mfma_f32_16x16x32_bf16 v[70:73], v[146:149], v[212:215], v[70:73]
	v_mfma_f32_16x16x32_bf16 v[70:73], v[150:153], v[216:219], v[70:73]
	s_barrier
; #define PG8_STAGE(bufoff, gbase, voff) do { _Pragma("unroll") for (int _i = 0; _i < 2; ++_i) \
;         __builtin_amdgcn_global_load_lds((const unsigned*)((const char*)(gbase) + (voff)[_i]), (PG8_LAS unsigned*)(lds + (bufoff) + ldsw + _i * 8192), 16, 0, 0); } while (0)
; #define PG8_LDA(dst, b, h) do { _Pragma("unroll") for (int m = 0; m < 4; ++m) _Pragma("unroll") for (int k = 0; k < 2; ++k) dst[m][k] = *(const PG8_LAS bf16x8*)(lds + PG8_SA(b, h) + aoff + m * 2048 + k * 1024); } while (0)
; #define PG8_MMA(ai, bj, At, Bt) do { __builtin_amdgcn_s_setprio(3); _Pragma("unroll") for (int m = 0; m < 4; ++m) _Pragma("unroll") for (int n = 0; n < 2; ++n) _Pragma("unroll") for (int k = 0; k < 2; ++k) \
;         acc[ai][bj][m][n] = __builtin_amdgcn_mfma_f32_16x16x32_bf16(Bt[n][k], At[m][k], acc[ai][bj][m][n], 0, 0, 0); __builtin_amdgcn_s_setprio(0); } while (0)
; #define PG8_WAIT_V(n) asm volatile("s_waitcnt vmcnt(" #n ")" ::: "memory")
; #define PG8_WAIT_L(n) asm volatile("s_waitcnt lgkmcnt(" #n ")" ::: "memory")
; #define PG8_BAR __builtin_amdgcn_s_barrier()
; #define PG8_SCHED __builtin_amdgcn_sched_barrier(0)
; template <class Epi, class Sched, bool ALIGN_EPI = false, bool SP2 = false>
; __device__ __forceinline__ void gemm_phase(PG8_LAS unsigned char* lds, const Gemm g, const Sched& S, const Epi& E) {
;     ...
;             PG8_LDA(At, 1, 1); PG8_STAGE(PG8_SB(1, 0), b3, voffB); PG8_STAGE(PG8_SB(1, 1), b3 + hstepB, voffB); PG8_STAGE(PG8_SA(1, 0), a3, voffA);
;             PG8_WAIT_V(8); PG8_WAIT_L(0); PG8_BAR; PG8_MMA(1, 0, At, B0); PG8_MMA(1, 1, At, B1); PG8_BAR; PG8_SCHED;
	s_setprio 0
	s_mov_b32 m0, s83
	v_lshl_add_u64 v[186:187], v[186:187], 0, s[18:19]
	s_add_u32 s40, s40, 0x2b0080
	ds_read_b128 v[162:165], v180 offset:49152
	ds_read_b128 v[166:169], v180 offset:50176
	ds_read_b128 v[182:185], v180 offset:51200
	ds_read_b128 v[190:193], v180 offset:52224
	ds_read_b128 v[194:197], v180 offset:53248
	ds_read_b128 v[208:211], v180 offset:54272
	ds_read_b128 v[212:215], v180 offset:55296
	ds_read_b128 v[216:219], v180 offset:56320
	global_load_lds_dwordx4 v[186:187], off
	v_lshl_add_u64 v[186:187], v[198:199], 0, s[18:19]
	s_mov_b32 m0, s84
	s_addc_u32 s41, s41, 0
	global_load_lds_dwordx4 v[186:187], off
	v_lshl_add_u64 v[186:187], s[40:41], 0, v[174:175]
	s_mov_b32 m0, s85
	s_nop 0
	global_load_lds_dwordx4 v[186:187], off
	v_lshl_add_u64 v[186:187], s[40:41], 0, v[178:179]
	s_mov_b32 m0, s86
	s_nop 0
	global_load_lds_dwordx4 v[186:187], off
	v_lshl_add_u64 v[186:187], v[204:205], 0, s[18:19]
	s_mov_b32 m0, s63
	s_nop 0
	global_load_lds_dwordx4 v[186:187], off
	v_lshl_add_u64 v[186:187], v[220:221], 0, s[18:19]
	s_mov_b32 m0, s64
	s_nop 0
	global_load_lds_dwordx4 v[186:187], off
	s_waitcnt vmcnt(8)
	s_waitcnt lgkmcnt(0)
	v_mfma_f32_16x16x32_bf16 v[62:65], v[130:133], v[162:165], v[62:65]
	v_mfma_f32_16x16x32_bf16 v[62:65], v[134:137], v[166:169], v[62:65]
	v_mfma_f32_16x16x32_bf16 v[58:61], v[138:141], v[162:165], v[58:61]
	v_mfma_f32_16x16x32_bf16 v[58:61], v[142:145], v[166:169], v[58:61]
	s_barrier
	s_setprio 3
	v_mfma_f32_16x16x32_bf16 v[42:45], v[138:141], v[182:185], v[42:45]
	v_mfma_f32_16x16x32_bf16 v[42:45], v[142:145], v[190:193], v[42:45]
	v_mfma_f32_16x16x32_bf16 v[46:49], v[130:133], v[182:185], v[46:49]
	v_mfma_f32_16x16x32_bf16 v[46:49], v[134:137], v[190:193], v[46:49]
	v_mfma_f32_16x16x32_bf16 v[30:33], v[130:133], v[194:197], v[30:33]
	v_mfma_f32_16x16x32_bf16 v[30:33], v[134:137], v[208:211], v[30:33]
	v_mfma_f32_16x16x32_bf16 v[26:29], v[138:141], v[194:197], v[26:29]
	v_mfma_f32_16x16x32_bf16 v[26:29], v[142:145], v[208:211], v[26:29]
	v_mfma_f32_16x16x32_bf16 v[10:13], v[138:141], v[212:215], v[10:13]
	v_mfma_f32_16x16x32_bf16 v[10:13], v[142:145], v[216:219], v[10:13]
	v_mfma_f32_16x16x32_bf16 v[14:17], v[130:133], v[212:215], v[14:17]
	v_mfma_f32_16x16x32_bf16 v[14:17], v[134:137], v[216:219], v[14:17]
	v_mfma_f32_16x16x32_bf16 v[54:57], v[146:149], v[162:165], v[54:57]
	v_mfma_f32_16x16x32_bf16 v[54:57], v[150:153], v[166:169], v[54:57]
	v_mfma_f32_16x16x32_bf16 v[50:53], v[154:157], v[162:165], v[50:53]
	v_mfma_f32_16x16x32_bf16 v[50:53], v[158:161], v[166:169], v[50:53]
	v_mfma_f32_16x16x32_bf16 v[34:37], v[154:157], v[182:185], v[34:37]
	v_mfma_f32_16x16x32_bf16 v[34:37], v[158:161], v[190:193], v[34:37]
	v_mfma_f32_16x16x32_bf16 v[38:41], v[146:149], v[182:185], v[38:41]
	v_mfma_f32_16x16x32_bf16 v[38:41], v[150:153], v[190:193], v[38:41]
	v_mfma_f32_16x16x32_bf16 v[22:25], v[146:149], v[194:197], v[22:25]
	v_mfma_f32_16x16x32_bf16 v[22:25], v[150:153], v[208:211], v[22:25]
	v_mfma_f32_16x16x32_bf16 v[18:21], v[154:157], v[194:197], v[18:21]
	v_mfma_f32_16x16x32_bf16 v[18:21], v[158:161], v[208:211], v[18:21]
	v_mfma_f32_16x16x32_bf16 v[2:5], v[154:157], v[212:215], v[2:5]
	v_mfma_f32_16x16x32_bf16 v[2:5], v[158:161], v[216:219], v[2:5]
	v_mfma_f32_16x16x32_bf16 v[6:9], v[146:149], v[212:215], v[6:9]
	v_mfma_f32_16x16x32_bf16 v[6:9], v[150:153], v[216:219], v[6:9]
	s_barrier
	s_setprio 0
	s_add_i32 s67, s67, 2
	s_add_u32 s22, s22, 0x100
	s_addc_u32 s23, s23, 0
	s_cmpk_gt_u32 s67, 0xa9
	s_cbranch_scc1 .LBB0_1021
